# phase 4 prompt rows hand-written: row pairs share dt weight tiles from LDS, DPP transpose-reduce, 8 rows of loads in flight
# speedup vs baseline: 1.0379x; 1.0225x over previous
; #define LAS __attribute__((address_space(3)))
; template <bool WITH_DT, bool OUT8> __device__ __forceinline__ void norm_mod_rows(const void* xp, bool pb16, const void* xs, bool sb16, const float* w, const float* MOD, int ish, int isc, bf16* H, ...
;     asm volatile("" : "+v"(tid)); const int lane = tid & 63, gw = vcu * NWAVES + __builtin_amdgcn_readfirstlane(tid >> 6), NGW = G * NWAVES;
;     f32x4 wv[4];
; #pragma unroll
;     for (int j = 0; j < 4; ++j) wv[j] = ((const f32x4*)w)[lane + 64 * j];
;     f32x4 wdt[WITH_DT ? 8 : 1][4];
;     if (WITH_DT) {
; #pragma unroll
;         for (int c = 0; c < 8; ++c)
; #pragma unroll
;             for (int j = 0; j < 4; ++j) wdt[c][j] = *(const LAS f32x4*)(sW + c * 1024 + 4 * (lane + 64 * j)); }
;     f32x4 vn[4];
;     if (gw < MT) { if (gw < MP) load_row4(xp, pb16, (size_t)gw, lane, vn); else load_row4(xs, sb16, (size_t)(gw - MP), lane, vn); }
;     for (int row = gw; row < MT; row += NGW) {
;         const int mb = row < MP ? (row >> 12) : 8 + ((row - MP) >> 6);
;         f32x4 v[4]; float s = 0.f;
; #pragma unroll
;         for (int j = 0; j < 4; ++j) v[j] = vn[j];
;         { const int rn = row + NGW; if (rn < MT) { if (rn < MP) load_row4(xp, pb16, (size_t)rn, lane, vn); else load_row4(xs, sb16, (size_t)(rn - MP), lane, vn); } }
; __global__ void __launch_bounds__(NWAVES * 64, 2) mk_fwd(Args args) {
;     ...
;         LAS float* sW = (LAS float*)L;
;         for (int i = tid; i < 8192; i += 512) { const int c = i & 7, k = i >> 3; sW[c * 1024 + k] = karg_in<14>()[(size_t)k * INC + 1536 + c]; }
;         __syncthreads();
;         norm_mod_rows<true, false>(XB, true, karg_in<1>(), false, karg_in<13>(), MOD, 3, 4, H, vcu, G, tid, sW, karg_in<17>(), DT, (const bf16*)(ws + WS_HST), 11, MOD + 2 * 1024, 0.5f * INV_D, XB);
.LBB0_381:
	v_readlane_b32 s4, v254, 0
	s_cmp_lt_i32 s4, 5
	s_cselect_b64 s[2:3], -1, 0
	s_and_b64 s[8:9], s[2:3], s[0:1]
	s_andn2_b64 vcc, exec, s[8:9]
	v_readlane_b32 s5, v254, 1
	v_readlane_b32 s6, v254, 2
	v_readlane_b32 s7, v254, 3
	s_cbranch_vccnz .LBB0_401
	v_lshrrev_b32_e32 v1, 3, v252
	v_and_b32_e32 v0, 7, v252
	v_lshlrev_b32_e32 v3, 2, v1
	v_mul_u32_u24_e32 v1, 0xc08, v1
	v_lshl_or_b32 v3, v0, 12, v3
	v_or_b32_e32 v0, v1, v0
	v_mov_b32_e32 v1, 0x1800
	v_add_u32_e32 v2, 0xfffffe00, v252
	v_add_u32_e32 v3, 0, v3
	v_lshl_add_u32 v0, v0, 2, v1
	v_mov_b32_e32 v1, 0
	s_load_dwordx2 s[6:7], s[58:59], 0x70
	s_waitcnt lgkmcnt(0)
	s_mov_b64 s[2:3], 0xc0800
	v_lshl_add_u64 v[4:5], s[6:7], 0, v[0:1]
	global_load_dword v8, v[4:5], off
	v_lshl_add_u64 v[4:5], v[4:5], 0, s[2:3]
	global_load_dword v9, v[4:5], off
	v_lshl_add_u64 v[4:5], v[4:5], 0, s[2:3]
	global_load_dword v10, v[4:5], off
	v_lshl_add_u64 v[4:5], v[4:5], 0, s[2:3]
	global_load_dword v11, v[4:5], off
	v_lshl_add_u64 v[4:5], v[4:5], 0, s[2:3]
	global_load_dword v12, v[4:5], off
	v_lshl_add_u64 v[4:5], v[4:5], 0, s[2:3]
	global_load_dword v13, v[4:5], off
	v_lshl_add_u64 v[4:5], v[4:5], 0, s[2:3]
	global_load_dword v14, v[4:5], off
	v_lshl_add_u64 v[4:5], v[4:5], 0, s[2:3]
	global_load_dword v15, v[4:5], off
	v_lshl_add_u64 v[4:5], v[4:5], 0, s[2:3]
	global_load_dword v16, v[4:5], off
	v_lshl_add_u64 v[4:5], v[4:5], 0, s[2:3]
	global_load_dword v17, v[4:5], off
	v_lshl_add_u64 v[4:5], v[4:5], 0, s[2:3]
	global_load_dword v18, v[4:5], off
	v_lshl_add_u64 v[4:5], v[4:5], 0, s[2:3]
	global_load_dword v19, v[4:5], off
	v_lshl_add_u64 v[4:5], v[4:5], 0, s[2:3]
	global_load_dword v20, v[4:5], off
	v_lshl_add_u64 v[4:5], v[4:5], 0, s[2:3]
	global_load_dword v21, v[4:5], off
	v_lshl_add_u64 v[4:5], v[4:5], 0, s[2:3]
	global_load_dword v22, v[4:5], off
	v_lshl_add_u64 v[4:5], v[4:5], 0, s[2:3]
	global_load_dword v23, v[4:5], off
	s_waitcnt vmcnt(15)
	ds_write_b32 v3, v8 offset:0
	s_waitcnt vmcnt(14)
	ds_write_b32 v3, v9 offset:256
	s_waitcnt vmcnt(13)
	ds_write_b32 v3, v10 offset:512
	s_waitcnt vmcnt(12)
	ds_write_b32 v3, v11 offset:768
	s_waitcnt vmcnt(11)
	ds_write_b32 v3, v12 offset:1024
	s_waitcnt vmcnt(10)
	ds_write_b32 v3, v13 offset:1280
	s_waitcnt vmcnt(9)
	ds_write_b32 v3, v14 offset:1536
	s_waitcnt vmcnt(8)
	ds_write_b32 v3, v15 offset:1792
	s_waitcnt vmcnt(7)
	ds_write_b32 v3, v16 offset:2048
	s_waitcnt vmcnt(6)
	ds_write_b32 v3, v17 offset:2304
	s_waitcnt vmcnt(5)
	ds_write_b32 v3, v18 offset:2560
	s_waitcnt vmcnt(4)
	ds_write_b32 v3, v19 offset:2816
	s_waitcnt vmcnt(3)
	ds_write_b32 v3, v20 offset:3072
	s_waitcnt vmcnt(2)
	ds_write_b32 v3, v21 offset:3328
	s_waitcnt vmcnt(1)
	ds_write_b32 v3, v22 offset:3584
	s_waitcnt vmcnt(0)
	ds_write_b32 v3, v23 offset:3840
	s_waitcnt lgkmcnt(0)
	s_barrier
	s_load_dwordx2 s[0:1], s[58:59], 8
	s_waitcnt lgkmcnt(0)
	s_load_dwordx2 s[2:3], s[58:59], 0x68
	s_waitcnt lgkmcnt(0)
	v_mov_b32_e32 v144, v252
	s_load_dwordx2 s[14:15], s[58:59], 0x88
	s_waitcnt lgkmcnt(0)
	s_lshl_b32 s4, s92, 3
	v_readfirstlane_b32 s5, v144
	s_ashr_i32 s5, s5, 6
	s_cmpk_lg_u32 s69, 0x100
	s_cbranch_scc1 .Lp4_orig
	s_add_i32 s16, s5, s4
	v_and_b32_e32 v1, 63, v252
	v_lshlrev_b32_e32 v2, 3, v1
	v_lshlrev_b32_e32 v3, 4, v1
	v_xor_b32_e32 v5, 16, v1
	v_lshlrev_b32_e32 v5, 2, v5
	v_and_b32_e32 v6, 1, v1
	v_lshlrev_b32_e32 v6, 2, v6
	v_and_b32_e32 v7, 2, v1
	v_or_b32_e32 v6, v6, v7
	v_bfe_u32 v7, v1, 2, 1
	v_or_b32_e32 v6, v6, v7
	v_lshlrev_b32_e32 v6, 2, v6
	v_and_b32_e32 v7, 8, v1
	v_lshl_add_u32 v4, v7, 2, v6
	global_load_dword v12, v6, s[14:15]
	s_lshl_b32 s18, s16, 15
	s_add_u32 s20, s66, s18
	s_addc_u32 s21, s67, 0
	s_add_u32 s20, s20, 0x2e00000
	s_addc_u32 s21, s21, 0
	s_add_u32 s18, s64, s18
	s_addc_u32 s19, s65, 0
	s_lshl_b32 s28, s16, 9
	s_add_u32 s28, s66, s28
	s_addc_u32 s29, s67, 0
	s_add_u32 s28, s28, 0x200000
	s_addc_u32 s29, s29, 0
	s_lshr_b32 s22, s16, 8
	s_mul_i32 s22, s22, 0x9000
	s_add_u32 s22, s66, s22
	s_addc_u32 s23, s67, 0
	s_add_u32 s22, s22, 0x103000
	s_addc_u32 s23, s23, 0
	s_add_u32 s26, s22, 0x1000
	s_addc_u32 s27, s23, 0
	global_load_dwordx4 v[128:131], v3, s[2:3]
	global_load_dwordx4 v[132:135], v3, s[2:3] offset:1024
	global_load_dwordx4 v[136:139], v3, s[2:3] offset:2048
	global_load_dwordx4 v[140:143], v3, s[2:3] offset:3072
	global_load_dwordx4 v[16:19], v3, s[26:27]
	global_load_dwordx4 v[20:23], v3, s[26:27] offset:1024
	global_load_dwordx4 v[24:27], v3, s[26:27] offset:2048
	global_load_dwordx4 v[28:31], v3, s[26:27] offset:3072
	global_load_dwordx4 v[32:35], v3, s[22:23]
	global_load_dwordx4 v[36:39], v3, s[22:23] offset:1024
	global_load_dwordx4 v[40:43], v3, s[22:23] offset:2048
	global_load_dwordx4 v[44:47], v3, s[22:23] offset:3072
	global_load_dwordx2 v[64:65], v2, s[18:19]
	global_load_dwordx2 v[66:67], v2, s[18:19] offset:512
	global_load_dwordx2 v[68:69], v2, s[18:19] offset:1024
	global_load_dwordx2 v[70:71], v2, s[18:19] offset:1536
	s_add_u32 s18, s18, 0x800
	s_addc_u32 s19, s19, 0
	global_load_dwordx2 v[72:73], v2, s[18:19]
	global_load_dwordx2 v[74:75], v2, s[18:19] offset:512
	global_load_dwordx2 v[76:77], v2, s[18:19] offset:1024
	global_load_dwordx2 v[78:79], v2, s[18:19] offset:1536
	s_add_u32 s18, s18, 0x800
	s_addc_u32 s19, s19, 0
	global_load_dwordx2 v[80:81], v2, s[18:19]
	global_load_dwordx2 v[82:83], v2, s[18:19] offset:512
	global_load_dwordx2 v[84:85], v2, s[18:19] offset:1024
	global_load_dwordx2 v[86:87], v2, s[18:19] offset:1536
	s_add_u32 s18, s18, 0x800
	s_addc_u32 s19, s19, 0
	global_load_dwordx2 v[88:89], v2, s[18:19]
	global_load_dwordx2 v[90:91], v2, s[18:19] offset:512
; __device__ __forceinline__ float bflo(unsigned x) { return __uint_as_float(x << 16); }
; __device__ __forceinline__ float bfhi(unsigned x) { return __uint_as_float(x & 0xffff0000u); }
; __device__ __forceinline__ unsigned pk2(float lo, float hi) { return pg8::cvt_pk_bf16(lo, hi); }
; template <bool WITH_DT, bool OUT8> __device__ __forceinline__ void norm_mod_rows(const void* xp, bool pb16, const void* xs, bool sb16, const float* w, const float* MOD, int ish, int isc, bf16* H, ...
;     ...
;     if (gw < MT) { if (gw < MP) load_row4(xp, pb16, (size_t)gw, lane, vn); else load_row4(xs, sb16, (size_t)(gw - MP), lane, vn); }
;     for (int row = gw; row < MT; row += NGW) {
;         const int mb = row < MP ? (row >> 12) : 8 + ((row - MP) >> 6);
;         f32x4 v[4]; float s = 0.f;
; #pragma unroll
;         for (int j = 0; j < 4; ++j) v[j] = vn[j];
;         { const int rn = row + NGW; if (rn < MT) { if (rn < MP) load_row4(xp, pb16, (size_t)rn, lane, vn); else load_row4(xs, sb16, (size_t)(rn - MP), lane, vn); } }
;         if (fslab && row >= MP) {
;             f32x4 a[4];
; #pragma unroll
;             for (int j = 0; j < 4; ++j) a[j] = (f32x4){0.f, 0.f, 0.f, 0.f};
;             for (int ks = 0; ks < fS; ++ks) { const v2u* sp = (const v2u*)(fslab + ((size_t)ks * MS + (row - MP)) * DM);
; #pragma unroll
;                 for (int j = 0; j < 4; ++j) { const v2u r = sp[lane + 64 * j]; a[j] += (f32x4){bflo(r.x), bfhi(r.x), bflo(r.y), bfhi(r.y)}; } }
; #pragma unroll
;             for (int j = 0; j < 4; ++j) { v[j] += ((const f32x4*)(fgate + (size_t)mb * 9216))[lane + 64 * j] * fsc * a[j];
;                 v2u o; o.x = pk2(v[j][0], v[j][1]); o.y = pk2(v[j][2], v[j][3]); *(v2u*)(fxout + (size_t)row * DM + 4 * (lane + 64 * j)) = o; }
;         }
; #pragma unroll
;         for (int j = 0; j < 4; ++j) s += (v[j][0] * v[j][0] + v[j][1] * v[j][1]) + (v[j][2] * v[j][2] + v[j][3] * v[j][3]);
;         const float rstd = rsqrtf(wave_sum(s) * (1.0f / DM) + EPSN);
	global_load_dwordx2 v[92:93], v2, s[18:19] offset:1024
	global_load_dwordx2 v[94:95], v2, s[18:19] offset:1536
	s_add_u32 s18, s18, 0x800
	s_addc_u32 s19, s19, 0
	global_load_dwordx2 v[96:97], v2, s[18:19]
	global_load_dwordx2 v[98:99], v2, s[18:19] offset:512
	global_load_dwordx2 v[100:101], v2, s[18:19] offset:1024
	global_load_dwordx2 v[102:103], v2, s[18:19] offset:1536
	s_add_u32 s18, s18, 0x800
	s_addc_u32 s19, s19, 0
	global_load_dwordx2 v[104:105], v2, s[18:19]
	global_load_dwordx2 v[106:107], v2, s[18:19] offset:512
	global_load_dwordx2 v[108:109], v2, s[18:19] offset:1024
	global_load_dwordx2 v[110:111], v2, s[18:19] offset:1536
	s_add_u32 s18, s18, 0x800
	s_addc_u32 s19, s19, 0
	global_load_dwordx2 v[112:113], v2, s[18:19]
	global_load_dwordx2 v[114:115], v2, s[18:19] offset:512
	global_load_dwordx2 v[116:117], v2, s[18:19] offset:1024
	global_load_dwordx2 v[118:119], v2, s[18:19] offset:1536
	s_add_u32 s18, s18, 0x800
	s_addc_u32 s19, s19, 0
	global_load_dwordx2 v[120:121], v2, s[18:19]
	global_load_dwordx2 v[122:123], v2, s[18:19] offset:512
	global_load_dwordx2 v[124:125], v2, s[18:19] offset:1024
	global_load_dwordx2 v[126:127], v2, s[18:19] offset:1536
	s_add_u32 s18, s18, 0x800
	s_addc_u32 s19, s19, 0
	v_mov_b32_e32 v8, 0x358637bd
	s_mov_b32 s38, 0xaaaaaaaa
	s_mov_b32 s39, s38
	s_mov_b32 s40, 0xcccccccc
	s_mov_b32 s41, s40
	s_mov_b32 s42, 0xf0f0f0f0
	s_mov_b32 s43, s42
	s_mov_b32 s44, 0xff00ff00
	s_mov_b32 s45, s44
	s_waitcnt vmcnt(32)
	v_pk_add_f32 v[16:17], v[16:17], 1.0 op_sel_hi:[1,0]
	v_pk_add_f32 v[18:19], v[18:19], 1.0 op_sel_hi:[1,0]
	v_pk_add_f32 v[20:21], v[20:21], 1.0 op_sel_hi:[1,0]
	v_pk_add_f32 v[22:23], v[22:23], 1.0 op_sel_hi:[1,0]
	v_pk_add_f32 v[24:25], v[24:25], 1.0 op_sel_hi:[1,0]
	v_pk_add_f32 v[26:27], v[26:27], 1.0 op_sel_hi:[1,0]
	v_pk_add_f32 v[28:29], v[28:29], 1.0 op_sel_hi:[1,0]
	v_pk_add_f32 v[30:31], v[30:31], 1.0 op_sel_hi:[1,0]
	v_pk_mul_f32 v[16:17], v[16:17], v[128:129]
	v_pk_mul_f32 v[18:19], v[18:19], v[130:131]
	v_pk_mul_f32 v[20:21], v[20:21], v[132:133]
	v_pk_mul_f32 v[22:23], v[22:23], v[134:135]
	v_pk_mul_f32 v[24:25], v[24:25], v[136:137]
	v_pk_mul_f32 v[26:27], v[26:27], v[138:139]
	v_pk_mul_f32 v[28:29], v[28:29], v[140:141]
	v_pk_mul_f32 v[30:31], v[30:31], v[142:143]
	s_waitcnt vmcnt(24)
	v_lshlrev_b32_e32 v128, 16, v64
	v_and_b32_e32 v129, 0xffff0000, v64
	v_lshlrev_b32_e32 v130, 16, v65
	v_and_b32_e32 v131, 0xffff0000, v65
	v_lshlrev_b32_e32 v132, 16, v66
	v_and_b32_e32 v133, 0xffff0000, v66
	v_lshlrev_b32_e32 v134, 16, v67
	v_and_b32_e32 v135, 0xffff0000, v67
	v_lshlrev_b32_e32 v136, 16, v68
	v_and_b32_e32 v137, 0xffff0000, v68
	v_lshlrev_b32_e32 v138, 16, v69
	v_and_b32_e32 v139, 0xffff0000, v69
	v_lshlrev_b32_e32 v140, 16, v70
	v_and_b32_e32 v141, 0xffff0000, v70
	v_lshlrev_b32_e32 v142, 16, v71
	v_and_b32_e32 v143, 0xffff0000, v71
	v_lshlrev_b32_e32 v144, 16, v72
	v_and_b32_e32 v145, 0xffff0000, v72
	v_lshlrev_b32_e32 v146, 16, v73
	v_and_b32_e32 v147, 0xffff0000, v73
	v_lshlrev_b32_e32 v148, 16, v74
	v_and_b32_e32 v149, 0xffff0000, v74
	v_lshlrev_b32_e32 v150, 16, v75
	v_and_b32_e32 v151, 0xffff0000, v75
	v_lshlrev_b32_e32 v152, 16, v76
	v_and_b32_e32 v153, 0xffff0000, v76
	v_lshlrev_b32_e32 v154, 16, v77
	v_and_b32_e32 v155, 0xffff0000, v77
	v_lshlrev_b32_e32 v156, 16, v78
	v_and_b32_e32 v157, 0xffff0000, v78
	v_lshlrev_b32_e32 v158, 16, v79
	v_and_b32_e32 v159, 0xffff0000, v79
	global_load_dwordx2 v[64:65], v2, s[18:19]
	global_load_dwordx2 v[66:67], v2, s[18:19] offset:512
	global_load_dwordx2 v[68:69], v2, s[18:19] offset:1024
	global_load_dwordx2 v[70:71], v2, s[18:19] offset:1536
	s_add_u32 s18, s18, 0x800
	s_addc_u32 s19, s19, 0
	global_load_dwordx2 v[72:73], v2, s[18:19]
	global_load_dwordx2 v[74:75], v2, s[18:19] offset:512
	global_load_dwordx2 v[76:77], v2, s[18:19] offset:1024
	global_load_dwordx2 v[78:79], v2, s[18:19] offset:1536
	s_add_u32 s18, s18, 0x800
	s_addc_u32 s19, s19, 0
	v_pk_mul_f32 v[208:209], v[128:129], v[128:129]
	v_pk_mul_f32 v[210:211], v[130:131], v[130:131]
	v_pk_mul_f32 v[212:213], v[144:145], v[144:145]
	v_pk_mul_f32 v[214:215], v[146:147], v[146:147]
	v_pk_fma_f32 v[208:209], v[132:133], v[132:133], v[208:209]
	v_pk_fma_f32 v[210:211], v[134:135], v[134:135], v[210:211]
	v_pk_fma_f32 v[212:213], v[148:149], v[148:149], v[212:213]
	v_pk_fma_f32 v[214:215], v[150:151], v[150:151], v[214:215]
	v_pk_fma_f32 v[208:209], v[136:137], v[136:137], v[208:209]
	v_pk_fma_f32 v[210:211], v[138:139], v[138:139], v[210:211]
	v_pk_fma_f32 v[212:213], v[152:153], v[152:153], v[212:213]
	v_pk_fma_f32 v[214:215], v[154:155], v[154:155], v[214:215]
	v_pk_fma_f32 v[208:209], v[140:141], v[140:141], v[208:209]
	v_pk_fma_f32 v[210:211], v[142:143], v[142:143], v[210:211]
	v_pk_fma_f32 v[212:213], v[156:157], v[156:157], v[212:213]
	v_pk_fma_f32 v[214:215], v[158:159], v[158:159], v[214:215]
	v_pk_add_f32 v[208:209], v[208:209], v[210:211]
	v_pk_add_f32 v[212:213], v[212:213], v[214:215]
	v_add_f32_e32 v208, v208, v209
	v_add_f32_e32 v212, v212, v213
	s_nop 0
	v_add_f32_dpp v208, v208, v208 quad_perm:[1,0,3,2] row_mask:0xf bank_mask:0xf
	v_add_f32_dpp v212, v212, v212 quad_perm:[1,0,3,2] row_mask:0xf bank_mask:0xf
	s_nop 0
	v_add_f32_dpp v208, v208, v208 quad_perm:[2,3,0,1] row_mask:0xf bank_mask:0xf
	v_add_f32_dpp v212, v212, v212 quad_perm:[2,3,0,1] row_mask:0xf bank_mask:0xf
	s_nop 0
	v_add_f32_dpp v208, v208, v208 row_half_mirror row_mask:0xf bank_mask:0xf
	v_add_f32_dpp v212, v212, v212 row_half_mirror row_mask:0xf bank_mask:0xf
	s_nop 0
	v_add_f32_dpp v208, v208, v208 row_mirror row_mask:0xf bank_mask:0xf
	v_add_f32_dpp v212, v212, v212 row_mirror row_mask:0xf bank_mask:0xf
; __device__ __forceinline__ unsigned pk2(float lo, float hi) { return pg8::cvt_pk_bf16(lo, hi); }
; template <bool WITH_DT, bool OUT8> __device__ __forceinline__ void norm_mod_rows(const void* xp, bool pb16, const void* xs, bool sb16, const float* w, const float* MOD, int ish, int isc, bf16* H, ...
;     ...
;         const float rstd = rsqrtf(wave_sum(s) * (1.0f / DM) + EPSN);
;         const f32x4* sh = (const f32x4*)(MOD + (size_t)mb * 9216 + ish * 1024); const f32x4* sc = (const f32x4*)(MOD + (size_t)mb * 9216 + isc * 1024);
; #pragma unroll
;         for (int j = 0; j < 4; ++j) { const f32x4 a = v[j] * rstd * wv[j]; v[j] = a * (sc[lane + 64 * j] + 1.0f) + sh[lane + 64 * j];
;             if (OUT8) { *(unsigned*)((unsigned char*)H + (size_t)row * DM + 4 * (lane + 64 * j)) = pk4_fp8(v[j][0] * SC_H8, v[j][1] * SC_H8, v[j][2] * SC_H8, v[j][3] * SC_H8); }
;             else { v2u o; o.x = pk2(v[j][0], v[j][1]); o.y = pk2(v[j][2], v[j][3]); *(v2u*)(H + (size_t)row * DM + 4 * (lane + 64 * j)) = o; } }
;         if (WITH_DT) {
;             float d[8];
; #pragma unroll
;             for (int c = 0; c < 8; ++c) { float p = 0.f;
; #pragma unroll
;                 for (int j = 0; j < 4; ++j) { const f32x4 ww = wdt[WITH_DT ? c : 0][j]; p += (v[j][0] * ww[0] + v[j][1] * ww[1]) + (v[j][2] * ww[2] + v[j][3] * ww[3]); }
;                 d[c] = p; }
	s_nop 0
	v_readlane_b32 s30, v208, 0
	v_readlane_b32 s31, v208, 16
	v_readlane_b32 s32, v208, 32
	v_readlane_b32 s33, v208, 48
	v_readlane_b32 s34, v212, 0
	v_readlane_b32 s35, v212, 16
	v_readlane_b32 s36, v212, 32
	v_readlane_b32 s37, v212, 48
	s_nop 1
	v_mov_b32_e32 v209, s30
	v_mov_b32_e32 v213, s34
	v_add_f32_e32 v209, s31, v209
	v_add_f32_e32 v213, s35, v213
	v_add_f32_e32 v209, s32, v209
	v_add_f32_e32 v213, s36, v213
	v_add_f32_e32 v209, s33, v209
	v_add_f32_e32 v213, s37, v213
	v_fmamk_f32 v209, v209, 0x3a800000, v8
	v_fmamk_f32 v213, v213, 0x3a800000, v8
	v_rsq_f32_e32 v210, v209
	v_rsq_f32_e32 v214, v213
	s_nop 0
	v_pk_mul_f32 v[128:129], v[128:129], v[210:211] op_sel_hi:[1,0]
	v_pk_mul_f32 v[130:131], v[130:131], v[210:211] op_sel_hi:[1,0]
	v_pk_mul_f32 v[132:133], v[132:133], v[210:211] op_sel_hi:[1,0]
	v_pk_mul_f32 v[134:135], v[134:135], v[210:211] op_sel_hi:[1,0]
	v_pk_mul_f32 v[136:137], v[136:137], v[210:211] op_sel_hi:[1,0]
	v_pk_mul_f32 v[138:139], v[138:139], v[210:211] op_sel_hi:[1,0]
	v_pk_mul_f32 v[140:141], v[140:141], v[210:211] op_sel_hi:[1,0]
	v_pk_mul_f32 v[142:143], v[142:143], v[210:211] op_sel_hi:[1,0]
	v_pk_mul_f32 v[144:145], v[144:145], v[214:215] op_sel_hi:[1,0]
	v_pk_mul_f32 v[146:147], v[146:147], v[214:215] op_sel_hi:[1,0]
	v_pk_mul_f32 v[148:149], v[148:149], v[214:215] op_sel_hi:[1,0]
	v_pk_mul_f32 v[150:151], v[150:151], v[214:215] op_sel_hi:[1,0]
	v_pk_mul_f32 v[152:153], v[152:153], v[214:215] op_sel_hi:[1,0]
	v_pk_mul_f32 v[154:155], v[154:155], v[214:215] op_sel_hi:[1,0]
	v_pk_mul_f32 v[156:157], v[156:157], v[214:215] op_sel_hi:[1,0]
	v_pk_mul_f32 v[158:159], v[158:159], v[214:215] op_sel_hi:[1,0]
	v_pk_fma_f32 v[128:129], v[128:129], v[16:17], v[32:33]
	v_pk_fma_f32 v[130:131], v[130:131], v[18:19], v[34:35]
	v_pk_fma_f32 v[132:133], v[132:133], v[20:21], v[36:37]
	v_pk_fma_f32 v[134:135], v[134:135], v[22:23], v[38:39]
	v_pk_fma_f32 v[136:137], v[136:137], v[24:25], v[40:41]
	v_pk_fma_f32 v[138:139], v[138:139], v[26:27], v[42:43]
	v_pk_fma_f32 v[140:141], v[140:141], v[28:29], v[44:45]
	v_pk_fma_f32 v[142:143], v[142:143], v[30:31], v[46:47]
	v_pk_fma_f32 v[144:145], v[144:145], v[16:17], v[32:33]
	v_pk_fma_f32 v[146:147], v[146:147], v[18:19], v[34:35]
	v_pk_fma_f32 v[148:149], v[148:149], v[20:21], v[36:37]
	v_pk_fma_f32 v[150:151], v[150:151], v[22:23], v[38:39]
	v_pk_fma_f32 v[152:153], v[152:153], v[24:25], v[40:41]
	v_pk_fma_f32 v[154:155], v[154:155], v[26:27], v[42:43]
	v_pk_fma_f32 v[156:157], v[156:157], v[28:29], v[44:45]
	v_pk_fma_f32 v[158:159], v[158:159], v[30:31], v[46:47]
	v_cvt_pk_bf16_f32 v216, v128, v129
	v_cvt_pk_bf16_f32 v217, v130, v131
	v_cvt_pk_bf16_f32 v218, v132, v133
	v_cvt_pk_bf16_f32 v219, v134, v135
	v_cvt_pk_bf16_f32 v220, v136, v137
	v_cvt_pk_bf16_f32 v221, v138, v139
	v_cvt_pk_bf16_f32 v222, v140, v141
	v_cvt_pk_bf16_f32 v223, v142, v143
	v_cvt_pk_bf16_f32 v224, v144, v145
	v_cvt_pk_bf16_f32 v225, v146, v147
	v_cvt_pk_bf16_f32 v226, v148, v149
	v_cvt_pk_bf16_f32 v227, v150, v151
	v_cvt_pk_bf16_f32 v228, v152, v153
	v_cvt_pk_bf16_f32 v229, v154, v155
	v_cvt_pk_bf16_f32 v230, v156, v157
	v_cvt_pk_bf16_f32 v231, v158, v159
	global_store_dwordx2 v2, v[216:217], s[20:21]
	global_store_dwordx2 v2, v[218:219], s[20:21] offset:512
	global_store_dwordx2 v2, v[220:221], s[20:21] offset:1024
	global_store_dwordx2 v2, v[222:223], s[20:21] offset:1536
	global_store_dwordx2 v2, v[224:225], s[20:21] offset:2048
	global_store_dwordx2 v2, v[226:227], s[20:21] offset:2560
	global_store_dwordx2 v2, v[228:229], s[20:21] offset:3072
	global_store_dwordx2 v2, v[230:231], s[20:21] offset:3584
	s_add_u32 s20, s20, 0x1000
	s_addc_u32 s21, s21, 0
	ds_read_b128 v[192:195], v3 offset:0
	ds_read_b128 v[196:199], v3 offset:1024
	ds_read_b128 v[200:203], v3 offset:2048
	ds_read_b128 v[204:207], v3 offset:3072
	s_waitcnt lgkmcnt(3)
	v_pk_mul_f32 v[160:161], v[128:129], v[192:193]
	v_pk_mul_f32 v[176:177], v[144:145], v[192:193]
	v_pk_fma_f32 v[160:161], v[130:131], v[194:195], v[160:161]
	v_pk_fma_f32 v[176:177], v[146:147], v[194:195], v[176:177]
	ds_read_b128 v[192:195], v3 offset:4096
	s_waitcnt lgkmcnt(3)
	v_pk_fma_f32 v[160:161], v[132:133], v[196:197], v[160:161]
	v_pk_fma_f32 v[176:177], v[148:149], v[196:197], v[176:177]
	v_pk_fma_f32 v[160:161], v[134:135], v[198:199], v[160:161]
	v_pk_fma_f32 v[176:177], v[150:151], v[198:199], v[176:177]
	ds_read_b128 v[196:199], v3 offset:5120
	s_waitcnt lgkmcnt(3)
	v_pk_fma_f32 v[160:161], v[136:137], v[200:201], v[160:161]
	v_pk_fma_f32 v[176:177], v[152:153], v[200:201], v[176:177]
	v_pk_fma_f32 v[160:161], v[138:139], v[202:203], v[160:161]
	v_pk_fma_f32 v[176:177], v[154:155], v[202:203], v[176:177]
	ds_read_b128 v[200:203], v3 offset:6144
	s_waitcnt lgkmcnt(3)
	v_pk_fma_f32 v[160:161], v[140:141], v[204:205], v[160:161]
	v_pk_fma_f32 v[176:177], v[156:157], v[204:205], v[176:177]
	v_pk_fma_f32 v[160:161], v[142:143], v[206:207], v[160:161]
	v_pk_fma_f32 v[176:177], v[158:159], v[206:207], v[176:177]
	ds_read_b128 v[204:207], v3 offset:7168
	s_waitcnt lgkmcnt(3)
	v_pk_mul_f32 v[162:163], v[128:129], v[192:193]
	v_pk_mul_f32 v[178:179], v[144:145], v[192:193]
	v_pk_fma_f32 v[162:163], v[130:131], v[194:195], v[162:163]
	v_pk_fma_f32 v[178:179], v[146:147], v[194:195], v[178:179]
	ds_read_b128 v[192:195], v3 offset:8192
	s_waitcnt lgkmcnt(3)
	v_pk_fma_f32 v[162:163], v[132:133], v[196:197], v[162:163]
	v_pk_fma_f32 v[178:179], v[148:149], v[196:197], v[178:179]
	v_pk_fma_f32 v[162:163], v[134:135], v[198:199], v[162:163]
	v_pk_fma_f32 v[178:179], v[150:151], v[198:199], v[178:179]
	ds_read_b128 v[196:199], v3 offset:9216
	s_waitcnt lgkmcnt(3)
; template <bool WITH_DT, bool OUT8> __device__ __forceinline__ void norm_mod_rows(const void* xp, bool pb16, const void* xs, bool sb16, const float* w, const float* MOD, int ish, int isc, bf16* H, ...
;     ...
;             for (int c = 0; c < 8; ++c) { float p = 0.f;
; #pragma unroll
;                 for (int j = 0; j < 4; ++j) { const f32x4 ww = wdt[WITH_DT ? c : 0][j]; p += (v[j][0] * ww[0] + v[j][1] * ww[1]) + (v[j][2] * ww[2] + v[j][3] * ww[3]); }
;                 d[c] = p; }
	v_pk_fma_f32 v[162:163], v[136:137], v[200:201], v[162:163]
	v_pk_fma_f32 v[178:179], v[152:153], v[200:201], v[178:179]
	v_pk_fma_f32 v[162:163], v[138:139], v[202:203], v[162:163]
	v_pk_fma_f32 v[178:179], v[154:155], v[202:203], v[178:179]
	ds_read_b128 v[200:203], v3 offset:10240
	s_waitcnt lgkmcnt(3)
	v_pk_fma_f32 v[162:163], v[140:141], v[204:205], v[162:163]
	v_pk_fma_f32 v[178:179], v[156:157], v[204:205], v[178:179]
	v_pk_fma_f32 v[162:163], v[142:143], v[206:207], v[162:163]
	v_pk_fma_f32 v[178:179], v[158:159], v[206:207], v[178:179]
	ds_read_b128 v[204:207], v3 offset:11264
	s_waitcnt lgkmcnt(3)
	v_pk_mul_f32 v[164:165], v[128:129], v[192:193]
	v_pk_mul_f32 v[180:181], v[144:145], v[192:193]
	v_pk_fma_f32 v[164:165], v[130:131], v[194:195], v[164:165]
	v_pk_fma_f32 v[180:181], v[146:147], v[194:195], v[180:181]
	ds_read_b128 v[192:195], v3 offset:12288
	s_waitcnt lgkmcnt(3)
	v_pk_fma_f32 v[164:165], v[132:133], v[196:197], v[164:165]
	v_pk_fma_f32 v[180:181], v[148:149], v[196:197], v[180:181]
	v_pk_fma_f32 v[164:165], v[134:135], v[198:199], v[164:165]
	v_pk_fma_f32 v[180:181], v[150:151], v[198:199], v[180:181]
	ds_read_b128 v[196:199], v3 offset:13312
	s_waitcnt lgkmcnt(3)
	v_pk_fma_f32 v[164:165], v[136:137], v[200:201], v[164:165]
	v_pk_fma_f32 v[180:181], v[152:153], v[200:201], v[180:181]
	v_pk_fma_f32 v[164:165], v[138:139], v[202:203], v[164:165]
	v_pk_fma_f32 v[180:181], v[154:155], v[202:203], v[180:181]
	ds_read_b128 v[200:203], v3 offset:14336
	s_waitcnt lgkmcnt(3)
	v_pk_fma_f32 v[164:165], v[140:141], v[204:205], v[164:165]
	v_pk_fma_f32 v[180:181], v[156:157], v[204:205], v[180:181]
	v_pk_fma_f32 v[164:165], v[142:143], v[206:207], v[164:165]
	v_pk_fma_f32 v[180:181], v[158:159], v[206:207], v[180:181]
	ds_read_b128 v[204:207], v3 offset:15360
	s_waitcnt lgkmcnt(3)
	v_pk_mul_f32 v[166:167], v[128:129], v[192:193]
	v_pk_mul_f32 v[182:183], v[144:145], v[192:193]
	v_pk_fma_f32 v[166:167], v[130:131], v[194:195], v[166:167]
	v_pk_fma_f32 v[182:183], v[146:147], v[194:195], v[182:183]
	ds_read_b128 v[192:195], v3 offset:16384
	s_waitcnt lgkmcnt(3)
	v_pk_fma_f32 v[166:167], v[132:133], v[196:197], v[166:167]
	v_pk_fma_f32 v[182:183], v[148:149], v[196:197], v[182:183]
	v_pk_fma_f32 v[166:167], v[134:135], v[198:199], v[166:167]
	v_pk_fma_f32 v[182:183], v[150:151], v[198:199], v[182:183]
	ds_read_b128 v[196:199], v3 offset:17408
	s_waitcnt lgkmcnt(3)
	v_pk_fma_f32 v[166:167], v[136:137], v[200:201], v[166:167]
	v_pk_fma_f32 v[182:183], v[152:153], v[200:201], v[182:183]
	v_pk_fma_f32 v[166:167], v[138:139], v[202:203], v[166:167]
	v_pk_fma_f32 v[182:183], v[154:155], v[202:203], v[182:183]
	ds_read_b128 v[200:203], v3 offset:18432
	s_waitcnt lgkmcnt(3)
	v_pk_fma_f32 v[166:167], v[140:141], v[204:205], v[166:167]
	v_pk_fma_f32 v[182:183], v[156:157], v[204:205], v[182:183]
	v_pk_fma_f32 v[166:167], v[142:143], v[206:207], v[166:167]
	v_pk_fma_f32 v[182:183], v[158:159], v[206:207], v[182:183]
	ds_read_b128 v[204:207], v3 offset:19456
	s_waitcnt lgkmcnt(3)
	v_pk_mul_f32 v[168:169], v[128:129], v[192:193]
	v_pk_mul_f32 v[184:185], v[144:145], v[192:193]
	v_pk_fma_f32 v[168:169], v[130:131], v[194:195], v[168:169]
	v_pk_fma_f32 v[184:185], v[146:147], v[194:195], v[184:185]
	ds_read_b128 v[192:195], v3 offset:20480
	s_waitcnt lgkmcnt(3)
	v_pk_fma_f32 v[168:169], v[132:133], v[196:197], v[168:169]
	v_pk_fma_f32 v[184:185], v[148:149], v[196:197], v[184:185]
	v_pk_fma_f32 v[168:169], v[134:135], v[198:199], v[168:169]
	v_pk_fma_f32 v[184:185], v[150:151], v[198:199], v[184:185]
	ds_read_b128 v[196:199], v3 offset:21504
	s_waitcnt lgkmcnt(3)
	v_pk_fma_f32 v[168:169], v[136:137], v[200:201], v[168:169]
	v_pk_fma_f32 v[184:185], v[152:153], v[200:201], v[184:185]
	v_pk_fma_f32 v[168:169], v[138:139], v[202:203], v[168:169]
	v_pk_fma_f32 v[184:185], v[154:155], v[202:203], v[184:185]
	ds_read_b128 v[200:203], v3 offset:22528
	s_waitcnt lgkmcnt(3)
	v_pk_fma_f32 v[168:169], v[140:141], v[204:205], v[168:169]
	v_pk_fma_f32 v[184:185], v[156:157], v[204:205], v[184:185]
	v_pk_fma_f32 v[168:169], v[142:143], v[206:207], v[168:169]
	v_pk_fma_f32 v[184:185], v[158:159], v[206:207], v[184:185]
	ds_read_b128 v[204:207], v3 offset:23552
	s_waitcnt lgkmcnt(3)
	v_pk_mul_f32 v[170:171], v[128:129], v[192:193]
	v_pk_mul_f32 v[186:187], v[144:145], v[192:193]
	v_pk_fma_f32 v[170:171], v[130:131], v[194:195], v[170:171]
	v_pk_fma_f32 v[186:187], v[146:147], v[194:195], v[186:187]
	ds_read_b128 v[192:195], v3 offset:24576
	s_waitcnt lgkmcnt(3)
	v_pk_fma_f32 v[170:171], v[132:133], v[196:197], v[170:171]
	v_pk_fma_f32 v[186:187], v[148:149], v[196:197], v[186:187]
	v_pk_fma_f32 v[170:171], v[134:135], v[198:199], v[170:171]
	v_pk_fma_f32 v[186:187], v[150:151], v[198:199], v[186:187]
	ds_read_b128 v[196:199], v3 offset:25600
	s_waitcnt lgkmcnt(3)
	v_pk_fma_f32 v[170:171], v[136:137], v[200:201], v[170:171]
	v_pk_fma_f32 v[186:187], v[152:153], v[200:201], v[186:187]
	v_pk_fma_f32 v[170:171], v[138:139], v[202:203], v[170:171]
	v_pk_fma_f32 v[186:187], v[154:155], v[202:203], v[186:187]
	ds_read_b128 v[200:203], v3 offset:26624
	s_waitcnt lgkmcnt(3)
	v_pk_fma_f32 v[170:171], v[140:141], v[204:205], v[170:171]
	v_pk_fma_f32 v[186:187], v[156:157], v[204:205], v[186:187]
	v_pk_fma_f32 v[170:171], v[142:143], v[206:207], v[170:171]
	v_pk_fma_f32 v[186:187], v[158:159], v[206:207], v[186:187]
	ds_read_b128 v[204:207], v3 offset:27648
	s_waitcnt lgkmcnt(3)
	v_pk_mul_f32 v[172:173], v[128:129], v[192:193]
	v_pk_mul_f32 v[188:189], v[144:145], v[192:193]
	v_pk_fma_f32 v[172:173], v[130:131], v[194:195], v[172:173]
	v_pk_fma_f32 v[188:189], v[146:147], v[194:195], v[188:189]
	ds_read_b128 v[192:195], v3 offset:28672
	s_waitcnt lgkmcnt(3)
; template <bool WITH_DT, bool OUT8> __device__ __forceinline__ void norm_mod_rows(const void* xp, bool pb16, const void* xs, bool sb16, const float* w, const float* MOD, int ish, int isc, bf16* H, ...
;     ...
;             for (int c = 0; c < 8; ++c) { float p = 0.f;
; #pragma unroll
;                 for (int j = 0; j < 4; ++j) { const f32x4 ww = wdt[WITH_DT ? c : 0][j]; p += (v[j][0] * ww[0] + v[j][1] * ww[1]) + (v[j][2] * ww[2] + v[j][3] * ww[3]); }
;                 d[c] = p; }
;             float e4[4], e2[2], e1;
;             { const bool up = (lane & 32) != 0;
; #pragma unroll
;               for (int c = 0; c < 4; ++c) { const float keep = up ? d[4 + c] : d[c], give = up ? d[c] : d[4 + c]; e4[c] = keep + __shfl_xor(give, 32); } }
;             { const bool up = (lane & 16) != 0;
; #pragma unroll
;               for (int c = 0; c < 2; ++c) { const float keep = up ? e4[2 + c] : e4[c], give = up ? e4[c] : e4[2 + c]; e2[c] = keep + __shfl_xor(give, 16); } }
;             { const bool up = (lane & 8) != 0; const float keep = up ? e2[1] : e2[0], give = up ? e2[0] : e2[1]; e1 = keep + __shfl_xor(give, 8); }
;             e1 += __shfl_xor(e1, 4); e1 += __shfl_xor(e1, 2); e1 += __shfl_xor(e1, 1);
	v_pk_fma_f32 v[172:173], v[132:133], v[196:197], v[172:173]
	v_pk_fma_f32 v[188:189], v[148:149], v[196:197], v[188:189]
	v_pk_fma_f32 v[172:173], v[134:135], v[198:199], v[172:173]
	v_pk_fma_f32 v[188:189], v[150:151], v[198:199], v[188:189]
	ds_read_b128 v[196:199], v3 offset:29696
	s_waitcnt lgkmcnt(3)
	v_pk_fma_f32 v[172:173], v[136:137], v[200:201], v[172:173]
	v_pk_fma_f32 v[188:189], v[152:153], v[200:201], v[188:189]
	v_pk_fma_f32 v[172:173], v[138:139], v[202:203], v[172:173]
	v_pk_fma_f32 v[188:189], v[154:155], v[202:203], v[188:189]
	ds_read_b128 v[200:203], v3 offset:30720
	s_waitcnt lgkmcnt(3)
	v_pk_fma_f32 v[172:173], v[140:141], v[204:205], v[172:173]
	v_pk_fma_f32 v[188:189], v[156:157], v[204:205], v[188:189]
	v_pk_fma_f32 v[172:173], v[142:143], v[206:207], v[172:173]
	v_pk_fma_f32 v[188:189], v[158:159], v[206:207], v[188:189]
	ds_read_b128 v[204:207], v3 offset:31744
	s_waitcnt lgkmcnt(3)
	v_pk_mul_f32 v[174:175], v[128:129], v[192:193]
	v_pk_mul_f32 v[190:191], v[144:145], v[192:193]
	v_pk_fma_f32 v[174:175], v[130:131], v[194:195], v[174:175]
	v_pk_fma_f32 v[190:191], v[146:147], v[194:195], v[190:191]
	s_waitcnt lgkmcnt(2)
	v_pk_fma_f32 v[174:175], v[132:133], v[196:197], v[174:175]
	v_pk_fma_f32 v[190:191], v[148:149], v[196:197], v[190:191]
	v_pk_fma_f32 v[174:175], v[134:135], v[198:199], v[174:175]
	v_pk_fma_f32 v[190:191], v[150:151], v[198:199], v[190:191]
	s_waitcnt lgkmcnt(1)
	v_pk_fma_f32 v[174:175], v[136:137], v[200:201], v[174:175]
	v_pk_fma_f32 v[190:191], v[152:153], v[200:201], v[190:191]
	v_pk_fma_f32 v[174:175], v[138:139], v[202:203], v[174:175]
	v_pk_fma_f32 v[190:191], v[154:155], v[202:203], v[190:191]
	s_waitcnt lgkmcnt(0)
	v_pk_fma_f32 v[174:175], v[140:141], v[204:205], v[174:175]
	v_pk_fma_f32 v[190:191], v[156:157], v[204:205], v[190:191]
	v_pk_fma_f32 v[174:175], v[142:143], v[206:207], v[174:175]
	v_pk_fma_f32 v[190:191], v[158:159], v[206:207], v[190:191]
	v_add_f32_e32 v160, v160, v161
	v_add_f32_e32 v176, v176, v177
	v_add_f32_e32 v162, v162, v163
	v_add_f32_e32 v178, v178, v179
	v_add_f32_e32 v164, v164, v165
	v_add_f32_e32 v180, v180, v181
	v_add_f32_e32 v166, v166, v167
	v_add_f32_e32 v182, v182, v183
	v_add_f32_e32 v168, v168, v169
	v_add_f32_e32 v184, v184, v185
	v_add_f32_e32 v170, v170, v171
	v_add_f32_e32 v186, v186, v187
	v_add_f32_e32 v172, v172, v173
	v_add_f32_e32 v188, v188, v189
	v_add_f32_e32 v174, v174, v175
	v_add_f32_e32 v190, v190, v191
	v_cndmask_b32_e64 v216, v160, v168, s[38:39]
	v_cndmask_b32_e64 v217, v168, v160, s[38:39]
	v_cndmask_b32_e64 v224, v176, v184, s[38:39]
	v_cndmask_b32_e64 v225, v184, v176, s[38:39]
	v_cndmask_b32_e64 v218, v162, v170, s[38:39]
	v_cndmask_b32_e64 v219, v170, v162, s[38:39]
	v_cndmask_b32_e64 v226, v178, v186, s[38:39]
	v_cndmask_b32_e64 v227, v186, v178, s[38:39]
	v_cndmask_b32_e64 v220, v164, v172, s[38:39]
	v_cndmask_b32_e64 v221, v172, v164, s[38:39]
	v_cndmask_b32_e64 v228, v180, v188, s[38:39]
	v_cndmask_b32_e64 v229, v188, v180, s[38:39]
	v_cndmask_b32_e64 v222, v166, v174, s[38:39]
	v_cndmask_b32_e64 v223, v174, v166, s[38:39]
	v_cndmask_b32_e64 v230, v182, v190, s[38:39]
	v_cndmask_b32_e64 v231, v190, v182, s[38:39]
	s_nop 0
	v_add_f32_dpp v160, v217, v216 quad_perm:[1,0,3,2] row_mask:0xf bank_mask:0xf
	v_add_f32_dpp v176, v225, v224 quad_perm:[1,0,3,2] row_mask:0xf bank_mask:0xf
	v_add_f32_dpp v162, v219, v218 quad_perm:[1,0,3,2] row_mask:0xf bank_mask:0xf
	v_add_f32_dpp v178, v227, v226 quad_perm:[1,0,3,2] row_mask:0xf bank_mask:0xf
	v_add_f32_dpp v164, v221, v220 quad_perm:[1,0,3,2] row_mask:0xf bank_mask:0xf
	v_add_f32_dpp v180, v229, v228 quad_perm:[1,0,3,2] row_mask:0xf bank_mask:0xf
	v_add_f32_dpp v166, v223, v222 quad_perm:[1,0,3,2] row_mask:0xf bank_mask:0xf
	v_add_f32_dpp v182, v231, v230 quad_perm:[1,0,3,2] row_mask:0xf bank_mask:0xf
	v_cndmask_b32_e64 v216, v160, v164, s[40:41]
	v_cndmask_b32_e64 v217, v164, v160, s[40:41]
	v_cndmask_b32_e64 v224, v176, v180, s[40:41]
	v_cndmask_b32_e64 v225, v180, v176, s[40:41]
	v_cndmask_b32_e64 v218, v162, v166, s[40:41]
	v_cndmask_b32_e64 v219, v166, v162, s[40:41]
	v_cndmask_b32_e64 v226, v178, v182, s[40:41]
	v_cndmask_b32_e64 v227, v182, v178, s[40:41]
	s_nop 0
	v_add_f32_dpp v160, v217, v216 quad_perm:[2,3,0,1] row_mask:0xf bank_mask:0xf
	v_add_f32_dpp v176, v225, v224 quad_perm:[2,3,0,1] row_mask:0xf bank_mask:0xf
	v_add_f32_dpp v162, v219, v218 quad_perm:[2,3,0,1] row_mask:0xf bank_mask:0xf
	v_add_f32_dpp v178, v227, v226 quad_perm:[2,3,0,1] row_mask:0xf bank_mask:0xf
	v_cndmask_b32_e64 v216, v160, v162, s[42:43]
	v_cndmask_b32_e64 v217, v162, v160, s[42:43]
	v_cndmask_b32_e64 v224, v176, v178, s[42:43]
	v_cndmask_b32_e64 v225, v178, v176, s[42:43]
	s_nop 0
	v_add_f32_dpp v160, v217, v216 row_shl:4 row_mask:0xf bank_mask:0x5
	v_add_f32_dpp v160, v217, v216 row_shr:4 row_mask:0xf bank_mask:0xa
	v_add_f32_dpp v176, v225, v224 row_shl:4 row_mask:0xf bank_mask:0x5
	v_add_f32_dpp v176, v225, v224 row_shr:4 row_mask:0xf bank_mask:0xa
	s_nop 1
	v_add_f32_dpp v160, v160, v160 row_ror:8 row_mask:0xf bank_mask:0xf
	v_add_f32_dpp v176, v176, v176 row_ror:8 row_mask:0xf bank_mask:0xf
	s_nop 0
	ds_bpermute_b32 v161, v5, v160
	ds_bpermute_b32 v177, v5, v176
	s_waitcnt lgkmcnt(0)
; template <bool WITH_DT, bool OUT8> __device__ __forceinline__ void norm_mod_rows(const void* xp, bool pb16, const void* xs, bool sb16, const float* w, const float* MOD, int ish, int isc, bf16* H, ...
;     ...
;         for (int j = 0; j < 4; ++j) s += (v[j][0] * v[j][0] + v[j][1] * v[j][1]) + (v[j][2] * v[j][2] + v[j][3] * v[j][3]);
;         const float rstd = rsqrtf(wave_sum(s) * (1.0f / DM) + EPSN);
;     ...
;             float e4[4], e2[2], e1;
;             { const bool up = (lane & 32) != 0;
; #pragma unroll
;               for (int c = 0; c < 4; ++c) { const float keep = up ? d[4 + c] : d[c], give = up ? d[c] : d[4 + c]; e4[c] = keep + __shfl_xor(give, 32); } }
;             { const bool up = (lane & 16) != 0;
; #pragma unroll
;               for (int c = 0; c < 2; ++c) { const float keep = up ? e4[2 + c] : e4[c], give = up ? e4[c] : e4[2 + c]; e2[c] = keep + __shfl_xor(give, 16); } }
;             { const bool up = (lane & 8) != 0; const float keep = up ? e2[1] : e2[0], give = up ? e2[0] : e2[1]; e1 = keep + __shfl_xor(give, 8); }
;             e1 += __shfl_xor(e1, 4); e1 += __shfl_xor(e1, 2); e1 += __shfl_xor(e1, 1);
;             const int col = ((lane >> 5) & 1) * 4 + ((lane >> 4) & 1) * 2 + ((lane >> 3) & 1);
;             if ((lane & 7) == 0) { const float p = e1 + dt_bias[col]; DT[(size_t)row * 8 + col] = fmaxf(p, 0.f) + log1pf(__expf(-fabsf(p))); }
	v_add_f32_e32 v160, v160, v161
	v_add_f32_e32 v176, v176, v177
	v_mov_b32_e32 v161, v160
	v_mov_b32_e32 v177, v176
	s_nop 1
	v_permlane32_swap_b32_e32 v160, v161
	v_permlane32_swap_b32_e32 v176, v177
	v_add_f32_e32 v160, v160, v161
	v_add_f32_e32 v176, v176, v177
	v_add_f32_e32 v160, v160, v12
	v_add_f32_e32 v176, v176, v12
	v_and_b32_e32 v216, 0x7fffffff, v160
	v_and_b32_e32 v224, 0x7fffffff, v176
	v_mul_f32_e32 v216, 0xbfb8aa3b, v216
	v_mul_f32_e32 v224, 0xbfb8aa3b, v224
	v_exp_f32_e32 v216, v216
	v_exp_f32_e32 v224, v224
	s_nop 0
	v_add_f32_e32 v217, 1.0, v216
	v_add_f32_e32 v225, 1.0, v224
	v_log_f32_e32 v218, v217
	v_log_f32_e32 v226, v225
	v_add_f32_e32 v219, -1.0, v217
	v_add_f32_e32 v227, -1.0, v225
	v_rcp_f32_e32 v219, v219
	v_rcp_f32_e32 v227, v227
	v_mul_f32_e32 v218, 0x3f317218, v218
	v_mul_f32_e32 v226, 0x3f317218, v226
	v_mul_f32_e32 v219, v216, v219
	v_mul_f32_e32 v227, v224, v227
	v_mul_f32_e32 v218, v218, v219
	v_mul_f32_e32 v226, v226, v227
	v_cmp_eq_f32_e32 vcc, 1.0, v217
	s_nop 1
	v_cndmask_b32_e32 v218, v218, v216, vcc
	v_cmp_eq_f32_e32 vcc, 1.0, v225
	s_nop 1
	v_cndmask_b32_e32 v226, v226, v224, vcc
	v_max_f32_e32 v160, 0, v160
	v_max_f32_e32 v176, 0, v176
	v_add_f32_e32 v160, v160, v218
	v_add_f32_e32 v176, v176, v226
	v_cndmask_b32_e64 v160, v160, v176, s[44:45]
	s_mov_b64 exec, 0xffff
	global_store_dword v4, v160, s[28:29]
	s_mov_b64 exec, -1
	s_add_u32 s28, s28, 64
	s_addc_u32 s29, s29, 0
	s_waitcnt vmcnt(33)
	v_lshlrev_b32_e32 v128, 16, v80
	v_and_b32_e32 v129, 0xffff0000, v80
	v_lshlrev_b32_e32 v130, 16, v81
	v_and_b32_e32 v131, 0xffff0000, v81
	v_lshlrev_b32_e32 v132, 16, v82
	v_and_b32_e32 v133, 0xffff0000, v82
	v_lshlrev_b32_e32 v134, 16, v83
	v_and_b32_e32 v135, 0xffff0000, v83
	v_lshlrev_b32_e32 v136, 16, v84
	v_and_b32_e32 v137, 0xffff0000, v84
	v_lshlrev_b32_e32 v138, 16, v85
	v_and_b32_e32 v139, 0xffff0000, v85
	v_lshlrev_b32_e32 v140, 16, v86
	v_and_b32_e32 v141, 0xffff0000, v86
	v_lshlrev_b32_e32 v142, 16, v87
	v_and_b32_e32 v143, 0xffff0000, v87
	v_lshlrev_b32_e32 v144, 16, v88
	v_and_b32_e32 v145, 0xffff0000, v88
	v_lshlrev_b32_e32 v146, 16, v89
	v_and_b32_e32 v147, 0xffff0000, v89
	v_lshlrev_b32_e32 v148, 16, v90
	v_and_b32_e32 v149, 0xffff0000, v90
	v_lshlrev_b32_e32 v150, 16, v91
	v_and_b32_e32 v151, 0xffff0000, v91
	v_lshlrev_b32_e32 v152, 16, v92
	v_and_b32_e32 v153, 0xffff0000, v92
	v_lshlrev_b32_e32 v154, 16, v93
	v_and_b32_e32 v155, 0xffff0000, v93
	v_lshlrev_b32_e32 v156, 16, v94
	v_and_b32_e32 v157, 0xffff0000, v94
	v_lshlrev_b32_e32 v158, 16, v95
	v_and_b32_e32 v159, 0xffff0000, v95
	global_load_dwordx2 v[80:81], v2, s[18:19]
	global_load_dwordx2 v[82:83], v2, s[18:19] offset:512
	global_load_dwordx2 v[84:85], v2, s[18:19] offset:1024
	global_load_dwordx2 v[86:87], v2, s[18:19] offset:1536
	s_add_u32 s18, s18, 0x800
	s_addc_u32 s19, s19, 0
	global_load_dwordx2 v[88:89], v2, s[18:19]
	global_load_dwordx2 v[90:91], v2, s[18:19] offset:512
	global_load_dwordx2 v[92:93], v2, s[18:19] offset:1024
	global_load_dwordx2 v[94:95], v2, s[18:19] offset:1536
	s_add_u32 s18, s18, 0x800
	s_addc_u32 s19, s19, 0
	v_pk_mul_f32 v[208:209], v[128:129], v[128:129]
	v_pk_mul_f32 v[210:211], v[130:131], v[130:131]
	v_pk_mul_f32 v[212:213], v[144:145], v[144:145]
	v_pk_mul_f32 v[214:215], v[146:147], v[146:147]
	v_pk_fma_f32 v[208:209], v[132:133], v[132:133], v[208:209]
	v_pk_fma_f32 v[210:211], v[134:135], v[134:135], v[210:211]
	v_pk_fma_f32 v[212:213], v[148:149], v[148:149], v[212:213]
	v_pk_fma_f32 v[214:215], v[150:151], v[150:151], v[214:215]
	v_pk_fma_f32 v[208:209], v[136:137], v[136:137], v[208:209]
	v_pk_fma_f32 v[210:211], v[138:139], v[138:139], v[210:211]
	v_pk_fma_f32 v[212:213], v[152:153], v[152:153], v[212:213]
	v_pk_fma_f32 v[214:215], v[154:155], v[154:155], v[214:215]
	v_pk_fma_f32 v[208:209], v[140:141], v[140:141], v[208:209]
	v_pk_fma_f32 v[210:211], v[142:143], v[142:143], v[210:211]
	v_pk_fma_f32 v[212:213], v[156:157], v[156:157], v[212:213]
	v_pk_fma_f32 v[214:215], v[158:159], v[158:159], v[214:215]
	v_pk_add_f32 v[208:209], v[208:209], v[210:211]
	v_pk_add_f32 v[212:213], v[212:213], v[214:215]
	v_add_f32_e32 v208, v208, v209
	v_add_f32_e32 v212, v212, v213
	s_nop 0
	v_add_f32_dpp v208, v208, v208 quad_perm:[1,0,3,2] row_mask:0xf bank_mask:0xf
	v_add_f32_dpp v212, v212, v212 quad_perm:[1,0,3,2] row_mask:0xf bank_mask:0xf
	s_nop 0
	v_add_f32_dpp v208, v208, v208 quad_perm:[2,3,0,1] row_mask:0xf bank_mask:0xf
	v_add_f32_dpp v212, v212, v212 quad_perm:[2,3,0,1] row_mask:0xf bank_mask:0xf
	s_nop 0
	v_add_f32_dpp v208, v208, v208 row_half_mirror row_mask:0xf bank_mask:0xf
	v_add_f32_dpp v212, v212, v212 row_half_mirror row_mask:0xf bank_mask:0xf
	s_nop 0
	v_add_f32_dpp v208, v208, v208 row_mirror row_mask:0xf bank_mask:0xf
	v_add_f32_dpp v212, v212, v212 row_mirror row_mask:0xf bank_mask:0xf
	s_nop 0
	v_readlane_b32 s30, v208, 0
	v_readlane_b32 s31, v208, 16
	v_readlane_b32 s32, v208, 32
	v_readlane_b32 s33, v208, 48
	v_readlane_b32 s34, v212, 0
	v_readlane_b32 s35, v212, 16
	v_readlane_b32 s36, v212, 32
	v_readlane_b32 s37, v212, 48
	s_nop 1
	v_mov_b32_e32 v209, s30
	v_mov_b32_e32 v213, s34
	v_add_f32_e32 v209, s31, v209
	v_add_f32_e32 v213, s35, v213
	v_add_f32_e32 v209, s32, v209
	v_add_f32_e32 v213, s36, v213
	v_add_f32_e32 v209, s33, v209
	v_add_f32_e32 v213, s37, v213
	v_fmamk_f32 v209, v209, 0x3a800000, v8
	v_fmamk_f32 v213, v213, 0x3a800000, v8
	v_rsq_f32_e32 v210, v209
	v_rsq_f32_e32 v214, v213
	s_nop 0
	v_pk_mul_f32 v[128:129], v[128:129], v[210:211] op_sel_hi:[1,0]
	v_pk_mul_f32 v[130:131], v[130:131], v[210:211] op_sel_hi:[1,0]
	v_pk_mul_f32 v[132:133], v[132:133], v[210:211] op_sel_hi:[1,0]
; __device__ __forceinline__ unsigned pk2(float lo, float hi) { return pg8::cvt_pk_bf16(lo, hi); }
; template <bool WITH_DT, bool OUT8> __device__ __forceinline__ void norm_mod_rows(const void* xp, bool pb16, const void* xs, bool sb16, const float* w, const float* MOD, int ish, int isc, bf16* H, ...
;     ...
;         const f32x4* sh = (const f32x4*)(MOD + (size_t)mb * 9216 + ish * 1024); const f32x4* sc = (const f32x4*)(MOD + (size_t)mb * 9216 + isc * 1024);
; #pragma unroll
;         for (int j = 0; j < 4; ++j) { const f32x4 a = v[j] * rstd * wv[j]; v[j] = a * (sc[lane + 64 * j] + 1.0f) + sh[lane + 64 * j];
;             if (OUT8) { *(unsigned*)((unsigned char*)H + (size_t)row * DM + 4 * (lane + 64 * j)) = pk4_fp8(v[j][0] * SC_H8, v[j][1] * SC_H8, v[j][2] * SC_H8, v[j][3] * SC_H8); }
;             else { v2u o; o.x = pk2(v[j][0], v[j][1]); o.y = pk2(v[j][2], v[j][3]); *(v2u*)(H + (size_t)row * DM + 4 * (lane + 64 * j)) = o; } }
;         if (WITH_DT) {
;             float d[8];
; #pragma unroll
;             for (int c = 0; c < 8; ++c) { float p = 0.f;
; #pragma unroll
;                 for (int j = 0; j < 4; ++j) { const f32x4 ww = wdt[WITH_DT ? c : 0][j]; p += (v[j][0] * ww[0] + v[j][1] * ww[1]) + (v[j][2] * ww[2] + v[j][3] * ww[3]); }
;                 d[c] = p; }
	v_pk_mul_f32 v[134:135], v[134:135], v[210:211] op_sel_hi:[1,0]
	v_pk_mul_f32 v[136:137], v[136:137], v[210:211] op_sel_hi:[1,0]
	v_pk_mul_f32 v[138:139], v[138:139], v[210:211] op_sel_hi:[1,0]
	v_pk_mul_f32 v[140:141], v[140:141], v[210:211] op_sel_hi:[1,0]
	v_pk_mul_f32 v[142:143], v[142:143], v[210:211] op_sel_hi:[1,0]
	v_pk_mul_f32 v[144:145], v[144:145], v[214:215] op_sel_hi:[1,0]
	v_pk_mul_f32 v[146:147], v[146:147], v[214:215] op_sel_hi:[1,0]
	v_pk_mul_f32 v[148:149], v[148:149], v[214:215] op_sel_hi:[1,0]
	v_pk_mul_f32 v[150:151], v[150:151], v[214:215] op_sel_hi:[1,0]
	v_pk_mul_f32 v[152:153], v[152:153], v[214:215] op_sel_hi:[1,0]
	v_pk_mul_f32 v[154:155], v[154:155], v[214:215] op_sel_hi:[1,0]
	v_pk_mul_f32 v[156:157], v[156:157], v[214:215] op_sel_hi:[1,0]
	v_pk_mul_f32 v[158:159], v[158:159], v[214:215] op_sel_hi:[1,0]
	v_pk_fma_f32 v[128:129], v[128:129], v[16:17], v[32:33]
	v_pk_fma_f32 v[130:131], v[130:131], v[18:19], v[34:35]
	v_pk_fma_f32 v[132:133], v[132:133], v[20:21], v[36:37]
	v_pk_fma_f32 v[134:135], v[134:135], v[22:23], v[38:39]
	v_pk_fma_f32 v[136:137], v[136:137], v[24:25], v[40:41]
	v_pk_fma_f32 v[138:139], v[138:139], v[26:27], v[42:43]
	v_pk_fma_f32 v[140:141], v[140:141], v[28:29], v[44:45]
	v_pk_fma_f32 v[142:143], v[142:143], v[30:31], v[46:47]
	v_pk_fma_f32 v[144:145], v[144:145], v[16:17], v[32:33]
	v_pk_fma_f32 v[146:147], v[146:147], v[18:19], v[34:35]
	v_pk_fma_f32 v[148:149], v[148:149], v[20:21], v[36:37]
	v_pk_fma_f32 v[150:151], v[150:151], v[22:23], v[38:39]
	v_pk_fma_f32 v[152:153], v[152:153], v[24:25], v[40:41]
	v_pk_fma_f32 v[154:155], v[154:155], v[26:27], v[42:43]
	v_pk_fma_f32 v[156:157], v[156:157], v[28:29], v[44:45]
	v_pk_fma_f32 v[158:159], v[158:159], v[30:31], v[46:47]
	v_cvt_pk_bf16_f32 v216, v128, v129
	v_cvt_pk_bf16_f32 v217, v130, v131
	v_cvt_pk_bf16_f32 v218, v132, v133
	v_cvt_pk_bf16_f32 v219, v134, v135
	v_cvt_pk_bf16_f32 v220, v136, v137
	v_cvt_pk_bf16_f32 v221, v138, v139
	v_cvt_pk_bf16_f32 v222, v140, v141
	v_cvt_pk_bf16_f32 v223, v142, v143
	v_cvt_pk_bf16_f32 v224, v144, v145
	v_cvt_pk_bf16_f32 v225, v146, v147
	v_cvt_pk_bf16_f32 v226, v148, v149
	v_cvt_pk_bf16_f32 v227, v150, v151
	v_cvt_pk_bf16_f32 v228, v152, v153
	v_cvt_pk_bf16_f32 v229, v154, v155
	v_cvt_pk_bf16_f32 v230, v156, v157
	v_cvt_pk_bf16_f32 v231, v158, v159
	global_store_dwordx2 v2, v[216:217], s[20:21]
	global_store_dwordx2 v2, v[218:219], s[20:21] offset:512
	global_store_dwordx2 v2, v[220:221], s[20:21] offset:1024
	global_store_dwordx2 v2, v[222:223], s[20:21] offset:1536
	global_store_dwordx2 v2, v[224:225], s[20:21] offset:2048
	global_store_dwordx2 v2, v[226:227], s[20:21] offset:2560
	global_store_dwordx2 v2, v[228:229], s[20:21] offset:3072
	global_store_dwordx2 v2, v[230:231], s[20:21] offset:3584
	s_add_u32 s20, s20, 0x1000
	s_addc_u32 s21, s21, 0
	ds_read_b128 v[192:195], v3 offset:0
	ds_read_b128 v[196:199], v3 offset:1024
	ds_read_b128 v[200:203], v3 offset:2048
	ds_read_b128 v[204:207], v3 offset:3072
	s_waitcnt lgkmcnt(3)
	v_pk_mul_f32 v[160:161], v[128:129], v[192:193]
	v_pk_mul_f32 v[176:177], v[144:145], v[192:193]
	v_pk_fma_f32 v[160:161], v[130:131], v[194:195], v[160:161]
	v_pk_fma_f32 v[176:177], v[146:147], v[194:195], v[176:177]
	ds_read_b128 v[192:195], v3 offset:4096
	s_waitcnt lgkmcnt(3)
	v_pk_fma_f32 v[160:161], v[132:133], v[196:197], v[160:161]
	v_pk_fma_f32 v[176:177], v[148:149], v[196:197], v[176:177]
	v_pk_fma_f32 v[160:161], v[134:135], v[198:199], v[160:161]
	v_pk_fma_f32 v[176:177], v[150:151], v[198:199], v[176:177]
	ds_read_b128 v[196:199], v3 offset:5120
	s_waitcnt lgkmcnt(3)
	v_pk_fma_f32 v[160:161], v[136:137], v[200:201], v[160:161]
	v_pk_fma_f32 v[176:177], v[152:153], v[200:201], v[176:177]
	v_pk_fma_f32 v[160:161], v[138:139], v[202:203], v[160:161]
	v_pk_fma_f32 v[176:177], v[154:155], v[202:203], v[176:177]
	ds_read_b128 v[200:203], v3 offset:6144
	s_waitcnt lgkmcnt(3)
	v_pk_fma_f32 v[160:161], v[140:141], v[204:205], v[160:161]
	v_pk_fma_f32 v[176:177], v[156:157], v[204:205], v[176:177]
	v_pk_fma_f32 v[160:161], v[142:143], v[206:207], v[160:161]
	v_pk_fma_f32 v[176:177], v[158:159], v[206:207], v[176:177]
	ds_read_b128 v[204:207], v3 offset:7168
	s_waitcnt lgkmcnt(3)
	v_pk_mul_f32 v[162:163], v[128:129], v[192:193]
	v_pk_mul_f32 v[178:179], v[144:145], v[192:193]
	v_pk_fma_f32 v[162:163], v[130:131], v[194:195], v[162:163]
	v_pk_fma_f32 v[178:179], v[146:147], v[194:195], v[178:179]
	ds_read_b128 v[192:195], v3 offset:8192
	s_waitcnt lgkmcnt(3)
	v_pk_fma_f32 v[162:163], v[132:133], v[196:197], v[162:163]
	v_pk_fma_f32 v[178:179], v[148:149], v[196:197], v[178:179]
	v_pk_fma_f32 v[162:163], v[134:135], v[198:199], v[162:163]
	v_pk_fma_f32 v[178:179], v[150:151], v[198:199], v[178:179]
	ds_read_b128 v[196:199], v3 offset:9216
	s_waitcnt lgkmcnt(3)
	v_pk_fma_f32 v[162:163], v[136:137], v[200:201], v[162:163]
	v_pk_fma_f32 v[178:179], v[152:153], v[200:201], v[178:179]
	v_pk_fma_f32 v[162:163], v[138:139], v[202:203], v[162:163]
	v_pk_fma_f32 v[178:179], v[154:155], v[202:203], v[178:179]
	ds_read_b128 v[200:203], v3 offset:10240
	s_waitcnt lgkmcnt(3)
	v_pk_fma_f32 v[162:163], v[140:141], v[204:205], v[162:163]
	v_pk_fma_f32 v[178:179], v[156:157], v[204:205], v[178:179]
	v_pk_fma_f32 v[162:163], v[142:143], v[206:207], v[162:163]
	v_pk_fma_f32 v[178:179], v[158:159], v[206:207], v[178:179]
	ds_read_b128 v[204:207], v3 offset:11264
	s_waitcnt lgkmcnt(3)
	v_pk_mul_f32 v[164:165], v[128:129], v[192:193]
	v_pk_mul_f32 v[180:181], v[144:145], v[192:193]
	v_pk_fma_f32 v[164:165], v[130:131], v[194:195], v[164:165]
	v_pk_fma_f32 v[180:181], v[146:147], v[194:195], v[180:181]
	ds_read_b128 v[192:195], v3 offset:12288
	s_waitcnt lgkmcnt(3)
; template <bool WITH_DT, bool OUT8> __device__ __forceinline__ void norm_mod_rows(const void* xp, bool pb16, const void* xs, bool sb16, const float* w, const float* MOD, int ish, int isc, bf16* H, ...
;     ...
;             for (int c = 0; c < 8; ++c) { float p = 0.f;
; #pragma unroll
;                 for (int j = 0; j < 4; ++j) { const f32x4 ww = wdt[WITH_DT ? c : 0][j]; p += (v[j][0] * ww[0] + v[j][1] * ww[1]) + (v[j][2] * ww[2] + v[j][3] * ww[3]); }
;                 d[c] = p; }
	v_pk_fma_f32 v[164:165], v[132:133], v[196:197], v[164:165]
	v_pk_fma_f32 v[180:181], v[148:149], v[196:197], v[180:181]
	v_pk_fma_f32 v[164:165], v[134:135], v[198:199], v[164:165]
	v_pk_fma_f32 v[180:181], v[150:151], v[198:199], v[180:181]
	ds_read_b128 v[196:199], v3 offset:13312
	s_waitcnt lgkmcnt(3)
	v_pk_fma_f32 v[164:165], v[136:137], v[200:201], v[164:165]
	v_pk_fma_f32 v[180:181], v[152:153], v[200:201], v[180:181]
	v_pk_fma_f32 v[164:165], v[138:139], v[202:203], v[164:165]
	v_pk_fma_f32 v[180:181], v[154:155], v[202:203], v[180:181]
	ds_read_b128 v[200:203], v3 offset:14336
	s_waitcnt lgkmcnt(3)
	v_pk_fma_f32 v[164:165], v[140:141], v[204:205], v[164:165]
	v_pk_fma_f32 v[180:181], v[156:157], v[204:205], v[180:181]
	v_pk_fma_f32 v[164:165], v[142:143], v[206:207], v[164:165]
	v_pk_fma_f32 v[180:181], v[158:159], v[206:207], v[180:181]
	ds_read_b128 v[204:207], v3 offset:15360
	s_waitcnt lgkmcnt(3)
	v_pk_mul_f32 v[166:167], v[128:129], v[192:193]
	v_pk_mul_f32 v[182:183], v[144:145], v[192:193]
	v_pk_fma_f32 v[166:167], v[130:131], v[194:195], v[166:167]
	v_pk_fma_f32 v[182:183], v[146:147], v[194:195], v[182:183]
	ds_read_b128 v[192:195], v3 offset:16384
	s_waitcnt lgkmcnt(3)
	v_pk_fma_f32 v[166:167], v[132:133], v[196:197], v[166:167]
	v_pk_fma_f32 v[182:183], v[148:149], v[196:197], v[182:183]
	v_pk_fma_f32 v[166:167], v[134:135], v[198:199], v[166:167]
	v_pk_fma_f32 v[182:183], v[150:151], v[198:199], v[182:183]
	ds_read_b128 v[196:199], v3 offset:17408
	s_waitcnt lgkmcnt(3)
	v_pk_fma_f32 v[166:167], v[136:137], v[200:201], v[166:167]
	v_pk_fma_f32 v[182:183], v[152:153], v[200:201], v[182:183]
	v_pk_fma_f32 v[166:167], v[138:139], v[202:203], v[166:167]
	v_pk_fma_f32 v[182:183], v[154:155], v[202:203], v[182:183]
	ds_read_b128 v[200:203], v3 offset:18432
	s_waitcnt lgkmcnt(3)
	v_pk_fma_f32 v[166:167], v[140:141], v[204:205], v[166:167]
	v_pk_fma_f32 v[182:183], v[156:157], v[204:205], v[182:183]
	v_pk_fma_f32 v[166:167], v[142:143], v[206:207], v[166:167]
	v_pk_fma_f32 v[182:183], v[158:159], v[206:207], v[182:183]
	ds_read_b128 v[204:207], v3 offset:19456
	s_waitcnt lgkmcnt(3)
	v_pk_mul_f32 v[168:169], v[128:129], v[192:193]
	v_pk_mul_f32 v[184:185], v[144:145], v[192:193]
	v_pk_fma_f32 v[168:169], v[130:131], v[194:195], v[168:169]
	v_pk_fma_f32 v[184:185], v[146:147], v[194:195], v[184:185]
	ds_read_b128 v[192:195], v3 offset:20480
	s_waitcnt lgkmcnt(3)
	v_pk_fma_f32 v[168:169], v[132:133], v[196:197], v[168:169]
	v_pk_fma_f32 v[184:185], v[148:149], v[196:197], v[184:185]
	v_pk_fma_f32 v[168:169], v[134:135], v[198:199], v[168:169]
	v_pk_fma_f32 v[184:185], v[150:151], v[198:199], v[184:185]
	ds_read_b128 v[196:199], v3 offset:21504
	s_waitcnt lgkmcnt(3)
	v_pk_fma_f32 v[168:169], v[136:137], v[200:201], v[168:169]
	v_pk_fma_f32 v[184:185], v[152:153], v[200:201], v[184:185]
	v_pk_fma_f32 v[168:169], v[138:139], v[202:203], v[168:169]
	v_pk_fma_f32 v[184:185], v[154:155], v[202:203], v[184:185]
	ds_read_b128 v[200:203], v3 offset:22528
	s_waitcnt lgkmcnt(3)
	v_pk_fma_f32 v[168:169], v[140:141], v[204:205], v[168:169]
	v_pk_fma_f32 v[184:185], v[156:157], v[204:205], v[184:185]
	v_pk_fma_f32 v[168:169], v[142:143], v[206:207], v[168:169]
	v_pk_fma_f32 v[184:185], v[158:159], v[206:207], v[184:185]
	ds_read_b128 v[204:207], v3 offset:23552
	s_waitcnt lgkmcnt(3)
	v_pk_mul_f32 v[170:171], v[128:129], v[192:193]
	v_pk_mul_f32 v[186:187], v[144:145], v[192:193]
	v_pk_fma_f32 v[170:171], v[130:131], v[194:195], v[170:171]
	v_pk_fma_f32 v[186:187], v[146:147], v[194:195], v[186:187]
	ds_read_b128 v[192:195], v3 offset:24576
	s_waitcnt lgkmcnt(3)
	v_pk_fma_f32 v[170:171], v[132:133], v[196:197], v[170:171]
	v_pk_fma_f32 v[186:187], v[148:149], v[196:197], v[186:187]
	v_pk_fma_f32 v[170:171], v[134:135], v[198:199], v[170:171]
	v_pk_fma_f32 v[186:187], v[150:151], v[198:199], v[186:187]
	ds_read_b128 v[196:199], v3 offset:25600
	s_waitcnt lgkmcnt(3)
	v_pk_fma_f32 v[170:171], v[136:137], v[200:201], v[170:171]
	v_pk_fma_f32 v[186:187], v[152:153], v[200:201], v[186:187]
	v_pk_fma_f32 v[170:171], v[138:139], v[202:203], v[170:171]
	v_pk_fma_f32 v[186:187], v[154:155], v[202:203], v[186:187]
	ds_read_b128 v[200:203], v3 offset:26624
	s_waitcnt lgkmcnt(3)
	v_pk_fma_f32 v[170:171], v[140:141], v[204:205], v[170:171]
	v_pk_fma_f32 v[186:187], v[156:157], v[204:205], v[186:187]
	v_pk_fma_f32 v[170:171], v[142:143], v[206:207], v[170:171]
	v_pk_fma_f32 v[186:187], v[158:159], v[206:207], v[186:187]
	ds_read_b128 v[204:207], v3 offset:27648
	s_waitcnt lgkmcnt(3)
	v_pk_mul_f32 v[172:173], v[128:129], v[192:193]
	v_pk_mul_f32 v[188:189], v[144:145], v[192:193]
	v_pk_fma_f32 v[172:173], v[130:131], v[194:195], v[172:173]
	v_pk_fma_f32 v[188:189], v[146:147], v[194:195], v[188:189]
	ds_read_b128 v[192:195], v3 offset:28672
	s_waitcnt lgkmcnt(3)
	v_pk_fma_f32 v[172:173], v[132:133], v[196:197], v[172:173]
	v_pk_fma_f32 v[188:189], v[148:149], v[196:197], v[188:189]
	v_pk_fma_f32 v[172:173], v[134:135], v[198:199], v[172:173]
	v_pk_fma_f32 v[188:189], v[150:151], v[198:199], v[188:189]
	ds_read_b128 v[196:199], v3 offset:29696
	s_waitcnt lgkmcnt(3)
	v_pk_fma_f32 v[172:173], v[136:137], v[200:201], v[172:173]
	v_pk_fma_f32 v[188:189], v[152:153], v[200:201], v[188:189]
	v_pk_fma_f32 v[172:173], v[138:139], v[202:203], v[172:173]
	v_pk_fma_f32 v[188:189], v[154:155], v[202:203], v[188:189]
	ds_read_b128 v[200:203], v3 offset:30720
	s_waitcnt lgkmcnt(3)
	v_pk_fma_f32 v[172:173], v[140:141], v[204:205], v[172:173]
	v_pk_fma_f32 v[188:189], v[156:157], v[204:205], v[188:189]
	v_pk_fma_f32 v[172:173], v[142:143], v[206:207], v[172:173]
	v_pk_fma_f32 v[188:189], v[158:159], v[206:207], v[188:189]
	ds_read_b128 v[204:207], v3 offset:31744
	s_waitcnt lgkmcnt(3)
; template <bool WITH_DT, bool OUT8> __device__ __forceinline__ void norm_mod_rows(const void* xp, bool pb16, const void* xs, bool sb16, const float* w, const float* MOD, int ish, int isc, bf16* H, ...
;     ...
;                 d[c] = p; }
;             float e4[4], e2[2], e1;
;             { const bool up = (lane & 32) != 0;
; #pragma unroll
;               for (int c = 0; c < 4; ++c) { const float keep = up ? d[4 + c] : d[c], give = up ? d[c] : d[4 + c]; e4[c] = keep + __shfl_xor(give, 32); } }
;             { const bool up = (lane & 16) != 0;
; #pragma unroll
;               for (int c = 0; c < 2; ++c) { const float keep = up ? e4[2 + c] : e4[c], give = up ? e4[c] : e4[2 + c]; e2[c] = keep + __shfl_xor(give, 16); } }
;             { const bool up = (lane & 8) != 0; const float keep = up ? e2[1] : e2[0], give = up ? e2[0] : e2[1]; e1 = keep + __shfl_xor(give, 8); }
;             e1 += __shfl_xor(e1, 4); e1 += __shfl_xor(e1, 2); e1 += __shfl_xor(e1, 1);
;             const int col = ((lane >> 5) & 1) * 4 + ((lane >> 4) & 1) * 2 + ((lane >> 3) & 1);
;             if ((lane & 7) == 0) { const float p = e1 + dt_bias[col]; DT[(size_t)row * 8 + col] = fmaxf(p, 0.f) + log1pf(__expf(-fabsf(p))); }
	v_pk_mul_f32 v[174:175], v[128:129], v[192:193]
	v_pk_mul_f32 v[190:191], v[144:145], v[192:193]
	v_pk_fma_f32 v[174:175], v[130:131], v[194:195], v[174:175]
	v_pk_fma_f32 v[190:191], v[146:147], v[194:195], v[190:191]
	s_waitcnt lgkmcnt(2)
	v_pk_fma_f32 v[174:175], v[132:133], v[196:197], v[174:175]
	v_pk_fma_f32 v[190:191], v[148:149], v[196:197], v[190:191]
	v_pk_fma_f32 v[174:175], v[134:135], v[198:199], v[174:175]
	v_pk_fma_f32 v[190:191], v[150:151], v[198:199], v[190:191]
	s_waitcnt lgkmcnt(1)
	v_pk_fma_f32 v[174:175], v[136:137], v[200:201], v[174:175]
	v_pk_fma_f32 v[190:191], v[152:153], v[200:201], v[190:191]
	v_pk_fma_f32 v[174:175], v[138:139], v[202:203], v[174:175]
	v_pk_fma_f32 v[190:191], v[154:155], v[202:203], v[190:191]
	s_waitcnt lgkmcnt(0)
	v_pk_fma_f32 v[174:175], v[140:141], v[204:205], v[174:175]
	v_pk_fma_f32 v[190:191], v[156:157], v[204:205], v[190:191]
	v_pk_fma_f32 v[174:175], v[142:143], v[206:207], v[174:175]
	v_pk_fma_f32 v[190:191], v[158:159], v[206:207], v[190:191]
	v_add_f32_e32 v160, v160, v161
	v_add_f32_e32 v176, v176, v177
	v_add_f32_e32 v162, v162, v163
	v_add_f32_e32 v178, v178, v179
	v_add_f32_e32 v164, v164, v165
	v_add_f32_e32 v180, v180, v181
	v_add_f32_e32 v166, v166, v167
	v_add_f32_e32 v182, v182, v183
	v_add_f32_e32 v168, v168, v169
	v_add_f32_e32 v184, v184, v185
	v_add_f32_e32 v170, v170, v171
	v_add_f32_e32 v186, v186, v187
	v_add_f32_e32 v172, v172, v173
	v_add_f32_e32 v188, v188, v189
	v_add_f32_e32 v174, v174, v175
	v_add_f32_e32 v190, v190, v191
	v_cndmask_b32_e64 v216, v160, v168, s[38:39]
	v_cndmask_b32_e64 v217, v168, v160, s[38:39]
	v_cndmask_b32_e64 v224, v176, v184, s[38:39]
	v_cndmask_b32_e64 v225, v184, v176, s[38:39]
	v_cndmask_b32_e64 v218, v162, v170, s[38:39]
	v_cndmask_b32_e64 v219, v170, v162, s[38:39]
	v_cndmask_b32_e64 v226, v178, v186, s[38:39]
	v_cndmask_b32_e64 v227, v186, v178, s[38:39]
	v_cndmask_b32_e64 v220, v164, v172, s[38:39]
	v_cndmask_b32_e64 v221, v172, v164, s[38:39]
	v_cndmask_b32_e64 v228, v180, v188, s[38:39]
	v_cndmask_b32_e64 v229, v188, v180, s[38:39]
	v_cndmask_b32_e64 v222, v166, v174, s[38:39]
	v_cndmask_b32_e64 v223, v174, v166, s[38:39]
	v_cndmask_b32_e64 v230, v182, v190, s[38:39]
	v_cndmask_b32_e64 v231, v190, v182, s[38:39]
	s_nop 0
	v_add_f32_dpp v160, v217, v216 quad_perm:[1,0,3,2] row_mask:0xf bank_mask:0xf
	v_add_f32_dpp v176, v225, v224 quad_perm:[1,0,3,2] row_mask:0xf bank_mask:0xf
	v_add_f32_dpp v162, v219, v218 quad_perm:[1,0,3,2] row_mask:0xf bank_mask:0xf
	v_add_f32_dpp v178, v227, v226 quad_perm:[1,0,3,2] row_mask:0xf bank_mask:0xf
	v_add_f32_dpp v164, v221, v220 quad_perm:[1,0,3,2] row_mask:0xf bank_mask:0xf
	v_add_f32_dpp v180, v229, v228 quad_perm:[1,0,3,2] row_mask:0xf bank_mask:0xf
	v_add_f32_dpp v166, v223, v222 quad_perm:[1,0,3,2] row_mask:0xf bank_mask:0xf
	v_add_f32_dpp v182, v231, v230 quad_perm:[1,0,3,2] row_mask:0xf bank_mask:0xf
	v_cndmask_b32_e64 v216, v160, v164, s[40:41]
	v_cndmask_b32_e64 v217, v164, v160, s[40:41]
	v_cndmask_b32_e64 v224, v176, v180, s[40:41]
	v_cndmask_b32_e64 v225, v180, v176, s[40:41]
	v_cndmask_b32_e64 v218, v162, v166, s[40:41]
	v_cndmask_b32_e64 v219, v166, v162, s[40:41]
	v_cndmask_b32_e64 v226, v178, v182, s[40:41]
	v_cndmask_b32_e64 v227, v182, v178, s[40:41]
	s_nop 0
	v_add_f32_dpp v160, v217, v216 quad_perm:[2,3,0,1] row_mask:0xf bank_mask:0xf
	v_add_f32_dpp v176, v225, v224 quad_perm:[2,3,0,1] row_mask:0xf bank_mask:0xf
	v_add_f32_dpp v162, v219, v218 quad_perm:[2,3,0,1] row_mask:0xf bank_mask:0xf
	v_add_f32_dpp v178, v227, v226 quad_perm:[2,3,0,1] row_mask:0xf bank_mask:0xf
	v_cndmask_b32_e64 v216, v160, v162, s[42:43]
	v_cndmask_b32_e64 v217, v162, v160, s[42:43]
	v_cndmask_b32_e64 v224, v176, v178, s[42:43]
	v_cndmask_b32_e64 v225, v178, v176, s[42:43]
	s_nop 0
	v_add_f32_dpp v160, v217, v216 row_shl:4 row_mask:0xf bank_mask:0x5
	v_add_f32_dpp v160, v217, v216 row_shr:4 row_mask:0xf bank_mask:0xa
	v_add_f32_dpp v176, v225, v224 row_shl:4 row_mask:0xf bank_mask:0x5
	v_add_f32_dpp v176, v225, v224 row_shr:4 row_mask:0xf bank_mask:0xa
	s_nop 1
	v_add_f32_dpp v160, v160, v160 row_ror:8 row_mask:0xf bank_mask:0xf
	v_add_f32_dpp v176, v176, v176 row_ror:8 row_mask:0xf bank_mask:0xf
	s_nop 0
	ds_bpermute_b32 v161, v5, v160
	ds_bpermute_b32 v177, v5, v176
	s_waitcnt lgkmcnt(0)
	v_add_f32_e32 v160, v160, v161
	v_add_f32_e32 v176, v176, v177
	v_mov_b32_e32 v161, v160
	v_mov_b32_e32 v177, v176
	s_nop 1
	v_permlane32_swap_b32_e32 v160, v161
	v_permlane32_swap_b32_e32 v176, v177
	v_add_f32_e32 v160, v160, v161
	v_add_f32_e32 v176, v176, v177
	v_add_f32_e32 v160, v160, v12
	v_add_f32_e32 v176, v176, v12
	v_and_b32_e32 v216, 0x7fffffff, v160
	v_and_b32_e32 v224, 0x7fffffff, v176
	v_mul_f32_e32 v216, 0xbfb8aa3b, v216
	v_mul_f32_e32 v224, 0xbfb8aa3b, v224
	v_exp_f32_e32 v216, v216
	v_exp_f32_e32 v224, v224
	s_nop 0
	v_add_f32_e32 v217, 1.0, v216
	v_add_f32_e32 v225, 1.0, v224
	v_log_f32_e32 v218, v217
	v_log_f32_e32 v226, v225
	v_add_f32_e32 v219, -1.0, v217
	v_add_f32_e32 v227, -1.0, v225
	v_rcp_f32_e32 v219, v219
	v_rcp_f32_e32 v227, v227
	v_mul_f32_e32 v218, 0x3f317218, v218
	v_mul_f32_e32 v226, 0x3f317218, v226
	v_mul_f32_e32 v219, v216, v219
	v_mul_f32_e32 v227, v224, v227
	v_mul_f32_e32 v218, v218, v219
	v_mul_f32_e32 v226, v226, v227
	v_cmp_eq_f32_e32 vcc, 1.0, v217
	s_nop 1
	v_cndmask_b32_e32 v218, v218, v216, vcc
	v_cmp_eq_f32_e32 vcc, 1.0, v225
	s_nop 1
	v_cndmask_b32_e32 v226, v226, v224, vcc
	v_max_f32_e32 v160, 0, v160
	v_max_f32_e32 v176, 0, v176
	v_add_f32_e32 v160, v160, v218
	v_add_f32_e32 v176, v176, v226
	v_cndmask_b32_e64 v160, v160, v176, s[44:45]
	s_mov_b64 exec, 0xffff
	global_store_dword v4, v160, s[28:29]
	s_mov_b64 exec, -1
	s_add_u32 s28, s28, 64
	s_addc_u32 s29, s29, 0
	s_waitcnt vmcnt(42)
; __device__ __forceinline__ float bflo(unsigned x) { return __uint_as_float(x << 16); }
; __device__ __forceinline__ float bfhi(unsigned x) { return __uint_as_float(x & 0xffff0000u); }
; template <bool WITH_DT, bool OUT8> __device__ __forceinline__ void norm_mod_rows(const void* xp, bool pb16, const void* xs, bool sb16, const float* w, const float* MOD, int ish, int isc, bf16* H, ...
;     ...
;     for (int row = gw; row < MT; row += NGW) {
;         const int mb = row < MP ? (row >> 12) : 8 + ((row - MP) >> 6);
;         f32x4 v[4]; float s = 0.f;
; #pragma unroll
;         for (int j = 0; j < 4; ++j) v[j] = vn[j];
;         { const int rn = row + NGW; if (rn < MT) { if (rn < MP) load_row4(xp, pb16, (size_t)rn, lane, vn); else load_row4(xs, sb16, (size_t)(rn - MP), lane, vn); } }
;         if (fslab && row >= MP) {
;             f32x4 a[4];
; #pragma unroll
;             for (int j = 0; j < 4; ++j) a[j] = (f32x4){0.f, 0.f, 0.f, 0.f};
;             for (int ks = 0; ks < fS; ++ks) { const v2u* sp = (const v2u*)(fslab + ((size_t)ks * MS + (row - MP)) * DM);
; #pragma unroll
;                 for (int j = 0; j < 4; ++j) { const v2u r = sp[lane + 64 * j]; a[j] += (f32x4){bflo(r.x), bfhi(r.x), bflo(r.y), bfhi(r.y)}; } }
; #pragma unroll
;             for (int j = 0; j < 4; ++j) { v[j] += ((const f32x4*)(fgate + (size_t)mb * 9216))[lane + 64 * j] * fsc * a[j];
;                 v2u o; o.x = pk2(v[j][0], v[j][1]); o.y = pk2(v[j][2], v[j][3]); *(v2u*)(fxout + (size_t)row * DM + 4 * (lane + 64 * j)) = o; }
;         }
; #pragma unroll
;         for (int j = 0; j < 4; ++j) s += (v[j][0] * v[j][0] + v[j][1] * v[j][1]) + (v[j][2] * v[j][2] + v[j][3] * v[j][3]);
;         const float rstd = rsqrtf(wave_sum(s) * (1.0f / DM) + EPSN);
;         const f32x4* sh = (const f32x4*)(MOD + (size_t)mb * 9216 + ish * 1024); const f32x4* sc = (const f32x4*)(MOD + (size_t)mb * 9216 + isc * 1024);
; #pragma unroll
;         for (int j = 0; j < 4; ++j) { const f32x4 a = v[j] * rstd * wv[j]; v[j] = a * (sc[lane + 64 * j] + 1.0f) + sh[lane + 64 * j];
;             if (OUT8) { *(unsigned*)((unsigned char*)H + (size_t)row * DM + 4 * (lane + 64 * j)) = pk4_fp8(v[j][0] * SC_H8, v[j][1] * SC_H8, v[j][2] * SC_H8, v[j][3] * SC_H8); }
;             else { v2u o; o.x = pk2(v[j][0], v[j][1]); o.y = pk2(v[j][2], v[j][3]); *(v2u*)(H + (size_t)row * DM + 4 * (lane + 64 * j)) = o; } }
	v_lshlrev_b32_e32 v128, 16, v96
	v_and_b32_e32 v129, 0xffff0000, v96
	v_lshlrev_b32_e32 v130, 16, v97
	v_and_b32_e32 v131, 0xffff0000, v97
	v_lshlrev_b32_e32 v132, 16, v98
	v_and_b32_e32 v133, 0xffff0000, v98
	v_lshlrev_b32_e32 v134, 16, v99
	v_and_b32_e32 v135, 0xffff0000, v99
	v_lshlrev_b32_e32 v136, 16, v100
	v_and_b32_e32 v137, 0xffff0000, v100
	v_lshlrev_b32_e32 v138, 16, v101
	v_and_b32_e32 v139, 0xffff0000, v101
	v_lshlrev_b32_e32 v140, 16, v102
	v_and_b32_e32 v141, 0xffff0000, v102
	v_lshlrev_b32_e32 v142, 16, v103
	v_and_b32_e32 v143, 0xffff0000, v103
	v_lshlrev_b32_e32 v144, 16, v104
	v_and_b32_e32 v145, 0xffff0000, v104
	v_lshlrev_b32_e32 v146, 16, v105
	v_and_b32_e32 v147, 0xffff0000, v105
	v_lshlrev_b32_e32 v148, 16, v106
	v_and_b32_e32 v149, 0xffff0000, v106
	v_lshlrev_b32_e32 v150, 16, v107
	v_and_b32_e32 v151, 0xffff0000, v107
	v_lshlrev_b32_e32 v152, 16, v108
	v_and_b32_e32 v153, 0xffff0000, v108
	v_lshlrev_b32_e32 v154, 16, v109
	v_and_b32_e32 v155, 0xffff0000, v109
	v_lshlrev_b32_e32 v156, 16, v110
	v_and_b32_e32 v157, 0xffff0000, v110
	v_lshlrev_b32_e32 v158, 16, v111
	v_and_b32_e32 v159, 0xffff0000, v111
	global_load_dwordx2 v[96:97], v2, s[18:19]
	global_load_dwordx2 v[98:99], v2, s[18:19] offset:512
	global_load_dwordx2 v[100:101], v2, s[18:19] offset:1024
	global_load_dwordx2 v[102:103], v2, s[18:19] offset:1536
	s_add_u32 s18, s18, 0x800
	s_addc_u32 s19, s19, 0
	global_load_dwordx2 v[104:105], v2, s[18:19]
	global_load_dwordx2 v[106:107], v2, s[18:19] offset:512
	global_load_dwordx2 v[108:109], v2, s[18:19] offset:1024
	global_load_dwordx2 v[110:111], v2, s[18:19] offset:1536
	s_add_u32 s18, s18, 0x800
	s_addc_u32 s19, s19, 0
	v_pk_mul_f32 v[208:209], v[128:129], v[128:129]
	v_pk_mul_f32 v[210:211], v[130:131], v[130:131]
	v_pk_mul_f32 v[212:213], v[144:145], v[144:145]
	v_pk_mul_f32 v[214:215], v[146:147], v[146:147]
	v_pk_fma_f32 v[208:209], v[132:133], v[132:133], v[208:209]
	v_pk_fma_f32 v[210:211], v[134:135], v[134:135], v[210:211]
	v_pk_fma_f32 v[212:213], v[148:149], v[148:149], v[212:213]
	v_pk_fma_f32 v[214:215], v[150:151], v[150:151], v[214:215]
	v_pk_fma_f32 v[208:209], v[136:137], v[136:137], v[208:209]
	v_pk_fma_f32 v[210:211], v[138:139], v[138:139], v[210:211]
	v_pk_fma_f32 v[212:213], v[152:153], v[152:153], v[212:213]
	v_pk_fma_f32 v[214:215], v[154:155], v[154:155], v[214:215]
	v_pk_fma_f32 v[208:209], v[140:141], v[140:141], v[208:209]
	v_pk_fma_f32 v[210:211], v[142:143], v[142:143], v[210:211]
	v_pk_fma_f32 v[212:213], v[156:157], v[156:157], v[212:213]
	v_pk_fma_f32 v[214:215], v[158:159], v[158:159], v[214:215]
	v_pk_add_f32 v[208:209], v[208:209], v[210:211]
	v_pk_add_f32 v[212:213], v[212:213], v[214:215]
	v_add_f32_e32 v208, v208, v209
	v_add_f32_e32 v212, v212, v213
	s_nop 0
	v_add_f32_dpp v208, v208, v208 quad_perm:[1,0,3,2] row_mask:0xf bank_mask:0xf
	v_add_f32_dpp v212, v212, v212 quad_perm:[1,0,3,2] row_mask:0xf bank_mask:0xf
	s_nop 0
	v_add_f32_dpp v208, v208, v208 quad_perm:[2,3,0,1] row_mask:0xf bank_mask:0xf
	v_add_f32_dpp v212, v212, v212 quad_perm:[2,3,0,1] row_mask:0xf bank_mask:0xf
	s_nop 0
	v_add_f32_dpp v208, v208, v208 row_half_mirror row_mask:0xf bank_mask:0xf
	v_add_f32_dpp v212, v212, v212 row_half_mirror row_mask:0xf bank_mask:0xf
	s_nop 0
	v_add_f32_dpp v208, v208, v208 row_mirror row_mask:0xf bank_mask:0xf
	v_add_f32_dpp v212, v212, v212 row_mirror row_mask:0xf bank_mask:0xf
	s_nop 0
	v_readlane_b32 s30, v208, 0
	v_readlane_b32 s31, v208, 16
	v_readlane_b32 s32, v208, 32
	v_readlane_b32 s33, v208, 48
	v_readlane_b32 s34, v212, 0
	v_readlane_b32 s35, v212, 16
	v_readlane_b32 s36, v212, 32
	v_readlane_b32 s37, v212, 48
	s_nop 1
	v_mov_b32_e32 v209, s30
	v_mov_b32_e32 v213, s34
	v_add_f32_e32 v209, s31, v209
	v_add_f32_e32 v213, s35, v213
	v_add_f32_e32 v209, s32, v209
	v_add_f32_e32 v213, s36, v213
	v_add_f32_e32 v209, s33, v209
	v_add_f32_e32 v213, s37, v213
	v_fmamk_f32 v209, v209, 0x3a800000, v8
	v_fmamk_f32 v213, v213, 0x3a800000, v8
	v_rsq_f32_e32 v210, v209
	v_rsq_f32_e32 v214, v213
	s_nop 0
	v_pk_mul_f32 v[128:129], v[128:129], v[210:211] op_sel_hi:[1,0]
	v_pk_mul_f32 v[130:131], v[130:131], v[210:211] op_sel_hi:[1,0]
	v_pk_mul_f32 v[132:133], v[132:133], v[210:211] op_sel_hi:[1,0]
	v_pk_mul_f32 v[134:135], v[134:135], v[210:211] op_sel_hi:[1,0]
	v_pk_mul_f32 v[136:137], v[136:137], v[210:211] op_sel_hi:[1,0]
	v_pk_mul_f32 v[138:139], v[138:139], v[210:211] op_sel_hi:[1,0]
	v_pk_mul_f32 v[140:141], v[140:141], v[210:211] op_sel_hi:[1,0]
	v_pk_mul_f32 v[142:143], v[142:143], v[210:211] op_sel_hi:[1,0]
	v_pk_mul_f32 v[144:145], v[144:145], v[214:215] op_sel_hi:[1,0]
	v_pk_mul_f32 v[146:147], v[146:147], v[214:215] op_sel_hi:[1,0]
	v_pk_mul_f32 v[148:149], v[148:149], v[214:215] op_sel_hi:[1,0]
	v_pk_mul_f32 v[150:151], v[150:151], v[214:215] op_sel_hi:[1,0]
	v_pk_mul_f32 v[152:153], v[152:153], v[214:215] op_sel_hi:[1,0]
	v_pk_mul_f32 v[154:155], v[154:155], v[214:215] op_sel_hi:[1,0]
	v_pk_mul_f32 v[156:157], v[156:157], v[214:215] op_sel_hi:[1,0]
	v_pk_mul_f32 v[158:159], v[158:159], v[214:215] op_sel_hi:[1,0]
	v_pk_fma_f32 v[128:129], v[128:129], v[16:17], v[32:33]
	v_pk_fma_f32 v[130:131], v[130:131], v[18:19], v[34:35]
	v_pk_fma_f32 v[132:133], v[132:133], v[20:21], v[36:37]
	v_pk_fma_f32 v[134:135], v[134:135], v[22:23], v[38:39]
	v_pk_fma_f32 v[136:137], v[136:137], v[24:25], v[40:41]
	v_pk_fma_f32 v[138:139], v[138:139], v[26:27], v[42:43]
	v_pk_fma_f32 v[140:141], v[140:141], v[28:29], v[44:45]
	v_pk_fma_f32 v[142:143], v[142:143], v[30:31], v[46:47]
	v_pk_fma_f32 v[144:145], v[144:145], v[16:17], v[32:33]
	v_pk_fma_f32 v[146:147], v[146:147], v[18:19], v[34:35]
; __device__ __forceinline__ unsigned pk2(float lo, float hi) { return pg8::cvt_pk_bf16(lo, hi); }
; template <bool WITH_DT, bool OUT8> __device__ __forceinline__ void norm_mod_rows(const void* xp, bool pb16, const void* xs, bool sb16, const float* w, const float* MOD, int ish, int isc, bf16* H, ...
;     ...
;         for (int j = 0; j < 4; ++j) { const f32x4 a = v[j] * rstd * wv[j]; v[j] = a * (sc[lane + 64 * j] + 1.0f) + sh[lane + 64 * j];
;             if (OUT8) { *(unsigned*)((unsigned char*)H + (size_t)row * DM + 4 * (lane + 64 * j)) = pk4_fp8(v[j][0] * SC_H8, v[j][1] * SC_H8, v[j][2] * SC_H8, v[j][3] * SC_H8); }
;             else { v2u o; o.x = pk2(v[j][0], v[j][1]); o.y = pk2(v[j][2], v[j][3]); *(v2u*)(H + (size_t)row * DM + 4 * (lane + 64 * j)) = o; } }
;         if (WITH_DT) {
;             float d[8];
; #pragma unroll
;             for (int c = 0; c < 8; ++c) { float p = 0.f;
; #pragma unroll
;                 for (int j = 0; j < 4; ++j) { const f32x4 ww = wdt[WITH_DT ? c : 0][j]; p += (v[j][0] * ww[0] + v[j][1] * ww[1]) + (v[j][2] * ww[2] + v[j][3] * ww[3]); }
;                 d[c] = p; }
	v_pk_fma_f32 v[148:149], v[148:149], v[20:21], v[36:37]
	v_pk_fma_f32 v[150:151], v[150:151], v[22:23], v[38:39]
	v_pk_fma_f32 v[152:153], v[152:153], v[24:25], v[40:41]
	v_pk_fma_f32 v[154:155], v[154:155], v[26:27], v[42:43]
	v_pk_fma_f32 v[156:157], v[156:157], v[28:29], v[44:45]
	v_pk_fma_f32 v[158:159], v[158:159], v[30:31], v[46:47]
	v_cvt_pk_bf16_f32 v216, v128, v129
	v_cvt_pk_bf16_f32 v217, v130, v131
	v_cvt_pk_bf16_f32 v218, v132, v133
	v_cvt_pk_bf16_f32 v219, v134, v135
	v_cvt_pk_bf16_f32 v220, v136, v137
	v_cvt_pk_bf16_f32 v221, v138, v139
	v_cvt_pk_bf16_f32 v222, v140, v141
	v_cvt_pk_bf16_f32 v223, v142, v143
	v_cvt_pk_bf16_f32 v224, v144, v145
	v_cvt_pk_bf16_f32 v225, v146, v147
	v_cvt_pk_bf16_f32 v226, v148, v149
	v_cvt_pk_bf16_f32 v227, v150, v151
	v_cvt_pk_bf16_f32 v228, v152, v153
	v_cvt_pk_bf16_f32 v229, v154, v155
	v_cvt_pk_bf16_f32 v230, v156, v157
	v_cvt_pk_bf16_f32 v231, v158, v159
	global_store_dwordx2 v2, v[216:217], s[20:21]
	global_store_dwordx2 v2, v[218:219], s[20:21] offset:512
	global_store_dwordx2 v2, v[220:221], s[20:21] offset:1024
	global_store_dwordx2 v2, v[222:223], s[20:21] offset:1536
	global_store_dwordx2 v2, v[224:225], s[20:21] offset:2048
	global_store_dwordx2 v2, v[226:227], s[20:21] offset:2560
	global_store_dwordx2 v2, v[228:229], s[20:21] offset:3072
	global_store_dwordx2 v2, v[230:231], s[20:21] offset:3584
	s_add_u32 s20, s20, 0x1000
	s_addc_u32 s21, s21, 0
	ds_read_b128 v[192:195], v3 offset:0
	ds_read_b128 v[196:199], v3 offset:1024
	ds_read_b128 v[200:203], v3 offset:2048
	ds_read_b128 v[204:207], v3 offset:3072
	s_waitcnt lgkmcnt(3)
	v_pk_mul_f32 v[160:161], v[128:129], v[192:193]
	v_pk_mul_f32 v[176:177], v[144:145], v[192:193]
	v_pk_fma_f32 v[160:161], v[130:131], v[194:195], v[160:161]
	v_pk_fma_f32 v[176:177], v[146:147], v[194:195], v[176:177]
	ds_read_b128 v[192:195], v3 offset:4096
	s_waitcnt lgkmcnt(3)
	v_pk_fma_f32 v[160:161], v[132:133], v[196:197], v[160:161]
	v_pk_fma_f32 v[176:177], v[148:149], v[196:197], v[176:177]
	v_pk_fma_f32 v[160:161], v[134:135], v[198:199], v[160:161]
	v_pk_fma_f32 v[176:177], v[150:151], v[198:199], v[176:177]
	ds_read_b128 v[196:199], v3 offset:5120
	s_waitcnt lgkmcnt(3)
	v_pk_fma_f32 v[160:161], v[136:137], v[200:201], v[160:161]
	v_pk_fma_f32 v[176:177], v[152:153], v[200:201], v[176:177]
	v_pk_fma_f32 v[160:161], v[138:139], v[202:203], v[160:161]
	v_pk_fma_f32 v[176:177], v[154:155], v[202:203], v[176:177]
	ds_read_b128 v[200:203], v3 offset:6144
	s_waitcnt lgkmcnt(3)
	v_pk_fma_f32 v[160:161], v[140:141], v[204:205], v[160:161]
	v_pk_fma_f32 v[176:177], v[156:157], v[204:205], v[176:177]
	v_pk_fma_f32 v[160:161], v[142:143], v[206:207], v[160:161]
	v_pk_fma_f32 v[176:177], v[158:159], v[206:207], v[176:177]
	ds_read_b128 v[204:207], v3 offset:7168
	s_waitcnt lgkmcnt(3)
	v_pk_mul_f32 v[162:163], v[128:129], v[192:193]
	v_pk_mul_f32 v[178:179], v[144:145], v[192:193]
	v_pk_fma_f32 v[162:163], v[130:131], v[194:195], v[162:163]
	v_pk_fma_f32 v[178:179], v[146:147], v[194:195], v[178:179]
	ds_read_b128 v[192:195], v3 offset:8192
	s_waitcnt lgkmcnt(3)
	v_pk_fma_f32 v[162:163], v[132:133], v[196:197], v[162:163]
	v_pk_fma_f32 v[178:179], v[148:149], v[196:197], v[178:179]
	v_pk_fma_f32 v[162:163], v[134:135], v[198:199], v[162:163]
	v_pk_fma_f32 v[178:179], v[150:151], v[198:199], v[178:179]
	ds_read_b128 v[196:199], v3 offset:9216
	s_waitcnt lgkmcnt(3)
	v_pk_fma_f32 v[162:163], v[136:137], v[200:201], v[162:163]
	v_pk_fma_f32 v[178:179], v[152:153], v[200:201], v[178:179]
	v_pk_fma_f32 v[162:163], v[138:139], v[202:203], v[162:163]
	v_pk_fma_f32 v[178:179], v[154:155], v[202:203], v[178:179]
	ds_read_b128 v[200:203], v3 offset:10240
	s_waitcnt lgkmcnt(3)
	v_pk_fma_f32 v[162:163], v[140:141], v[204:205], v[162:163]
	v_pk_fma_f32 v[178:179], v[156:157], v[204:205], v[178:179]
	v_pk_fma_f32 v[162:163], v[142:143], v[206:207], v[162:163]
	v_pk_fma_f32 v[178:179], v[158:159], v[206:207], v[178:179]
	ds_read_b128 v[204:207], v3 offset:11264
	s_waitcnt lgkmcnt(3)
	v_pk_mul_f32 v[164:165], v[128:129], v[192:193]
	v_pk_mul_f32 v[180:181], v[144:145], v[192:193]
	v_pk_fma_f32 v[164:165], v[130:131], v[194:195], v[164:165]
	v_pk_fma_f32 v[180:181], v[146:147], v[194:195], v[180:181]
	ds_read_b128 v[192:195], v3 offset:12288
	s_waitcnt lgkmcnt(3)
	v_pk_fma_f32 v[164:165], v[132:133], v[196:197], v[164:165]
	v_pk_fma_f32 v[180:181], v[148:149], v[196:197], v[180:181]
	v_pk_fma_f32 v[164:165], v[134:135], v[198:199], v[164:165]
	v_pk_fma_f32 v[180:181], v[150:151], v[198:199], v[180:181]
	ds_read_b128 v[196:199], v3 offset:13312
	s_waitcnt lgkmcnt(3)
	v_pk_fma_f32 v[164:165], v[136:137], v[200:201], v[164:165]
	v_pk_fma_f32 v[180:181], v[152:153], v[200:201], v[180:181]
	v_pk_fma_f32 v[164:165], v[138:139], v[202:203], v[164:165]
	v_pk_fma_f32 v[180:181], v[154:155], v[202:203], v[180:181]
	ds_read_b128 v[200:203], v3 offset:14336
	s_waitcnt lgkmcnt(3)
	v_pk_fma_f32 v[164:165], v[140:141], v[204:205], v[164:165]
	v_pk_fma_f32 v[180:181], v[156:157], v[204:205], v[180:181]
	v_pk_fma_f32 v[164:165], v[142:143], v[206:207], v[164:165]
	v_pk_fma_f32 v[180:181], v[158:159], v[206:207], v[180:181]
	ds_read_b128 v[204:207], v3 offset:15360
	s_waitcnt lgkmcnt(3)
	v_pk_mul_f32 v[166:167], v[128:129], v[192:193]
	v_pk_mul_f32 v[182:183], v[144:145], v[192:193]
	v_pk_fma_f32 v[166:167], v[130:131], v[194:195], v[166:167]
	v_pk_fma_f32 v[182:183], v[146:147], v[194:195], v[182:183]
	ds_read_b128 v[192:195], v3 offset:16384
	s_waitcnt lgkmcnt(3)
; template <bool WITH_DT, bool OUT8> __device__ __forceinline__ void norm_mod_rows(const void* xp, bool pb16, const void* xs, bool sb16, const float* w, const float* MOD, int ish, int isc, bf16* H, ...
;     ...
;             for (int c = 0; c < 8; ++c) { float p = 0.f;
; #pragma unroll
;                 for (int j = 0; j < 4; ++j) { const f32x4 ww = wdt[WITH_DT ? c : 0][j]; p += (v[j][0] * ww[0] + v[j][1] * ww[1]) + (v[j][2] * ww[2] + v[j][3] * ww[3]); }
;                 d[c] = p; }
	v_pk_fma_f32 v[166:167], v[132:133], v[196:197], v[166:167]
	v_pk_fma_f32 v[182:183], v[148:149], v[196:197], v[182:183]
	v_pk_fma_f32 v[166:167], v[134:135], v[198:199], v[166:167]
	v_pk_fma_f32 v[182:183], v[150:151], v[198:199], v[182:183]
	ds_read_b128 v[196:199], v3 offset:17408
	s_waitcnt lgkmcnt(3)
	v_pk_fma_f32 v[166:167], v[136:137], v[200:201], v[166:167]
	v_pk_fma_f32 v[182:183], v[152:153], v[200:201], v[182:183]
	v_pk_fma_f32 v[166:167], v[138:139], v[202:203], v[166:167]
	v_pk_fma_f32 v[182:183], v[154:155], v[202:203], v[182:183]
	ds_read_b128 v[200:203], v3 offset:18432
	s_waitcnt lgkmcnt(3)
	v_pk_fma_f32 v[166:167], v[140:141], v[204:205], v[166:167]
	v_pk_fma_f32 v[182:183], v[156:157], v[204:205], v[182:183]
	v_pk_fma_f32 v[166:167], v[142:143], v[206:207], v[166:167]
	v_pk_fma_f32 v[182:183], v[158:159], v[206:207], v[182:183]
	ds_read_b128 v[204:207], v3 offset:19456
	s_waitcnt lgkmcnt(3)
	v_pk_mul_f32 v[168:169], v[128:129], v[192:193]
	v_pk_mul_f32 v[184:185], v[144:145], v[192:193]
	v_pk_fma_f32 v[168:169], v[130:131], v[194:195], v[168:169]
	v_pk_fma_f32 v[184:185], v[146:147], v[194:195], v[184:185]
	ds_read_b128 v[192:195], v3 offset:20480
	s_waitcnt lgkmcnt(3)
	v_pk_fma_f32 v[168:169], v[132:133], v[196:197], v[168:169]
	v_pk_fma_f32 v[184:185], v[148:149], v[196:197], v[184:185]
	v_pk_fma_f32 v[168:169], v[134:135], v[198:199], v[168:169]
	v_pk_fma_f32 v[184:185], v[150:151], v[198:199], v[184:185]
	ds_read_b128 v[196:199], v3 offset:21504
	s_waitcnt lgkmcnt(3)
	v_pk_fma_f32 v[168:169], v[136:137], v[200:201], v[168:169]
	v_pk_fma_f32 v[184:185], v[152:153], v[200:201], v[184:185]
	v_pk_fma_f32 v[168:169], v[138:139], v[202:203], v[168:169]
	v_pk_fma_f32 v[184:185], v[154:155], v[202:203], v[184:185]
	ds_read_b128 v[200:203], v3 offset:22528
	s_waitcnt lgkmcnt(3)
	v_pk_fma_f32 v[168:169], v[140:141], v[204:205], v[168:169]
	v_pk_fma_f32 v[184:185], v[156:157], v[204:205], v[184:185]
	v_pk_fma_f32 v[168:169], v[142:143], v[206:207], v[168:169]
	v_pk_fma_f32 v[184:185], v[158:159], v[206:207], v[184:185]
	ds_read_b128 v[204:207], v3 offset:23552
	s_waitcnt lgkmcnt(3)
	v_pk_mul_f32 v[170:171], v[128:129], v[192:193]
	v_pk_mul_f32 v[186:187], v[144:145], v[192:193]
	v_pk_fma_f32 v[170:171], v[130:131], v[194:195], v[170:171]
	v_pk_fma_f32 v[186:187], v[146:147], v[194:195], v[186:187]
	ds_read_b128 v[192:195], v3 offset:24576
	s_waitcnt lgkmcnt(3)
	v_pk_fma_f32 v[170:171], v[132:133], v[196:197], v[170:171]
	v_pk_fma_f32 v[186:187], v[148:149], v[196:197], v[186:187]
	v_pk_fma_f32 v[170:171], v[134:135], v[198:199], v[170:171]
	v_pk_fma_f32 v[186:187], v[150:151], v[198:199], v[186:187]
	ds_read_b128 v[196:199], v3 offset:25600
	s_waitcnt lgkmcnt(3)
	v_pk_fma_f32 v[170:171], v[136:137], v[200:201], v[170:171]
	v_pk_fma_f32 v[186:187], v[152:153], v[200:201], v[186:187]
	v_pk_fma_f32 v[170:171], v[138:139], v[202:203], v[170:171]
	v_pk_fma_f32 v[186:187], v[154:155], v[202:203], v[186:187]
	ds_read_b128 v[200:203], v3 offset:26624
	s_waitcnt lgkmcnt(3)
	v_pk_fma_f32 v[170:171], v[140:141], v[204:205], v[170:171]
	v_pk_fma_f32 v[186:187], v[156:157], v[204:205], v[186:187]
	v_pk_fma_f32 v[170:171], v[142:143], v[206:207], v[170:171]
	v_pk_fma_f32 v[186:187], v[158:159], v[206:207], v[186:187]
	ds_read_b128 v[204:207], v3 offset:27648
	s_waitcnt lgkmcnt(3)
	v_pk_mul_f32 v[172:173], v[128:129], v[192:193]
	v_pk_mul_f32 v[188:189], v[144:145], v[192:193]
	v_pk_fma_f32 v[172:173], v[130:131], v[194:195], v[172:173]
	v_pk_fma_f32 v[188:189], v[146:147], v[194:195], v[188:189]
	ds_read_b128 v[192:195], v3 offset:28672
	s_waitcnt lgkmcnt(3)
	v_pk_fma_f32 v[172:173], v[132:133], v[196:197], v[172:173]
	v_pk_fma_f32 v[188:189], v[148:149], v[196:197], v[188:189]
	v_pk_fma_f32 v[172:173], v[134:135], v[198:199], v[172:173]
	v_pk_fma_f32 v[188:189], v[150:151], v[198:199], v[188:189]
	ds_read_b128 v[196:199], v3 offset:29696
	s_waitcnt lgkmcnt(3)
	v_pk_fma_f32 v[172:173], v[136:137], v[200:201], v[172:173]
	v_pk_fma_f32 v[188:189], v[152:153], v[200:201], v[188:189]
	v_pk_fma_f32 v[172:173], v[138:139], v[202:203], v[172:173]
	v_pk_fma_f32 v[188:189], v[154:155], v[202:203], v[188:189]
	ds_read_b128 v[200:203], v3 offset:30720
	s_waitcnt lgkmcnt(3)
	v_pk_fma_f32 v[172:173], v[140:141], v[204:205], v[172:173]
	v_pk_fma_f32 v[188:189], v[156:157], v[204:205], v[188:189]
	v_pk_fma_f32 v[172:173], v[142:143], v[206:207], v[172:173]
	v_pk_fma_f32 v[188:189], v[158:159], v[206:207], v[188:189]
	ds_read_b128 v[204:207], v3 offset:31744
	s_waitcnt lgkmcnt(3)
	v_pk_mul_f32 v[174:175], v[128:129], v[192:193]
	v_pk_mul_f32 v[190:191], v[144:145], v[192:193]
	v_pk_fma_f32 v[174:175], v[130:131], v[194:195], v[174:175]
	v_pk_fma_f32 v[190:191], v[146:147], v[194:195], v[190:191]
	s_waitcnt lgkmcnt(2)
	v_pk_fma_f32 v[174:175], v[132:133], v[196:197], v[174:175]
	v_pk_fma_f32 v[190:191], v[148:149], v[196:197], v[190:191]
	v_pk_fma_f32 v[174:175], v[134:135], v[198:199], v[174:175]
	v_pk_fma_f32 v[190:191], v[150:151], v[198:199], v[190:191]
	s_waitcnt lgkmcnt(1)
	v_pk_fma_f32 v[174:175], v[136:137], v[200:201], v[174:175]
	v_pk_fma_f32 v[190:191], v[152:153], v[200:201], v[190:191]
	v_pk_fma_f32 v[174:175], v[138:139], v[202:203], v[174:175]
	v_pk_fma_f32 v[190:191], v[154:155], v[202:203], v[190:191]
	s_waitcnt lgkmcnt(0)
; template <bool WITH_DT, bool OUT8> __device__ __forceinline__ void norm_mod_rows(const void* xp, bool pb16, const void* xs, bool sb16, const float* w, const float* MOD, int ish, int isc, bf16* H, ...
;     ...
;                 d[c] = p; }
;             float e4[4], e2[2], e1;
;             { const bool up = (lane & 32) != 0;
; #pragma unroll
;               for (int c = 0; c < 4; ++c) { const float keep = up ? d[4 + c] : d[c], give = up ? d[c] : d[4 + c]; e4[c] = keep + __shfl_xor(give, 32); } }
;             { const bool up = (lane & 16) != 0;
; #pragma unroll
;               for (int c = 0; c < 2; ++c) { const float keep = up ? e4[2 + c] : e4[c], give = up ? e4[c] : e4[2 + c]; e2[c] = keep + __shfl_xor(give, 16); } }
;             { const bool up = (lane & 8) != 0; const float keep = up ? e2[1] : e2[0], give = up ? e2[0] : e2[1]; e1 = keep + __shfl_xor(give, 8); }
;             e1 += __shfl_xor(e1, 4); e1 += __shfl_xor(e1, 2); e1 += __shfl_xor(e1, 1);
;             const int col = ((lane >> 5) & 1) * 4 + ((lane >> 4) & 1) * 2 + ((lane >> 3) & 1);
;             if ((lane & 7) == 0) { const float p = e1 + dt_bias[col]; DT[(size_t)row * 8 + col] = fmaxf(p, 0.f) + log1pf(__expf(-fabsf(p))); }
	v_pk_fma_f32 v[174:175], v[140:141], v[204:205], v[174:175]
	v_pk_fma_f32 v[190:191], v[156:157], v[204:205], v[190:191]
	v_pk_fma_f32 v[174:175], v[142:143], v[206:207], v[174:175]
	v_pk_fma_f32 v[190:191], v[158:159], v[206:207], v[190:191]
	v_add_f32_e32 v160, v160, v161
	v_add_f32_e32 v176, v176, v177
	v_add_f32_e32 v162, v162, v163
	v_add_f32_e32 v178, v178, v179
	v_add_f32_e32 v164, v164, v165
	v_add_f32_e32 v180, v180, v181
	v_add_f32_e32 v166, v166, v167
	v_add_f32_e32 v182, v182, v183
	v_add_f32_e32 v168, v168, v169
	v_add_f32_e32 v184, v184, v185
	v_add_f32_e32 v170, v170, v171
	v_add_f32_e32 v186, v186, v187
	v_add_f32_e32 v172, v172, v173
	v_add_f32_e32 v188, v188, v189
	v_add_f32_e32 v174, v174, v175
	v_add_f32_e32 v190, v190, v191
	v_cndmask_b32_e64 v216, v160, v168, s[38:39]
	v_cndmask_b32_e64 v217, v168, v160, s[38:39]
	v_cndmask_b32_e64 v224, v176, v184, s[38:39]
	v_cndmask_b32_e64 v225, v184, v176, s[38:39]
	v_cndmask_b32_e64 v218, v162, v170, s[38:39]
	v_cndmask_b32_e64 v219, v170, v162, s[38:39]
	v_cndmask_b32_e64 v226, v178, v186, s[38:39]
	v_cndmask_b32_e64 v227, v186, v178, s[38:39]
	v_cndmask_b32_e64 v220, v164, v172, s[38:39]
	v_cndmask_b32_e64 v221, v172, v164, s[38:39]
	v_cndmask_b32_e64 v228, v180, v188, s[38:39]
	v_cndmask_b32_e64 v229, v188, v180, s[38:39]
	v_cndmask_b32_e64 v222, v166, v174, s[38:39]
	v_cndmask_b32_e64 v223, v174, v166, s[38:39]
	v_cndmask_b32_e64 v230, v182, v190, s[38:39]
	v_cndmask_b32_e64 v231, v190, v182, s[38:39]
	s_nop 0
	v_add_f32_dpp v160, v217, v216 quad_perm:[1,0,3,2] row_mask:0xf bank_mask:0xf
	v_add_f32_dpp v176, v225, v224 quad_perm:[1,0,3,2] row_mask:0xf bank_mask:0xf
	v_add_f32_dpp v162, v219, v218 quad_perm:[1,0,3,2] row_mask:0xf bank_mask:0xf
	v_add_f32_dpp v178, v227, v226 quad_perm:[1,0,3,2] row_mask:0xf bank_mask:0xf
	v_add_f32_dpp v164, v221, v220 quad_perm:[1,0,3,2] row_mask:0xf bank_mask:0xf
	v_add_f32_dpp v180, v229, v228 quad_perm:[1,0,3,2] row_mask:0xf bank_mask:0xf
	v_add_f32_dpp v166, v223, v222 quad_perm:[1,0,3,2] row_mask:0xf bank_mask:0xf
	v_add_f32_dpp v182, v231, v230 quad_perm:[1,0,3,2] row_mask:0xf bank_mask:0xf
	v_cndmask_b32_e64 v216, v160, v164, s[40:41]
	v_cndmask_b32_e64 v217, v164, v160, s[40:41]
	v_cndmask_b32_e64 v224, v176, v180, s[40:41]
	v_cndmask_b32_e64 v225, v180, v176, s[40:41]
	v_cndmask_b32_e64 v218, v162, v166, s[40:41]
	v_cndmask_b32_e64 v219, v166, v162, s[40:41]
	v_cndmask_b32_e64 v226, v178, v182, s[40:41]
	v_cndmask_b32_e64 v227, v182, v178, s[40:41]
	s_nop 0
	v_add_f32_dpp v160, v217, v216 quad_perm:[2,3,0,1] row_mask:0xf bank_mask:0xf
	v_add_f32_dpp v176, v225, v224 quad_perm:[2,3,0,1] row_mask:0xf bank_mask:0xf
	v_add_f32_dpp v162, v219, v218 quad_perm:[2,3,0,1] row_mask:0xf bank_mask:0xf
	v_add_f32_dpp v178, v227, v226 quad_perm:[2,3,0,1] row_mask:0xf bank_mask:0xf
	v_cndmask_b32_e64 v216, v160, v162, s[42:43]
	v_cndmask_b32_e64 v217, v162, v160, s[42:43]
	v_cndmask_b32_e64 v224, v176, v178, s[42:43]
	v_cndmask_b32_e64 v225, v178, v176, s[42:43]
	s_nop 0
	v_add_f32_dpp v160, v217, v216 row_shl:4 row_mask:0xf bank_mask:0x5
	v_add_f32_dpp v160, v217, v216 row_shr:4 row_mask:0xf bank_mask:0xa
	v_add_f32_dpp v176, v225, v224 row_shl:4 row_mask:0xf bank_mask:0x5
	v_add_f32_dpp v176, v225, v224 row_shr:4 row_mask:0xf bank_mask:0xa
	s_nop 1
	v_add_f32_dpp v160, v160, v160 row_ror:8 row_mask:0xf bank_mask:0xf
	v_add_f32_dpp v176, v176, v176 row_ror:8 row_mask:0xf bank_mask:0xf
	s_nop 0
	ds_bpermute_b32 v161, v5, v160
	ds_bpermute_b32 v177, v5, v176
	s_waitcnt lgkmcnt(0)
	v_add_f32_e32 v160, v160, v161
	v_add_f32_e32 v176, v176, v177
	v_mov_b32_e32 v161, v160
	v_mov_b32_e32 v177, v176
	s_nop 1
	v_permlane32_swap_b32_e32 v160, v161
	v_permlane32_swap_b32_e32 v176, v177
	v_add_f32_e32 v160, v160, v161
	v_add_f32_e32 v176, v176, v177
	v_add_f32_e32 v160, v160, v12
	v_add_f32_e32 v176, v176, v12
	v_and_b32_e32 v216, 0x7fffffff, v160
	v_and_b32_e32 v224, 0x7fffffff, v176
	v_mul_f32_e32 v216, 0xbfb8aa3b, v216
	v_mul_f32_e32 v224, 0xbfb8aa3b, v224
	v_exp_f32_e32 v216, v216
	v_exp_f32_e32 v224, v224
	s_nop 0
	v_add_f32_e32 v217, 1.0, v216
	v_add_f32_e32 v225, 1.0, v224
	v_log_f32_e32 v218, v217
	v_log_f32_e32 v226, v225
	v_add_f32_e32 v219, -1.0, v217
	v_add_f32_e32 v227, -1.0, v225
	v_rcp_f32_e32 v219, v219
	v_rcp_f32_e32 v227, v227
	v_mul_f32_e32 v218, 0x3f317218, v218
	v_mul_f32_e32 v226, 0x3f317218, v226
	v_mul_f32_e32 v219, v216, v219
	v_mul_f32_e32 v227, v224, v227
	v_mul_f32_e32 v218, v218, v219
	v_mul_f32_e32 v226, v226, v227
	v_cmp_eq_f32_e32 vcc, 1.0, v217
	s_nop 1
	v_cndmask_b32_e32 v218, v218, v216, vcc
	v_cmp_eq_f32_e32 vcc, 1.0, v225
	s_nop 1
	v_cndmask_b32_e32 v226, v226, v224, vcc
	v_max_f32_e32 v160, 0, v160
	v_max_f32_e32 v176, 0, v176
	v_add_f32_e32 v160, v160, v218
	v_add_f32_e32 v176, v176, v226
	v_cndmask_b32_e64 v160, v160, v176, s[44:45]
	s_mov_b64 exec, 0xffff
	global_store_dword v4, v160, s[28:29]
	s_mov_b64 exec, -1
	s_add_u32 s28, s28, 64
	s_addc_u32 s29, s29, 0
	s_waitcnt vmcnt(51)
; __device__ __forceinline__ float bflo(unsigned x) { return __uint_as_float(x << 16); }
; __device__ __forceinline__ float bfhi(unsigned x) { return __uint_as_float(x & 0xffff0000u); }
; __device__ __forceinline__ unsigned pk2(float lo, float hi) { return pg8::cvt_pk_bf16(lo, hi); }
; template <bool WITH_DT, bool OUT8> __device__ __forceinline__ void norm_mod_rows(const void* xp, bool pb16, const void* xs, bool sb16, const float* w, const float* MOD, int ish, int isc, bf16* H, ...
;     ...
;         f32x4 v[4]; float s = 0.f;
; #pragma unroll
;         for (int j = 0; j < 4; ++j) v[j] = vn[j];
;         { const int rn = row + NGW; if (rn < MT) { if (rn < MP) load_row4(xp, pb16, (size_t)rn, lane, vn); else load_row4(xs, sb16, (size_t)(rn - MP), lane, vn); } }
;         if (fslab && row >= MP) {
;             f32x4 a[4];
; #pragma unroll
;             for (int j = 0; j < 4; ++j) a[j] = (f32x4){0.f, 0.f, 0.f, 0.f};
;             for (int ks = 0; ks < fS; ++ks) { const v2u* sp = (const v2u*)(fslab + ((size_t)ks * MS + (row - MP)) * DM);
; #pragma unroll
;                 for (int j = 0; j < 4; ++j) { const v2u r = sp[lane + 64 * j]; a[j] += (f32x4){bflo(r.x), bfhi(r.x), bflo(r.y), bfhi(r.y)}; } }
; #pragma unroll
;             for (int j = 0; j < 4; ++j) { v[j] += ((const f32x4*)(fgate + (size_t)mb * 9216))[lane + 64 * j] * fsc * a[j];
;                 v2u o; o.x = pk2(v[j][0], v[j][1]); o.y = pk2(v[j][2], v[j][3]); *(v2u*)(fxout + (size_t)row * DM + 4 * (lane + 64 * j)) = o; }
;         }
; #pragma unroll
;         for (int j = 0; j < 4; ++j) s += (v[j][0] * v[j][0] + v[j][1] * v[j][1]) + (v[j][2] * v[j][2] + v[j][3] * v[j][3]);
;         const float rstd = rsqrtf(wave_sum(s) * (1.0f / DM) + EPSN);
;         const f32x4* sh = (const f32x4*)(MOD + (size_t)mb * 9216 + ish * 1024); const f32x4* sc = (const f32x4*)(MOD + (size_t)mb * 9216 + isc * 1024);
; #pragma unroll
;         for (int j = 0; j < 4; ++j) { const f32x4 a = v[j] * rstd * wv[j]; v[j] = a * (sc[lane + 64 * j] + 1.0f) + sh[lane + 64 * j];
;             if (OUT8) { *(unsigned*)((unsigned char*)H + (size_t)row * DM + 4 * (lane + 64 * j)) = pk4_fp8(v[j][0] * SC_H8, v[j][1] * SC_H8, v[j][2] * SC_H8, v[j][3] * SC_H8); }
;             else { v2u o; o.x = pk2(v[j][0], v[j][1]); o.y = pk2(v[j][2], v[j][3]); *(v2u*)(H + (size_t)row * DM + 4 * (lane + 64 * j)) = o; } }
	v_lshlrev_b32_e32 v128, 16, v112
	v_and_b32_e32 v129, 0xffff0000, v112
	v_lshlrev_b32_e32 v130, 16, v113
	v_and_b32_e32 v131, 0xffff0000, v113
	v_lshlrev_b32_e32 v132, 16, v114
	v_and_b32_e32 v133, 0xffff0000, v114
	v_lshlrev_b32_e32 v134, 16, v115
	v_and_b32_e32 v135, 0xffff0000, v115
	v_lshlrev_b32_e32 v136, 16, v116
	v_and_b32_e32 v137, 0xffff0000, v116
	v_lshlrev_b32_e32 v138, 16, v117
	v_and_b32_e32 v139, 0xffff0000, v117
	v_lshlrev_b32_e32 v140, 16, v118
	v_and_b32_e32 v141, 0xffff0000, v118
	v_lshlrev_b32_e32 v142, 16, v119
	v_and_b32_e32 v143, 0xffff0000, v119
	v_lshlrev_b32_e32 v144, 16, v120
	v_and_b32_e32 v145, 0xffff0000, v120
	v_lshlrev_b32_e32 v146, 16, v121
	v_and_b32_e32 v147, 0xffff0000, v121
	v_lshlrev_b32_e32 v148, 16, v122
	v_and_b32_e32 v149, 0xffff0000, v122
	v_lshlrev_b32_e32 v150, 16, v123
	v_and_b32_e32 v151, 0xffff0000, v123
	v_lshlrev_b32_e32 v152, 16, v124
	v_and_b32_e32 v153, 0xffff0000, v124
	v_lshlrev_b32_e32 v154, 16, v125
	v_and_b32_e32 v155, 0xffff0000, v125
	v_lshlrev_b32_e32 v156, 16, v126
	v_and_b32_e32 v157, 0xffff0000, v126
	v_lshlrev_b32_e32 v158, 16, v127
	v_and_b32_e32 v159, 0xffff0000, v127
	global_load_dwordx2 v[112:113], v2, s[18:19]
	global_load_dwordx2 v[114:115], v2, s[18:19] offset:512
	global_load_dwordx2 v[116:117], v2, s[18:19] offset:1024
	global_load_dwordx2 v[118:119], v2, s[18:19] offset:1536
	s_add_u32 s18, s18, 0x800
	s_addc_u32 s19, s19, 0
	global_load_dwordx2 v[120:121], v2, s[18:19]
	global_load_dwordx2 v[122:123], v2, s[18:19] offset:512
	global_load_dwordx2 v[124:125], v2, s[18:19] offset:1024
	global_load_dwordx2 v[126:127], v2, s[18:19] offset:1536
	s_add_u32 s18, s18, 0x800
	s_addc_u32 s19, s19, 0
	v_pk_mul_f32 v[208:209], v[128:129], v[128:129]
	v_pk_mul_f32 v[210:211], v[130:131], v[130:131]
	v_pk_mul_f32 v[212:213], v[144:145], v[144:145]
	v_pk_mul_f32 v[214:215], v[146:147], v[146:147]
	v_pk_fma_f32 v[208:209], v[132:133], v[132:133], v[208:209]
	v_pk_fma_f32 v[210:211], v[134:135], v[134:135], v[210:211]
	v_pk_fma_f32 v[212:213], v[148:149], v[148:149], v[212:213]
	v_pk_fma_f32 v[214:215], v[150:151], v[150:151], v[214:215]
	v_pk_fma_f32 v[208:209], v[136:137], v[136:137], v[208:209]
	v_pk_fma_f32 v[210:211], v[138:139], v[138:139], v[210:211]
	v_pk_fma_f32 v[212:213], v[152:153], v[152:153], v[212:213]
	v_pk_fma_f32 v[214:215], v[154:155], v[154:155], v[214:215]
	v_pk_fma_f32 v[208:209], v[140:141], v[140:141], v[208:209]
	v_pk_fma_f32 v[210:211], v[142:143], v[142:143], v[210:211]
	v_pk_fma_f32 v[212:213], v[156:157], v[156:157], v[212:213]
	v_pk_fma_f32 v[214:215], v[158:159], v[158:159], v[214:215]
	v_pk_add_f32 v[208:209], v[208:209], v[210:211]
	v_pk_add_f32 v[212:213], v[212:213], v[214:215]
	v_add_f32_e32 v208, v208, v209
	v_add_f32_e32 v212, v212, v213
	s_nop 0
	v_add_f32_dpp v208, v208, v208 quad_perm:[1,0,3,2] row_mask:0xf bank_mask:0xf
	v_add_f32_dpp v212, v212, v212 quad_perm:[1,0,3,2] row_mask:0xf bank_mask:0xf
	s_nop 0
	v_add_f32_dpp v208, v208, v208 quad_perm:[2,3,0,1] row_mask:0xf bank_mask:0xf
	v_add_f32_dpp v212, v212, v212 quad_perm:[2,3,0,1] row_mask:0xf bank_mask:0xf
	s_nop 0
	v_add_f32_dpp v208, v208, v208 row_half_mirror row_mask:0xf bank_mask:0xf
	v_add_f32_dpp v212, v212, v212 row_half_mirror row_mask:0xf bank_mask:0xf
	s_nop 0
	v_add_f32_dpp v208, v208, v208 row_mirror row_mask:0xf bank_mask:0xf
	v_add_f32_dpp v212, v212, v212 row_mirror row_mask:0xf bank_mask:0xf
	s_nop 0
	v_readlane_b32 s30, v208, 0
	v_readlane_b32 s31, v208, 16
	v_readlane_b32 s32, v208, 32
	v_readlane_b32 s33, v208, 48
	v_readlane_b32 s34, v212, 0
	v_readlane_b32 s35, v212, 16
	v_readlane_b32 s36, v212, 32
	v_readlane_b32 s37, v212, 48
	s_nop 1
	v_mov_b32_e32 v209, s30
	v_mov_b32_e32 v213, s34
	v_add_f32_e32 v209, s31, v209
	v_add_f32_e32 v213, s35, v213
	v_add_f32_e32 v209, s32, v209
	v_add_f32_e32 v213, s36, v213
	v_add_f32_e32 v209, s33, v209
	v_add_f32_e32 v213, s37, v213
	v_fmamk_f32 v209, v209, 0x3a800000, v8
	v_fmamk_f32 v213, v213, 0x3a800000, v8
	v_rsq_f32_e32 v210, v209
	v_rsq_f32_e32 v214, v213
	s_nop 0
	v_pk_mul_f32 v[128:129], v[128:129], v[210:211] op_sel_hi:[1,0]
	v_pk_mul_f32 v[130:131], v[130:131], v[210:211] op_sel_hi:[1,0]
	v_pk_mul_f32 v[132:133], v[132:133], v[210:211] op_sel_hi:[1,0]
	v_pk_mul_f32 v[134:135], v[134:135], v[210:211] op_sel_hi:[1,0]
	v_pk_mul_f32 v[136:137], v[136:137], v[210:211] op_sel_hi:[1,0]
	v_pk_mul_f32 v[138:139], v[138:139], v[210:211] op_sel_hi:[1,0]
	v_pk_mul_f32 v[140:141], v[140:141], v[210:211] op_sel_hi:[1,0]
	v_pk_mul_f32 v[142:143], v[142:143], v[210:211] op_sel_hi:[1,0]
	v_pk_mul_f32 v[144:145], v[144:145], v[214:215] op_sel_hi:[1,0]
	v_pk_mul_f32 v[146:147], v[146:147], v[214:215] op_sel_hi:[1,0]
	v_pk_mul_f32 v[148:149], v[148:149], v[214:215] op_sel_hi:[1,0]
	v_pk_mul_f32 v[150:151], v[150:151], v[214:215] op_sel_hi:[1,0]
	v_pk_mul_f32 v[152:153], v[152:153], v[214:215] op_sel_hi:[1,0]
	v_pk_mul_f32 v[154:155], v[154:155], v[214:215] op_sel_hi:[1,0]
	v_pk_mul_f32 v[156:157], v[156:157], v[214:215] op_sel_hi:[1,0]
	v_pk_mul_f32 v[158:159], v[158:159], v[214:215] op_sel_hi:[1,0]
	v_pk_fma_f32 v[128:129], v[128:129], v[16:17], v[32:33]
	v_pk_fma_f32 v[130:131], v[130:131], v[18:19], v[34:35]
	v_pk_fma_f32 v[132:133], v[132:133], v[20:21], v[36:37]
	v_pk_fma_f32 v[134:135], v[134:135], v[22:23], v[38:39]
	v_pk_fma_f32 v[136:137], v[136:137], v[24:25], v[40:41]
	v_pk_fma_f32 v[138:139], v[138:139], v[26:27], v[42:43]
	v_pk_fma_f32 v[140:141], v[140:141], v[28:29], v[44:45]
	v_pk_fma_f32 v[142:143], v[142:143], v[30:31], v[46:47]
	v_pk_fma_f32 v[144:145], v[144:145], v[16:17], v[32:33]
	v_pk_fma_f32 v[146:147], v[146:147], v[18:19], v[34:35]
; __device__ __forceinline__ unsigned pk2(float lo, float hi) { return pg8::cvt_pk_bf16(lo, hi); }
; template <bool WITH_DT, bool OUT8> __device__ __forceinline__ void norm_mod_rows(const void* xp, bool pb16, const void* xs, bool sb16, const float* w, const float* MOD, int ish, int isc, bf16* H, ...
;     ...
;         for (int j = 0; j < 4; ++j) { const f32x4 a = v[j] * rstd * wv[j]; v[j] = a * (sc[lane + 64 * j] + 1.0f) + sh[lane + 64 * j];
;             if (OUT8) { *(unsigned*)((unsigned char*)H + (size_t)row * DM + 4 * (lane + 64 * j)) = pk4_fp8(v[j][0] * SC_H8, v[j][1] * SC_H8, v[j][2] * SC_H8, v[j][3] * SC_H8); }
;             else { v2u o; o.x = pk2(v[j][0], v[j][1]); o.y = pk2(v[j][2], v[j][3]); *(v2u*)(H + (size_t)row * DM + 4 * (lane + 64 * j)) = o; } }
;         if (WITH_DT) {
;             float d[8];
; #pragma unroll
;             for (int c = 0; c < 8; ++c) { float p = 0.f;
; #pragma unroll
;                 for (int j = 0; j < 4; ++j) { const f32x4 ww = wdt[WITH_DT ? c : 0][j]; p += (v[j][0] * ww[0] + v[j][1] * ww[1]) + (v[j][2] * ww[2] + v[j][3] * ww[3]); }
;                 d[c] = p; }
	v_pk_fma_f32 v[148:149], v[148:149], v[20:21], v[36:37]
	v_pk_fma_f32 v[150:151], v[150:151], v[22:23], v[38:39]
	v_pk_fma_f32 v[152:153], v[152:153], v[24:25], v[40:41]
	v_pk_fma_f32 v[154:155], v[154:155], v[26:27], v[42:43]
	v_pk_fma_f32 v[156:157], v[156:157], v[28:29], v[44:45]
	v_pk_fma_f32 v[158:159], v[158:159], v[30:31], v[46:47]
	v_cvt_pk_bf16_f32 v216, v128, v129
	v_cvt_pk_bf16_f32 v217, v130, v131
	v_cvt_pk_bf16_f32 v218, v132, v133
	v_cvt_pk_bf16_f32 v219, v134, v135
	v_cvt_pk_bf16_f32 v220, v136, v137
	v_cvt_pk_bf16_f32 v221, v138, v139
	v_cvt_pk_bf16_f32 v222, v140, v141
	v_cvt_pk_bf16_f32 v223, v142, v143
	v_cvt_pk_bf16_f32 v224, v144, v145
	v_cvt_pk_bf16_f32 v225, v146, v147
	v_cvt_pk_bf16_f32 v226, v148, v149
	v_cvt_pk_bf16_f32 v227, v150, v151
	v_cvt_pk_bf16_f32 v228, v152, v153
	v_cvt_pk_bf16_f32 v229, v154, v155
	v_cvt_pk_bf16_f32 v230, v156, v157
	v_cvt_pk_bf16_f32 v231, v158, v159
	global_store_dwordx2 v2, v[216:217], s[20:21]
	global_store_dwordx2 v2, v[218:219], s[20:21] offset:512
	global_store_dwordx2 v2, v[220:221], s[20:21] offset:1024
	global_store_dwordx2 v2, v[222:223], s[20:21] offset:1536
	global_store_dwordx2 v2, v[224:225], s[20:21] offset:2048
	global_store_dwordx2 v2, v[226:227], s[20:21] offset:2560
	global_store_dwordx2 v2, v[228:229], s[20:21] offset:3072
	global_store_dwordx2 v2, v[230:231], s[20:21] offset:3584
	s_add_u32 s20, s20, 0x1000
	s_addc_u32 s21, s21, 0
	ds_read_b128 v[192:195], v3 offset:0
	ds_read_b128 v[196:199], v3 offset:1024
	ds_read_b128 v[200:203], v3 offset:2048
	ds_read_b128 v[204:207], v3 offset:3072
	s_waitcnt lgkmcnt(3)
	v_pk_mul_f32 v[160:161], v[128:129], v[192:193]
	v_pk_mul_f32 v[176:177], v[144:145], v[192:193]
	v_pk_fma_f32 v[160:161], v[130:131], v[194:195], v[160:161]
	v_pk_fma_f32 v[176:177], v[146:147], v[194:195], v[176:177]
	ds_read_b128 v[192:195], v3 offset:4096
	s_waitcnt lgkmcnt(3)
	v_pk_fma_f32 v[160:161], v[132:133], v[196:197], v[160:161]
	v_pk_fma_f32 v[176:177], v[148:149], v[196:197], v[176:177]
	v_pk_fma_f32 v[160:161], v[134:135], v[198:199], v[160:161]
	v_pk_fma_f32 v[176:177], v[150:151], v[198:199], v[176:177]
	ds_read_b128 v[196:199], v3 offset:5120
	s_waitcnt lgkmcnt(3)
	v_pk_fma_f32 v[160:161], v[136:137], v[200:201], v[160:161]
	v_pk_fma_f32 v[176:177], v[152:153], v[200:201], v[176:177]
	v_pk_fma_f32 v[160:161], v[138:139], v[202:203], v[160:161]
	v_pk_fma_f32 v[176:177], v[154:155], v[202:203], v[176:177]
	ds_read_b128 v[200:203], v3 offset:6144
	s_waitcnt lgkmcnt(3)
	v_pk_fma_f32 v[160:161], v[140:141], v[204:205], v[160:161]
	v_pk_fma_f32 v[176:177], v[156:157], v[204:205], v[176:177]
	v_pk_fma_f32 v[160:161], v[142:143], v[206:207], v[160:161]
	v_pk_fma_f32 v[176:177], v[158:159], v[206:207], v[176:177]
	ds_read_b128 v[204:207], v3 offset:7168
	s_waitcnt lgkmcnt(3)
	v_pk_mul_f32 v[162:163], v[128:129], v[192:193]
	v_pk_mul_f32 v[178:179], v[144:145], v[192:193]
	v_pk_fma_f32 v[162:163], v[130:131], v[194:195], v[162:163]
	v_pk_fma_f32 v[178:179], v[146:147], v[194:195], v[178:179]
	ds_read_b128 v[192:195], v3 offset:8192
	s_waitcnt lgkmcnt(3)
	v_pk_fma_f32 v[162:163], v[132:133], v[196:197], v[162:163]
	v_pk_fma_f32 v[178:179], v[148:149], v[196:197], v[178:179]
	v_pk_fma_f32 v[162:163], v[134:135], v[198:199], v[162:163]
	v_pk_fma_f32 v[178:179], v[150:151], v[198:199], v[178:179]
	ds_read_b128 v[196:199], v3 offset:9216
	s_waitcnt lgkmcnt(3)
	v_pk_fma_f32 v[162:163], v[136:137], v[200:201], v[162:163]
	v_pk_fma_f32 v[178:179], v[152:153], v[200:201], v[178:179]
	v_pk_fma_f32 v[162:163], v[138:139], v[202:203], v[162:163]
	v_pk_fma_f32 v[178:179], v[154:155], v[202:203], v[178:179]
	ds_read_b128 v[200:203], v3 offset:10240
	s_waitcnt lgkmcnt(3)
	v_pk_fma_f32 v[162:163], v[140:141], v[204:205], v[162:163]
	v_pk_fma_f32 v[178:179], v[156:157], v[204:205], v[178:179]
	v_pk_fma_f32 v[162:163], v[142:143], v[206:207], v[162:163]
	v_pk_fma_f32 v[178:179], v[158:159], v[206:207], v[178:179]
	ds_read_b128 v[204:207], v3 offset:11264
	s_waitcnt lgkmcnt(3)
	v_pk_mul_f32 v[164:165], v[128:129], v[192:193]
	v_pk_mul_f32 v[180:181], v[144:145], v[192:193]
	v_pk_fma_f32 v[164:165], v[130:131], v[194:195], v[164:165]
	v_pk_fma_f32 v[180:181], v[146:147], v[194:195], v[180:181]
	ds_read_b128 v[192:195], v3 offset:12288
	s_waitcnt lgkmcnt(3)
	v_pk_fma_f32 v[164:165], v[132:133], v[196:197], v[164:165]
	v_pk_fma_f32 v[180:181], v[148:149], v[196:197], v[180:181]
	v_pk_fma_f32 v[164:165], v[134:135], v[198:199], v[164:165]
	v_pk_fma_f32 v[180:181], v[150:151], v[198:199], v[180:181]
	ds_read_b128 v[196:199], v3 offset:13312
	s_waitcnt lgkmcnt(3)
	v_pk_fma_f32 v[164:165], v[136:137], v[200:201], v[164:165]
	v_pk_fma_f32 v[180:181], v[152:153], v[200:201], v[180:181]
	v_pk_fma_f32 v[164:165], v[138:139], v[202:203], v[164:165]
	v_pk_fma_f32 v[180:181], v[154:155], v[202:203], v[180:181]
	ds_read_b128 v[200:203], v3 offset:14336
	s_waitcnt lgkmcnt(3)
	v_pk_fma_f32 v[164:165], v[140:141], v[204:205], v[164:165]
	v_pk_fma_f32 v[180:181], v[156:157], v[204:205], v[180:181]
	v_pk_fma_f32 v[164:165], v[142:143], v[206:207], v[164:165]
	v_pk_fma_f32 v[180:181], v[158:159], v[206:207], v[180:181]
	ds_read_b128 v[204:207], v3 offset:15360
	s_waitcnt lgkmcnt(3)
	v_pk_mul_f32 v[166:167], v[128:129], v[192:193]
	v_pk_mul_f32 v[182:183], v[144:145], v[192:193]
	v_pk_fma_f32 v[166:167], v[130:131], v[194:195], v[166:167]
	v_pk_fma_f32 v[182:183], v[146:147], v[194:195], v[182:183]
	ds_read_b128 v[192:195], v3 offset:16384
	s_waitcnt lgkmcnt(3)
; template <bool WITH_DT, bool OUT8> __device__ __forceinline__ void norm_mod_rows(const void* xp, bool pb16, const void* xs, bool sb16, const float* w, const float* MOD, int ish, int isc, bf16* H, ...
;     ...
;             for (int c = 0; c < 8; ++c) { float p = 0.f;
; #pragma unroll
;                 for (int j = 0; j < 4; ++j) { const f32x4 ww = wdt[WITH_DT ? c : 0][j]; p += (v[j][0] * ww[0] + v[j][1] * ww[1]) + (v[j][2] * ww[2] + v[j][3] * ww[3]); }
;                 d[c] = p; }
	v_pk_fma_f32 v[166:167], v[132:133], v[196:197], v[166:167]
	v_pk_fma_f32 v[182:183], v[148:149], v[196:197], v[182:183]
	v_pk_fma_f32 v[166:167], v[134:135], v[198:199], v[166:167]
	v_pk_fma_f32 v[182:183], v[150:151], v[198:199], v[182:183]
	ds_read_b128 v[196:199], v3 offset:17408
	s_waitcnt lgkmcnt(3)
	v_pk_fma_f32 v[166:167], v[136:137], v[200:201], v[166:167]
	v_pk_fma_f32 v[182:183], v[152:153], v[200:201], v[182:183]
	v_pk_fma_f32 v[166:167], v[138:139], v[202:203], v[166:167]
	v_pk_fma_f32 v[182:183], v[154:155], v[202:203], v[182:183]
	ds_read_b128 v[200:203], v3 offset:18432
	s_waitcnt lgkmcnt(3)
	v_pk_fma_f32 v[166:167], v[140:141], v[204:205], v[166:167]
	v_pk_fma_f32 v[182:183], v[156:157], v[204:205], v[182:183]
	v_pk_fma_f32 v[166:167], v[142:143], v[206:207], v[166:167]
	v_pk_fma_f32 v[182:183], v[158:159], v[206:207], v[182:183]
	ds_read_b128 v[204:207], v3 offset:19456
	s_waitcnt lgkmcnt(3)
	v_pk_mul_f32 v[168:169], v[128:129], v[192:193]
	v_pk_mul_f32 v[184:185], v[144:145], v[192:193]
	v_pk_fma_f32 v[168:169], v[130:131], v[194:195], v[168:169]
	v_pk_fma_f32 v[184:185], v[146:147], v[194:195], v[184:185]
	ds_read_b128 v[192:195], v3 offset:20480
	s_waitcnt lgkmcnt(3)
	v_pk_fma_f32 v[168:169], v[132:133], v[196:197], v[168:169]
	v_pk_fma_f32 v[184:185], v[148:149], v[196:197], v[184:185]
	v_pk_fma_f32 v[168:169], v[134:135], v[198:199], v[168:169]
	v_pk_fma_f32 v[184:185], v[150:151], v[198:199], v[184:185]
	ds_read_b128 v[196:199], v3 offset:21504
	s_waitcnt lgkmcnt(3)
	v_pk_fma_f32 v[168:169], v[136:137], v[200:201], v[168:169]
	v_pk_fma_f32 v[184:185], v[152:153], v[200:201], v[184:185]
	v_pk_fma_f32 v[168:169], v[138:139], v[202:203], v[168:169]
	v_pk_fma_f32 v[184:185], v[154:155], v[202:203], v[184:185]
	ds_read_b128 v[200:203], v3 offset:22528
	s_waitcnt lgkmcnt(3)
	v_pk_fma_f32 v[168:169], v[140:141], v[204:205], v[168:169]
	v_pk_fma_f32 v[184:185], v[156:157], v[204:205], v[184:185]
	v_pk_fma_f32 v[168:169], v[142:143], v[206:207], v[168:169]
	v_pk_fma_f32 v[184:185], v[158:159], v[206:207], v[184:185]
	ds_read_b128 v[204:207], v3 offset:23552
	s_waitcnt lgkmcnt(3)
	v_pk_mul_f32 v[170:171], v[128:129], v[192:193]
	v_pk_mul_f32 v[186:187], v[144:145], v[192:193]
	v_pk_fma_f32 v[170:171], v[130:131], v[194:195], v[170:171]
	v_pk_fma_f32 v[186:187], v[146:147], v[194:195], v[186:187]
	ds_read_b128 v[192:195], v3 offset:24576
	s_waitcnt lgkmcnt(3)
	v_pk_fma_f32 v[170:171], v[132:133], v[196:197], v[170:171]
	v_pk_fma_f32 v[186:187], v[148:149], v[196:197], v[186:187]
	v_pk_fma_f32 v[170:171], v[134:135], v[198:199], v[170:171]
	v_pk_fma_f32 v[186:187], v[150:151], v[198:199], v[186:187]
	ds_read_b128 v[196:199], v3 offset:25600
	s_waitcnt lgkmcnt(3)
	v_pk_fma_f32 v[170:171], v[136:137], v[200:201], v[170:171]
	v_pk_fma_f32 v[186:187], v[152:153], v[200:201], v[186:187]
	v_pk_fma_f32 v[170:171], v[138:139], v[202:203], v[170:171]
	v_pk_fma_f32 v[186:187], v[154:155], v[202:203], v[186:187]
	ds_read_b128 v[200:203], v3 offset:26624
	s_waitcnt lgkmcnt(3)
	v_pk_fma_f32 v[170:171], v[140:141], v[204:205], v[170:171]
	v_pk_fma_f32 v[186:187], v[156:157], v[204:205], v[186:187]
	v_pk_fma_f32 v[170:171], v[142:143], v[206:207], v[170:171]
	v_pk_fma_f32 v[186:187], v[158:159], v[206:207], v[186:187]
	ds_read_b128 v[204:207], v3 offset:27648
	s_waitcnt lgkmcnt(3)
	v_pk_mul_f32 v[172:173], v[128:129], v[192:193]
	v_pk_mul_f32 v[188:189], v[144:145], v[192:193]
	v_pk_fma_f32 v[172:173], v[130:131], v[194:195], v[172:173]
	v_pk_fma_f32 v[188:189], v[146:147], v[194:195], v[188:189]
	ds_read_b128 v[192:195], v3 offset:28672
	s_waitcnt lgkmcnt(3)
	v_pk_fma_f32 v[172:173], v[132:133], v[196:197], v[172:173]
	v_pk_fma_f32 v[188:189], v[148:149], v[196:197], v[188:189]
	v_pk_fma_f32 v[172:173], v[134:135], v[198:199], v[172:173]
	v_pk_fma_f32 v[188:189], v[150:151], v[198:199], v[188:189]
	ds_read_b128 v[196:199], v3 offset:29696
	s_waitcnt lgkmcnt(3)
	v_pk_fma_f32 v[172:173], v[136:137], v[200:201], v[172:173]
	v_pk_fma_f32 v[188:189], v[152:153], v[200:201], v[188:189]
	v_pk_fma_f32 v[172:173], v[138:139], v[202:203], v[172:173]
	v_pk_fma_f32 v[188:189], v[154:155], v[202:203], v[188:189]
	ds_read_b128 v[200:203], v3 offset:30720
	s_waitcnt lgkmcnt(3)
	v_pk_fma_f32 v[172:173], v[140:141], v[204:205], v[172:173]
	v_pk_fma_f32 v[188:189], v[156:157], v[204:205], v[188:189]
	v_pk_fma_f32 v[172:173], v[142:143], v[206:207], v[172:173]
	v_pk_fma_f32 v[188:189], v[158:159], v[206:207], v[188:189]
	ds_read_b128 v[204:207], v3 offset:31744
	s_waitcnt lgkmcnt(3)
	v_pk_mul_f32 v[174:175], v[128:129], v[192:193]
	v_pk_mul_f32 v[190:191], v[144:145], v[192:193]
	v_pk_fma_f32 v[174:175], v[130:131], v[194:195], v[174:175]
	v_pk_fma_f32 v[190:191], v[146:147], v[194:195], v[190:191]
	s_waitcnt lgkmcnt(2)
	v_pk_fma_f32 v[174:175], v[132:133], v[196:197], v[174:175]
	v_pk_fma_f32 v[190:191], v[148:149], v[196:197], v[190:191]
	v_pk_fma_f32 v[174:175], v[134:135], v[198:199], v[174:175]
	v_pk_fma_f32 v[190:191], v[150:151], v[198:199], v[190:191]
	s_waitcnt lgkmcnt(1)
	v_pk_fma_f32 v[174:175], v[136:137], v[200:201], v[174:175]
	v_pk_fma_f32 v[190:191], v[152:153], v[200:201], v[190:191]
	v_pk_fma_f32 v[174:175], v[138:139], v[202:203], v[174:175]
	v_pk_fma_f32 v[190:191], v[154:155], v[202:203], v[190:191]
	s_waitcnt lgkmcnt(0)
; template <bool WITH_DT, bool OUT8> __device__ __forceinline__ void norm_mod_rows(const void* xp, bool pb16, const void* xs, bool sb16, const float* w, const float* MOD, int ish, int isc, bf16* H, ...
;     ...
;             for (int c = 0; c < 8; ++c) { float p = 0.f;
; #pragma unroll
;                 for (int j = 0; j < 4; ++j) { const f32x4 ww = wdt[WITH_DT ? c : 0][j]; p += (v[j][0] * ww[0] + v[j][1] * ww[1]) + (v[j][2] * ww[2] + v[j][3] * ww[3]); }
;                 d[c] = p; }
;             float e4[4], e2[2], e1;
;             { const bool up = (lane & 32) != 0;
; #pragma unroll
;               for (int c = 0; c < 4; ++c) { const float keep = up ? d[4 + c] : d[c], give = up ? d[c] : d[4 + c]; e4[c] = keep + __shfl_xor(give, 32); } }
;             { const bool up = (lane & 16) != 0;
; #pragma unroll
;               for (int c = 0; c < 2; ++c) { const float keep = up ? e4[2 + c] : e4[c], give = up ? e4[c] : e4[2 + c]; e2[c] = keep + __shfl_xor(give, 16); } }
;             { const bool up = (lane & 8) != 0; const float keep = up ? e2[1] : e2[0], give = up ? e2[0] : e2[1]; e1 = keep + __shfl_xor(give, 8); }
;             e1 += __shfl_xor(e1, 4); e1 += __shfl_xor(e1, 2); e1 += __shfl_xor(e1, 1);
;             const int col = ((lane >> 5) & 1) * 4 + ((lane >> 4) & 1) * 2 + ((lane >> 3) & 1);
;             if ((lane & 7) == 0) { const float p = e1 + dt_bias[col]; DT[(size_t)row * 8 + col] = fmaxf(p, 0.f) + log1pf(__expf(-fabsf(p))); }
	v_pk_fma_f32 v[174:175], v[140:141], v[204:205], v[174:175]
	v_pk_fma_f32 v[190:191], v[156:157], v[204:205], v[190:191]
	v_pk_fma_f32 v[174:175], v[142:143], v[206:207], v[174:175]
	v_pk_fma_f32 v[190:191], v[158:159], v[206:207], v[190:191]
	v_add_f32_e32 v160, v160, v161
	v_add_f32_e32 v176, v176, v177
	v_add_f32_e32 v162, v162, v163
	v_add_f32_e32 v178, v178, v179
	v_add_f32_e32 v164, v164, v165
	v_add_f32_e32 v180, v180, v181
	v_add_f32_e32 v166, v166, v167
	v_add_f32_e32 v182, v182, v183
	v_add_f32_e32 v168, v168, v169
	v_add_f32_e32 v184, v184, v185
	v_add_f32_e32 v170, v170, v171
	v_add_f32_e32 v186, v186, v187
	v_add_f32_e32 v172, v172, v173
	v_add_f32_e32 v188, v188, v189
	v_add_f32_e32 v174, v174, v175
	v_add_f32_e32 v190, v190, v191
	v_cndmask_b32_e64 v216, v160, v168, s[38:39]
	v_cndmask_b32_e64 v217, v168, v160, s[38:39]
	v_cndmask_b32_e64 v224, v176, v184, s[38:39]
	v_cndmask_b32_e64 v225, v184, v176, s[38:39]
	v_cndmask_b32_e64 v218, v162, v170, s[38:39]
	v_cndmask_b32_e64 v219, v170, v162, s[38:39]
	v_cndmask_b32_e64 v226, v178, v186, s[38:39]
	v_cndmask_b32_e64 v227, v186, v178, s[38:39]
	v_cndmask_b32_e64 v220, v164, v172, s[38:39]
	v_cndmask_b32_e64 v221, v172, v164, s[38:39]
	v_cndmask_b32_e64 v228, v180, v188, s[38:39]
	v_cndmask_b32_e64 v229, v188, v180, s[38:39]
	v_cndmask_b32_e64 v222, v166, v174, s[38:39]
	v_cndmask_b32_e64 v223, v174, v166, s[38:39]
	v_cndmask_b32_e64 v230, v182, v190, s[38:39]
	v_cndmask_b32_e64 v231, v190, v182, s[38:39]
	s_nop 0
	v_add_f32_dpp v160, v217, v216 quad_perm:[1,0,3,2] row_mask:0xf bank_mask:0xf
	v_add_f32_dpp v176, v225, v224 quad_perm:[1,0,3,2] row_mask:0xf bank_mask:0xf
	v_add_f32_dpp v162, v219, v218 quad_perm:[1,0,3,2] row_mask:0xf bank_mask:0xf
	v_add_f32_dpp v178, v227, v226 quad_perm:[1,0,3,2] row_mask:0xf bank_mask:0xf
	v_add_f32_dpp v164, v221, v220 quad_perm:[1,0,3,2] row_mask:0xf bank_mask:0xf
	v_add_f32_dpp v180, v229, v228 quad_perm:[1,0,3,2] row_mask:0xf bank_mask:0xf
	v_add_f32_dpp v166, v223, v222 quad_perm:[1,0,3,2] row_mask:0xf bank_mask:0xf
	v_add_f32_dpp v182, v231, v230 quad_perm:[1,0,3,2] row_mask:0xf bank_mask:0xf
	v_cndmask_b32_e64 v216, v160, v164, s[40:41]
	v_cndmask_b32_e64 v217, v164, v160, s[40:41]
	v_cndmask_b32_e64 v224, v176, v180, s[40:41]
	v_cndmask_b32_e64 v225, v180, v176, s[40:41]
	v_cndmask_b32_e64 v218, v162, v166, s[40:41]
	v_cndmask_b32_e64 v219, v166, v162, s[40:41]
	v_cndmask_b32_e64 v226, v178, v182, s[40:41]
	v_cndmask_b32_e64 v227, v182, v178, s[40:41]
	s_nop 0
	v_add_f32_dpp v160, v217, v216 quad_perm:[2,3,0,1] row_mask:0xf bank_mask:0xf
	v_add_f32_dpp v176, v225, v224 quad_perm:[2,3,0,1] row_mask:0xf bank_mask:0xf
	v_add_f32_dpp v162, v219, v218 quad_perm:[2,3,0,1] row_mask:0xf bank_mask:0xf
	v_add_f32_dpp v178, v227, v226 quad_perm:[2,3,0,1] row_mask:0xf bank_mask:0xf
	v_cndmask_b32_e64 v216, v160, v162, s[42:43]
	v_cndmask_b32_e64 v217, v162, v160, s[42:43]
	v_cndmask_b32_e64 v224, v176, v178, s[42:43]
	v_cndmask_b32_e64 v225, v178, v176, s[42:43]
	s_nop 0
	v_add_f32_dpp v160, v217, v216 row_shl:4 row_mask:0xf bank_mask:0x5
	v_add_f32_dpp v160, v217, v216 row_shr:4 row_mask:0xf bank_mask:0xa
	v_add_f32_dpp v176, v225, v224 row_shl:4 row_mask:0xf bank_mask:0x5
	v_add_f32_dpp v176, v225, v224 row_shr:4 row_mask:0xf bank_mask:0xa
	s_nop 1
	v_add_f32_dpp v160, v160, v160 row_ror:8 row_mask:0xf bank_mask:0xf
	v_add_f32_dpp v176, v176, v176 row_ror:8 row_mask:0xf bank_mask:0xf
	s_nop 0
	ds_bpermute_b32 v161, v5, v160
	ds_bpermute_b32 v177, v5, v176
	s_waitcnt lgkmcnt(0)
	v_add_f32_e32 v160, v160, v161
	v_add_f32_e32 v176, v176, v177
	v_mov_b32_e32 v161, v160
	v_mov_b32_e32 v177, v176
	s_nop 1
	v_permlane32_swap_b32_e32 v160, v161
	v_permlane32_swap_b32_e32 v176, v177
	v_add_f32_e32 v160, v160, v161
	v_add_f32_e32 v176, v176, v177
	v_add_f32_e32 v160, v160, v12
	v_add_f32_e32 v176, v176, v12
	v_and_b32_e32 v216, 0x7fffffff, v160
	v_and_b32_e32 v224, 0x7fffffff, v176
	v_mul_f32_e32 v216, 0xbfb8aa3b, v216
	v_mul_f32_e32 v224, 0xbfb8aa3b, v224
	v_exp_f32_e32 v216, v216
	v_exp_f32_e32 v224, v224
	s_nop 0
	v_add_f32_e32 v217, 1.0, v216
	v_add_f32_e32 v225, 1.0, v224
	v_log_f32_e32 v218, v217
	v_log_f32_e32 v226, v225
	v_add_f32_e32 v219, -1.0, v217
	v_add_f32_e32 v227, -1.0, v225
	v_rcp_f32_e32 v219, v219
	v_rcp_f32_e32 v227, v227
	v_mul_f32_e32 v218, 0x3f317218, v218
	v_mul_f32_e32 v226, 0x3f317218, v226
	v_mul_f32_e32 v219, v216, v219
	v_mul_f32_e32 v227, v224, v227
	v_mul_f32_e32 v218, v218, v219
	v_mul_f32_e32 v226, v226, v227
	v_cmp_eq_f32_e32 vcc, 1.0, v217
	s_nop 1
	v_cndmask_b32_e32 v218, v218, v216, vcc
	v_cmp_eq_f32_e32 vcc, 1.0, v225
	s_nop 1
	v_cndmask_b32_e32 v226, v226, v224, vcc
	v_max_f32_e32 v160, 0, v160
	v_max_f32_e32 v176, 0, v176
	v_add_f32_e32 v160, v160, v218
	v_add_f32_e32 v176, v176, v226
	v_cndmask_b32_e64 v160, v160, v176, s[44:45]
	s_mov_b64 exec, 0xffff
	global_store_dword v4, v160, s[28:29]
	s_mov_b64 exec, -1
	s_add_u32 s28, s28, 64
	s_addc_u32 s29, s29, 0
	s_waitcnt vmcnt(60)
; __device__ __forceinline__ unsigned pk2(float lo, float hi) { return pg8::cvt_pk_bf16(lo, hi); }
; template <bool WITH_DT, bool OUT8> __device__ __forceinline__ void norm_mod_rows(const void* xp, bool pb16, const void* xs, bool sb16, const float* w, const float* MOD, int ish, int isc, bf16* H, ...
;     ...
;         for (int j = 0; j < 4; ++j) s += (v[j][0] * v[j][0] + v[j][1] * v[j][1]) + (v[j][2] * v[j][2] + v[j][3] * v[j][3]);
;         const float rstd = rsqrtf(wave_sum(s) * (1.0f / DM) + EPSN);
;         const f32x4* sh = (const f32x4*)(MOD + (size_t)mb * 9216 + ish * 1024); const f32x4* sc = (const f32x4*)(MOD + (size_t)mb * 9216 + isc * 1024);
; #pragma unroll
;         for (int j = 0; j < 4; ++j) { const f32x4 a = v[j] * rstd * wv[j]; v[j] = a * (sc[lane + 64 * j] + 1.0f) + sh[lane + 64 * j];
;             if (OUT8) { *(unsigned*)((unsigned char*)H + (size_t)row * DM + 4 * (lane + 64 * j)) = pk4_fp8(v[j][0] * SC_H8, v[j][1] * SC_H8, v[j][2] * SC_H8, v[j][3] * SC_H8); }
;             else { v2u o; o.x = pk2(v[j][0], v[j][1]); o.y = pk2(v[j][2], v[j][3]); *(v2u*)(H + (size_t)row * DM + 4 * (lane + 64 * j)) = o; } }
	v_lshlrev_b32_e32 v128, 16, v64
	v_and_b32_e32 v129, 0xffff0000, v64
	v_lshlrev_b32_e32 v130, 16, v65
	v_and_b32_e32 v131, 0xffff0000, v65
	v_lshlrev_b32_e32 v132, 16, v66
	v_and_b32_e32 v133, 0xffff0000, v66
	v_lshlrev_b32_e32 v134, 16, v67
	v_and_b32_e32 v135, 0xffff0000, v67
	v_lshlrev_b32_e32 v136, 16, v68
	v_and_b32_e32 v137, 0xffff0000, v68
	v_lshlrev_b32_e32 v138, 16, v69
	v_and_b32_e32 v139, 0xffff0000, v69
	v_lshlrev_b32_e32 v140, 16, v70
	v_and_b32_e32 v141, 0xffff0000, v70
	v_lshlrev_b32_e32 v142, 16, v71
	v_and_b32_e32 v143, 0xffff0000, v71
	v_lshlrev_b32_e32 v144, 16, v72
	v_and_b32_e32 v145, 0xffff0000, v72
	v_lshlrev_b32_e32 v146, 16, v73
	v_and_b32_e32 v147, 0xffff0000, v73
	v_lshlrev_b32_e32 v148, 16, v74
	v_and_b32_e32 v149, 0xffff0000, v74
	v_lshlrev_b32_e32 v150, 16, v75
	v_and_b32_e32 v151, 0xffff0000, v75
	v_lshlrev_b32_e32 v152, 16, v76
	v_and_b32_e32 v153, 0xffff0000, v76
	v_lshlrev_b32_e32 v154, 16, v77
	v_and_b32_e32 v155, 0xffff0000, v77
	v_lshlrev_b32_e32 v156, 16, v78
	v_and_b32_e32 v157, 0xffff0000, v78
	v_lshlrev_b32_e32 v158, 16, v79
	v_and_b32_e32 v159, 0xffff0000, v79
	v_pk_mul_f32 v[208:209], v[128:129], v[128:129]
	v_pk_mul_f32 v[210:211], v[130:131], v[130:131]
	v_pk_mul_f32 v[212:213], v[144:145], v[144:145]
	v_pk_mul_f32 v[214:215], v[146:147], v[146:147]
	v_pk_fma_f32 v[208:209], v[132:133], v[132:133], v[208:209]
	v_pk_fma_f32 v[210:211], v[134:135], v[134:135], v[210:211]
	v_pk_fma_f32 v[212:213], v[148:149], v[148:149], v[212:213]
	v_pk_fma_f32 v[214:215], v[150:151], v[150:151], v[214:215]
	v_pk_fma_f32 v[208:209], v[136:137], v[136:137], v[208:209]
	v_pk_fma_f32 v[210:211], v[138:139], v[138:139], v[210:211]
	v_pk_fma_f32 v[212:213], v[152:153], v[152:153], v[212:213]
	v_pk_fma_f32 v[214:215], v[154:155], v[154:155], v[214:215]
	v_pk_fma_f32 v[208:209], v[140:141], v[140:141], v[208:209]
	v_pk_fma_f32 v[210:211], v[142:143], v[142:143], v[210:211]
	v_pk_fma_f32 v[212:213], v[156:157], v[156:157], v[212:213]
	v_pk_fma_f32 v[214:215], v[158:159], v[158:159], v[214:215]
	v_pk_add_f32 v[208:209], v[208:209], v[210:211]
	v_pk_add_f32 v[212:213], v[212:213], v[214:215]
	v_add_f32_e32 v208, v208, v209
	v_add_f32_e32 v212, v212, v213
	s_nop 0
	v_add_f32_dpp v208, v208, v208 quad_perm:[1,0,3,2] row_mask:0xf bank_mask:0xf
	v_add_f32_dpp v212, v212, v212 quad_perm:[1,0,3,2] row_mask:0xf bank_mask:0xf
	s_nop 0
	v_add_f32_dpp v208, v208, v208 quad_perm:[2,3,0,1] row_mask:0xf bank_mask:0xf
	v_add_f32_dpp v212, v212, v212 quad_perm:[2,3,0,1] row_mask:0xf bank_mask:0xf
	s_nop 0
	v_add_f32_dpp v208, v208, v208 row_half_mirror row_mask:0xf bank_mask:0xf
	v_add_f32_dpp v212, v212, v212 row_half_mirror row_mask:0xf bank_mask:0xf
	s_nop 0
	v_add_f32_dpp v208, v208, v208 row_mirror row_mask:0xf bank_mask:0xf
	v_add_f32_dpp v212, v212, v212 row_mirror row_mask:0xf bank_mask:0xf
	s_nop 0
	v_readlane_b32 s30, v208, 0
	v_readlane_b32 s31, v208, 16
	v_readlane_b32 s32, v208, 32
	v_readlane_b32 s33, v208, 48
	v_readlane_b32 s34, v212, 0
	v_readlane_b32 s35, v212, 16
	v_readlane_b32 s36, v212, 32
	v_readlane_b32 s37, v212, 48
	s_nop 1
	v_mov_b32_e32 v209, s30
	v_mov_b32_e32 v213, s34
	v_add_f32_e32 v209, s31, v209
	v_add_f32_e32 v213, s35, v213
	v_add_f32_e32 v209, s32, v209
	v_add_f32_e32 v213, s36, v213
	v_add_f32_e32 v209, s33, v209
	v_add_f32_e32 v213, s37, v213
	v_fmamk_f32 v209, v209, 0x3a800000, v8
	v_fmamk_f32 v213, v213, 0x3a800000, v8
	v_rsq_f32_e32 v210, v209
	v_rsq_f32_e32 v214, v213
	s_nop 0
	v_pk_mul_f32 v[128:129], v[128:129], v[210:211] op_sel_hi:[1,0]
	v_pk_mul_f32 v[130:131], v[130:131], v[210:211] op_sel_hi:[1,0]
	v_pk_mul_f32 v[132:133], v[132:133], v[210:211] op_sel_hi:[1,0]
	v_pk_mul_f32 v[134:135], v[134:135], v[210:211] op_sel_hi:[1,0]
	v_pk_mul_f32 v[136:137], v[136:137], v[210:211] op_sel_hi:[1,0]
	v_pk_mul_f32 v[138:139], v[138:139], v[210:211] op_sel_hi:[1,0]
	v_pk_mul_f32 v[140:141], v[140:141], v[210:211] op_sel_hi:[1,0]
	v_pk_mul_f32 v[142:143], v[142:143], v[210:211] op_sel_hi:[1,0]
	v_pk_mul_f32 v[144:145], v[144:145], v[214:215] op_sel_hi:[1,0]
	v_pk_mul_f32 v[146:147], v[146:147], v[214:215] op_sel_hi:[1,0]
	v_pk_mul_f32 v[148:149], v[148:149], v[214:215] op_sel_hi:[1,0]
	v_pk_mul_f32 v[150:151], v[150:151], v[214:215] op_sel_hi:[1,0]
	v_pk_mul_f32 v[152:153], v[152:153], v[214:215] op_sel_hi:[1,0]
	v_pk_mul_f32 v[154:155], v[154:155], v[214:215] op_sel_hi:[1,0]
	v_pk_mul_f32 v[156:157], v[156:157], v[214:215] op_sel_hi:[1,0]
	v_pk_mul_f32 v[158:159], v[158:159], v[214:215] op_sel_hi:[1,0]
	v_pk_fma_f32 v[128:129], v[128:129], v[16:17], v[32:33]
	v_pk_fma_f32 v[130:131], v[130:131], v[18:19], v[34:35]
	v_pk_fma_f32 v[132:133], v[132:133], v[20:21], v[36:37]
	v_pk_fma_f32 v[134:135], v[134:135], v[22:23], v[38:39]
	v_pk_fma_f32 v[136:137], v[136:137], v[24:25], v[40:41]
	v_pk_fma_f32 v[138:139], v[138:139], v[26:27], v[42:43]
	v_pk_fma_f32 v[140:141], v[140:141], v[28:29], v[44:45]
	v_pk_fma_f32 v[142:143], v[142:143], v[30:31], v[46:47]
	v_pk_fma_f32 v[144:145], v[144:145], v[16:17], v[32:33]
	v_pk_fma_f32 v[146:147], v[146:147], v[18:19], v[34:35]
	v_pk_fma_f32 v[148:149], v[148:149], v[20:21], v[36:37]
	v_pk_fma_f32 v[150:151], v[150:151], v[22:23], v[38:39]
	v_pk_fma_f32 v[152:153], v[152:153], v[24:25], v[40:41]
	v_pk_fma_f32 v[154:155], v[154:155], v[26:27], v[42:43]
	v_pk_fma_f32 v[156:157], v[156:157], v[28:29], v[44:45]
	v_pk_fma_f32 v[158:159], v[158:159], v[30:31], v[46:47]
	v_cvt_pk_bf16_f32 v216, v128, v129
	v_cvt_pk_bf16_f32 v217, v130, v131
	v_cvt_pk_bf16_f32 v218, v132, v133
	v_cvt_pk_bf16_f32 v219, v134, v135
	v_cvt_pk_bf16_f32 v220, v136, v137
	v_cvt_pk_bf16_f32 v221, v138, v139
	v_cvt_pk_bf16_f32 v222, v140, v141
	v_cvt_pk_bf16_f32 v223, v142, v143
	v_cvt_pk_bf16_f32 v224, v144, v145
	v_cvt_pk_bf16_f32 v225, v146, v147
	v_cvt_pk_bf16_f32 v226, v148, v149
	v_cvt_pk_bf16_f32 v227, v150, v151
	v_cvt_pk_bf16_f32 v228, v152, v153
	v_cvt_pk_bf16_f32 v229, v154, v155
	v_cvt_pk_bf16_f32 v230, v156, v157
	v_cvt_pk_bf16_f32 v231, v158, v159
	global_store_dwordx2 v2, v[216:217], s[20:21]
	global_store_dwordx2 v2, v[218:219], s[20:21] offset:512
	global_store_dwordx2 v2, v[220:221], s[20:21] offset:1024
	global_store_dwordx2 v2, v[222:223], s[20:21] offset:1536
	global_store_dwordx2 v2, v[224:225], s[20:21] offset:2048
	global_store_dwordx2 v2, v[226:227], s[20:21] offset:2560
	global_store_dwordx2 v2, v[228:229], s[20:21] offset:3072
	global_store_dwordx2 v2, v[230:231], s[20:21] offset:3584
	s_add_u32 s20, s20, 0x1000
	s_addc_u32 s21, s21, 0
	ds_read_b128 v[192:195], v3 offset:0
	ds_read_b128 v[196:199], v3 offset:1024
	ds_read_b128 v[200:203], v3 offset:2048
	ds_read_b128 v[204:207], v3 offset:3072
	s_waitcnt lgkmcnt(3)
; template <bool WITH_DT, bool OUT8> __device__ __forceinline__ void norm_mod_rows(const void* xp, bool pb16, const void* xs, bool sb16, const float* w, const float* MOD, int ish, int isc, bf16* H, ...
;     ...
;         if (WITH_DT) {
;             float d[8];
; #pragma unroll
;             for (int c = 0; c < 8; ++c) { float p = 0.f;
; #pragma unroll
;                 for (int j = 0; j < 4; ++j) { const f32x4 ww = wdt[WITH_DT ? c : 0][j]; p += (v[j][0] * ww[0] + v[j][1] * ww[1]) + (v[j][2] * ww[2] + v[j][3] * ww[3]); }
;                 d[c] = p; }
	v_pk_mul_f32 v[160:161], v[128:129], v[192:193]
	v_pk_mul_f32 v[176:177], v[144:145], v[192:193]
	v_pk_fma_f32 v[160:161], v[130:131], v[194:195], v[160:161]
	v_pk_fma_f32 v[176:177], v[146:147], v[194:195], v[176:177]
	ds_read_b128 v[192:195], v3 offset:4096
	s_waitcnt lgkmcnt(3)
	v_pk_fma_f32 v[160:161], v[132:133], v[196:197], v[160:161]
	v_pk_fma_f32 v[176:177], v[148:149], v[196:197], v[176:177]
	v_pk_fma_f32 v[160:161], v[134:135], v[198:199], v[160:161]
	v_pk_fma_f32 v[176:177], v[150:151], v[198:199], v[176:177]
	ds_read_b128 v[196:199], v3 offset:5120
	s_waitcnt lgkmcnt(3)
	v_pk_fma_f32 v[160:161], v[136:137], v[200:201], v[160:161]
	v_pk_fma_f32 v[176:177], v[152:153], v[200:201], v[176:177]
	v_pk_fma_f32 v[160:161], v[138:139], v[202:203], v[160:161]
	v_pk_fma_f32 v[176:177], v[154:155], v[202:203], v[176:177]
	ds_read_b128 v[200:203], v3 offset:6144
	s_waitcnt lgkmcnt(3)
	v_pk_fma_f32 v[160:161], v[140:141], v[204:205], v[160:161]
	v_pk_fma_f32 v[176:177], v[156:157], v[204:205], v[176:177]
	v_pk_fma_f32 v[160:161], v[142:143], v[206:207], v[160:161]
	v_pk_fma_f32 v[176:177], v[158:159], v[206:207], v[176:177]
	ds_read_b128 v[204:207], v3 offset:7168
	s_waitcnt lgkmcnt(3)
	v_pk_mul_f32 v[162:163], v[128:129], v[192:193]
	v_pk_mul_f32 v[178:179], v[144:145], v[192:193]
	v_pk_fma_f32 v[162:163], v[130:131], v[194:195], v[162:163]
	v_pk_fma_f32 v[178:179], v[146:147], v[194:195], v[178:179]
	ds_read_b128 v[192:195], v3 offset:8192
	s_waitcnt lgkmcnt(3)
	v_pk_fma_f32 v[162:163], v[132:133], v[196:197], v[162:163]
	v_pk_fma_f32 v[178:179], v[148:149], v[196:197], v[178:179]
	v_pk_fma_f32 v[162:163], v[134:135], v[198:199], v[162:163]
	v_pk_fma_f32 v[178:179], v[150:151], v[198:199], v[178:179]
	ds_read_b128 v[196:199], v3 offset:9216
	s_waitcnt lgkmcnt(3)
	v_pk_fma_f32 v[162:163], v[136:137], v[200:201], v[162:163]
	v_pk_fma_f32 v[178:179], v[152:153], v[200:201], v[178:179]
	v_pk_fma_f32 v[162:163], v[138:139], v[202:203], v[162:163]
	v_pk_fma_f32 v[178:179], v[154:155], v[202:203], v[178:179]
	ds_read_b128 v[200:203], v3 offset:10240
	s_waitcnt lgkmcnt(3)
	v_pk_fma_f32 v[162:163], v[140:141], v[204:205], v[162:163]
	v_pk_fma_f32 v[178:179], v[156:157], v[204:205], v[178:179]
	v_pk_fma_f32 v[162:163], v[142:143], v[206:207], v[162:163]
	v_pk_fma_f32 v[178:179], v[158:159], v[206:207], v[178:179]
	ds_read_b128 v[204:207], v3 offset:11264
	s_waitcnt lgkmcnt(3)
	v_pk_mul_f32 v[164:165], v[128:129], v[192:193]
	v_pk_mul_f32 v[180:181], v[144:145], v[192:193]
	v_pk_fma_f32 v[164:165], v[130:131], v[194:195], v[164:165]
	v_pk_fma_f32 v[180:181], v[146:147], v[194:195], v[180:181]
	ds_read_b128 v[192:195], v3 offset:12288
	s_waitcnt lgkmcnt(3)
	v_pk_fma_f32 v[164:165], v[132:133], v[196:197], v[164:165]
	v_pk_fma_f32 v[180:181], v[148:149], v[196:197], v[180:181]
	v_pk_fma_f32 v[164:165], v[134:135], v[198:199], v[164:165]
	v_pk_fma_f32 v[180:181], v[150:151], v[198:199], v[180:181]
	ds_read_b128 v[196:199], v3 offset:13312
	s_waitcnt lgkmcnt(3)
	v_pk_fma_f32 v[164:165], v[136:137], v[200:201], v[164:165]
	v_pk_fma_f32 v[180:181], v[152:153], v[200:201], v[180:181]
	v_pk_fma_f32 v[164:165], v[138:139], v[202:203], v[164:165]
	v_pk_fma_f32 v[180:181], v[154:155], v[202:203], v[180:181]
	ds_read_b128 v[200:203], v3 offset:14336
	s_waitcnt lgkmcnt(3)
	v_pk_fma_f32 v[164:165], v[140:141], v[204:205], v[164:165]
	v_pk_fma_f32 v[180:181], v[156:157], v[204:205], v[180:181]
	v_pk_fma_f32 v[164:165], v[142:143], v[206:207], v[164:165]
	v_pk_fma_f32 v[180:181], v[158:159], v[206:207], v[180:181]
	ds_read_b128 v[204:207], v3 offset:15360
	s_waitcnt lgkmcnt(3)
	v_pk_mul_f32 v[166:167], v[128:129], v[192:193]
	v_pk_mul_f32 v[182:183], v[144:145], v[192:193]
	v_pk_fma_f32 v[166:167], v[130:131], v[194:195], v[166:167]
	v_pk_fma_f32 v[182:183], v[146:147], v[194:195], v[182:183]
	ds_read_b128 v[192:195], v3 offset:16384
	s_waitcnt lgkmcnt(3)
	v_pk_fma_f32 v[166:167], v[132:133], v[196:197], v[166:167]
	v_pk_fma_f32 v[182:183], v[148:149], v[196:197], v[182:183]
	v_pk_fma_f32 v[166:167], v[134:135], v[198:199], v[166:167]
	v_pk_fma_f32 v[182:183], v[150:151], v[198:199], v[182:183]
	ds_read_b128 v[196:199], v3 offset:17408
	s_waitcnt lgkmcnt(3)
	v_pk_fma_f32 v[166:167], v[136:137], v[200:201], v[166:167]
	v_pk_fma_f32 v[182:183], v[152:153], v[200:201], v[182:183]
	v_pk_fma_f32 v[166:167], v[138:139], v[202:203], v[166:167]
	v_pk_fma_f32 v[182:183], v[154:155], v[202:203], v[182:183]
	ds_read_b128 v[200:203], v3 offset:18432
	s_waitcnt lgkmcnt(3)
	v_pk_fma_f32 v[166:167], v[140:141], v[204:205], v[166:167]
	v_pk_fma_f32 v[182:183], v[156:157], v[204:205], v[182:183]
	v_pk_fma_f32 v[166:167], v[142:143], v[206:207], v[166:167]
	v_pk_fma_f32 v[182:183], v[158:159], v[206:207], v[182:183]
	ds_read_b128 v[204:207], v3 offset:19456
	s_waitcnt lgkmcnt(3)
	v_pk_mul_f32 v[168:169], v[128:129], v[192:193]
	v_pk_mul_f32 v[184:185], v[144:145], v[192:193]
	v_pk_fma_f32 v[168:169], v[130:131], v[194:195], v[168:169]
	v_pk_fma_f32 v[184:185], v[146:147], v[194:195], v[184:185]
	ds_read_b128 v[192:195], v3 offset:20480
	s_waitcnt lgkmcnt(3)
	v_pk_fma_f32 v[168:169], v[132:133], v[196:197], v[168:169]
	v_pk_fma_f32 v[184:185], v[148:149], v[196:197], v[184:185]
	v_pk_fma_f32 v[168:169], v[134:135], v[198:199], v[168:169]
	v_pk_fma_f32 v[184:185], v[150:151], v[198:199], v[184:185]
	ds_read_b128 v[196:199], v3 offset:21504
	s_waitcnt lgkmcnt(3)
	v_pk_fma_f32 v[168:169], v[136:137], v[200:201], v[168:169]
	v_pk_fma_f32 v[184:185], v[152:153], v[200:201], v[184:185]
	v_pk_fma_f32 v[168:169], v[138:139], v[202:203], v[168:169]
	v_pk_fma_f32 v[184:185], v[154:155], v[202:203], v[184:185]
	ds_read_b128 v[200:203], v3 offset:22528
	s_waitcnt lgkmcnt(3)
; template <bool WITH_DT, bool OUT8> __device__ __forceinline__ void norm_mod_rows(const void* xp, bool pb16, const void* xs, bool sb16, const float* w, const float* MOD, int ish, int isc, bf16* H, ...
;     ...
;             for (int c = 0; c < 8; ++c) { float p = 0.f;
; #pragma unroll
;                 for (int j = 0; j < 4; ++j) { const f32x4 ww = wdt[WITH_DT ? c : 0][j]; p += (v[j][0] * ww[0] + v[j][1] * ww[1]) + (v[j][2] * ww[2] + v[j][3] * ww[3]); }
;                 d[c] = p; }
;             float e4[4], e2[2], e1;
;             { const bool up = (lane & 32) != 0;
; #pragma unroll
;               for (int c = 0; c < 4; ++c) { const float keep = up ? d[4 + c] : d[c], give = up ? d[c] : d[4 + c]; e4[c] = keep + __shfl_xor(give, 32); } }
;             { const bool up = (lane & 16) != 0;
; #pragma unroll
;               for (int c = 0; c < 2; ++c) { const float keep = up ? e4[2 + c] : e4[c], give = up ? e4[c] : e4[2 + c]; e2[c] = keep + __shfl_xor(give, 16); } }
;             { const bool up = (lane & 8) != 0; const float keep = up ? e2[1] : e2[0], give = up ? e2[0] : e2[1]; e1 = keep + __shfl_xor(give, 8); }
;             e1 += __shfl_xor(e1, 4); e1 += __shfl_xor(e1, 2); e1 += __shfl_xor(e1, 1);
	v_pk_fma_f32 v[168:169], v[140:141], v[204:205], v[168:169]
	v_pk_fma_f32 v[184:185], v[156:157], v[204:205], v[184:185]
	v_pk_fma_f32 v[168:169], v[142:143], v[206:207], v[168:169]
	v_pk_fma_f32 v[184:185], v[158:159], v[206:207], v[184:185]
	ds_read_b128 v[204:207], v3 offset:23552
	s_waitcnt lgkmcnt(3)
	v_pk_mul_f32 v[170:171], v[128:129], v[192:193]
	v_pk_mul_f32 v[186:187], v[144:145], v[192:193]
	v_pk_fma_f32 v[170:171], v[130:131], v[194:195], v[170:171]
	v_pk_fma_f32 v[186:187], v[146:147], v[194:195], v[186:187]
	ds_read_b128 v[192:195], v3 offset:24576
	s_waitcnt lgkmcnt(3)
	v_pk_fma_f32 v[170:171], v[132:133], v[196:197], v[170:171]
	v_pk_fma_f32 v[186:187], v[148:149], v[196:197], v[186:187]
	v_pk_fma_f32 v[170:171], v[134:135], v[198:199], v[170:171]
	v_pk_fma_f32 v[186:187], v[150:151], v[198:199], v[186:187]
	ds_read_b128 v[196:199], v3 offset:25600
	s_waitcnt lgkmcnt(3)
	v_pk_fma_f32 v[170:171], v[136:137], v[200:201], v[170:171]
	v_pk_fma_f32 v[186:187], v[152:153], v[200:201], v[186:187]
	v_pk_fma_f32 v[170:171], v[138:139], v[202:203], v[170:171]
	v_pk_fma_f32 v[186:187], v[154:155], v[202:203], v[186:187]
	ds_read_b128 v[200:203], v3 offset:26624
	s_waitcnt lgkmcnt(3)
	v_pk_fma_f32 v[170:171], v[140:141], v[204:205], v[170:171]
	v_pk_fma_f32 v[186:187], v[156:157], v[204:205], v[186:187]
	v_pk_fma_f32 v[170:171], v[142:143], v[206:207], v[170:171]
	v_pk_fma_f32 v[186:187], v[158:159], v[206:207], v[186:187]
	ds_read_b128 v[204:207], v3 offset:27648
	s_waitcnt lgkmcnt(3)
	v_pk_mul_f32 v[172:173], v[128:129], v[192:193]
	v_pk_mul_f32 v[188:189], v[144:145], v[192:193]
	v_pk_fma_f32 v[172:173], v[130:131], v[194:195], v[172:173]
	v_pk_fma_f32 v[188:189], v[146:147], v[194:195], v[188:189]
	ds_read_b128 v[192:195], v3 offset:28672
	s_waitcnt lgkmcnt(3)
	v_pk_fma_f32 v[172:173], v[132:133], v[196:197], v[172:173]
	v_pk_fma_f32 v[188:189], v[148:149], v[196:197], v[188:189]
	v_pk_fma_f32 v[172:173], v[134:135], v[198:199], v[172:173]
	v_pk_fma_f32 v[188:189], v[150:151], v[198:199], v[188:189]
	ds_read_b128 v[196:199], v3 offset:29696
	s_waitcnt lgkmcnt(3)
	v_pk_fma_f32 v[172:173], v[136:137], v[200:201], v[172:173]
	v_pk_fma_f32 v[188:189], v[152:153], v[200:201], v[188:189]
	v_pk_fma_f32 v[172:173], v[138:139], v[202:203], v[172:173]
	v_pk_fma_f32 v[188:189], v[154:155], v[202:203], v[188:189]
	ds_read_b128 v[200:203], v3 offset:30720
	s_waitcnt lgkmcnt(3)
	v_pk_fma_f32 v[172:173], v[140:141], v[204:205], v[172:173]
	v_pk_fma_f32 v[188:189], v[156:157], v[204:205], v[188:189]
	v_pk_fma_f32 v[172:173], v[142:143], v[206:207], v[172:173]
	v_pk_fma_f32 v[188:189], v[158:159], v[206:207], v[188:189]
	ds_read_b128 v[204:207], v3 offset:31744
	s_waitcnt lgkmcnt(3)
	v_pk_mul_f32 v[174:175], v[128:129], v[192:193]
	v_pk_mul_f32 v[190:191], v[144:145], v[192:193]
	v_pk_fma_f32 v[174:175], v[130:131], v[194:195], v[174:175]
	v_pk_fma_f32 v[190:191], v[146:147], v[194:195], v[190:191]
	s_waitcnt lgkmcnt(2)
	v_pk_fma_f32 v[174:175], v[132:133], v[196:197], v[174:175]
	v_pk_fma_f32 v[190:191], v[148:149], v[196:197], v[190:191]
	v_pk_fma_f32 v[174:175], v[134:135], v[198:199], v[174:175]
	v_pk_fma_f32 v[190:191], v[150:151], v[198:199], v[190:191]
	s_waitcnt lgkmcnt(1)
	v_pk_fma_f32 v[174:175], v[136:137], v[200:201], v[174:175]
	v_pk_fma_f32 v[190:191], v[152:153], v[200:201], v[190:191]
	v_pk_fma_f32 v[174:175], v[138:139], v[202:203], v[174:175]
	v_pk_fma_f32 v[190:191], v[154:155], v[202:203], v[190:191]
	s_waitcnt lgkmcnt(0)
	v_pk_fma_f32 v[174:175], v[140:141], v[204:205], v[174:175]
	v_pk_fma_f32 v[190:191], v[156:157], v[204:205], v[190:191]
	v_pk_fma_f32 v[174:175], v[142:143], v[206:207], v[174:175]
	v_pk_fma_f32 v[190:191], v[158:159], v[206:207], v[190:191]
	v_add_f32_e32 v160, v160, v161
	v_add_f32_e32 v176, v176, v177
	v_add_f32_e32 v162, v162, v163
	v_add_f32_e32 v178, v178, v179
	v_add_f32_e32 v164, v164, v165
	v_add_f32_e32 v180, v180, v181
	v_add_f32_e32 v166, v166, v167
	v_add_f32_e32 v182, v182, v183
	v_add_f32_e32 v168, v168, v169
	v_add_f32_e32 v184, v184, v185
	v_add_f32_e32 v170, v170, v171
	v_add_f32_e32 v186, v186, v187
	v_add_f32_e32 v172, v172, v173
	v_add_f32_e32 v188, v188, v189
	v_add_f32_e32 v174, v174, v175
	v_add_f32_e32 v190, v190, v191
	v_cndmask_b32_e64 v216, v160, v168, s[38:39]
	v_cndmask_b32_e64 v217, v168, v160, s[38:39]
	v_cndmask_b32_e64 v224, v176, v184, s[38:39]
	v_cndmask_b32_e64 v225, v184, v176, s[38:39]
	v_cndmask_b32_e64 v218, v162, v170, s[38:39]
	v_cndmask_b32_e64 v219, v170, v162, s[38:39]
	v_cndmask_b32_e64 v226, v178, v186, s[38:39]
	v_cndmask_b32_e64 v227, v186, v178, s[38:39]
	v_cndmask_b32_e64 v220, v164, v172, s[38:39]
	v_cndmask_b32_e64 v221, v172, v164, s[38:39]
	v_cndmask_b32_e64 v228, v180, v188, s[38:39]
	v_cndmask_b32_e64 v229, v188, v180, s[38:39]
	v_cndmask_b32_e64 v222, v166, v174, s[38:39]
	v_cndmask_b32_e64 v223, v174, v166, s[38:39]
	v_cndmask_b32_e64 v230, v182, v190, s[38:39]
	v_cndmask_b32_e64 v231, v190, v182, s[38:39]
	s_nop 0
	v_add_f32_dpp v160, v217, v216 quad_perm:[1,0,3,2] row_mask:0xf bank_mask:0xf
	v_add_f32_dpp v176, v225, v224 quad_perm:[1,0,3,2] row_mask:0xf bank_mask:0xf
	v_add_f32_dpp v162, v219, v218 quad_perm:[1,0,3,2] row_mask:0xf bank_mask:0xf
	v_add_f32_dpp v178, v227, v226 quad_perm:[1,0,3,2] row_mask:0xf bank_mask:0xf
	v_add_f32_dpp v164, v221, v220 quad_perm:[1,0,3,2] row_mask:0xf bank_mask:0xf
	v_add_f32_dpp v180, v229, v228 quad_perm:[1,0,3,2] row_mask:0xf bank_mask:0xf
	v_add_f32_dpp v166, v223, v222 quad_perm:[1,0,3,2] row_mask:0xf bank_mask:0xf
	v_add_f32_dpp v182, v231, v230 quad_perm:[1,0,3,2] row_mask:0xf bank_mask:0xf
	v_cndmask_b32_e64 v216, v160, v164, s[40:41]
	v_cndmask_b32_e64 v217, v164, v160, s[40:41]
	v_cndmask_b32_e64 v224, v176, v180, s[40:41]
	v_cndmask_b32_e64 v225, v180, v176, s[40:41]
	v_cndmask_b32_e64 v218, v162, v166, s[40:41]
	v_cndmask_b32_e64 v219, v166, v162, s[40:41]
	v_cndmask_b32_e64 v226, v178, v182, s[40:41]
	v_cndmask_b32_e64 v227, v182, v178, s[40:41]
	s_nop 0
	v_add_f32_dpp v160, v217, v216 quad_perm:[2,3,0,1] row_mask:0xf bank_mask:0xf
	v_add_f32_dpp v176, v225, v224 quad_perm:[2,3,0,1] row_mask:0xf bank_mask:0xf
	v_add_f32_dpp v162, v219, v218 quad_perm:[2,3,0,1] row_mask:0xf bank_mask:0xf
	v_add_f32_dpp v178, v227, v226 quad_perm:[2,3,0,1] row_mask:0xf bank_mask:0xf
	v_cndmask_b32_e64 v216, v160, v162, s[42:43]
	v_cndmask_b32_e64 v217, v162, v160, s[42:43]
	v_cndmask_b32_e64 v224, v176, v178, s[42:43]
	v_cndmask_b32_e64 v225, v178, v176, s[42:43]
	s_nop 0
	v_add_f32_dpp v160, v217, v216 row_shl:4 row_mask:0xf bank_mask:0x5
	v_add_f32_dpp v160, v217, v216 row_shr:4 row_mask:0xf bank_mask:0xa
	v_add_f32_dpp v176, v225, v224 row_shl:4 row_mask:0xf bank_mask:0x5
	v_add_f32_dpp v176, v225, v224 row_shr:4 row_mask:0xf bank_mask:0xa
	s_nop 1
	v_add_f32_dpp v160, v160, v160 row_ror:8 row_mask:0xf bank_mask:0xf
	v_add_f32_dpp v176, v176, v176 row_ror:8 row_mask:0xf bank_mask:0xf
	s_nop 0
	ds_bpermute_b32 v161, v5, v160
	ds_bpermute_b32 v177, v5, v176
	s_waitcnt lgkmcnt(0)
; template <bool WITH_DT, bool OUT8> __device__ __forceinline__ void norm_mod_rows(const void* xp, bool pb16, const void* xs, bool sb16, const float* w, const float* MOD, int ish, int isc, bf16* H, ...
;     ...
;         for (int j = 0; j < 4; ++j) s += (v[j][0] * v[j][0] + v[j][1] * v[j][1]) + (v[j][2] * v[j][2] + v[j][3] * v[j][3]);
;         const float rstd = rsqrtf(wave_sum(s) * (1.0f / DM) + EPSN);
;         const f32x4* sh = (const f32x4*)(MOD + (size_t)mb * 9216 + ish * 1024); const f32x4* sc = (const f32x4*)(MOD + (size_t)mb * 9216 + isc * 1024);
; #pragma unroll
;         for (int j = 0; j < 4; ++j) { const f32x4 a = v[j] * rstd * wv[j]; v[j] = a * (sc[lane + 64 * j] + 1.0f) + sh[lane + 64 * j];
;     ...
;             float e4[4], e2[2], e1;
;             { const bool up = (lane & 32) != 0;
; #pragma unroll
;               for (int c = 0; c < 4; ++c) { const float keep = up ? d[4 + c] : d[c], give = up ? d[c] : d[4 + c]; e4[c] = keep + __shfl_xor(give, 32); } }
;             { const bool up = (lane & 16) != 0;
; #pragma unroll
;               for (int c = 0; c < 2; ++c) { const float keep = up ? e4[2 + c] : e4[c], give = up ? e4[c] : e4[2 + c]; e2[c] = keep + __shfl_xor(give, 16); } }
;             { const bool up = (lane & 8) != 0; const float keep = up ? e2[1] : e2[0], give = up ? e2[0] : e2[1]; e1 = keep + __shfl_xor(give, 8); }
;             e1 += __shfl_xor(e1, 4); e1 += __shfl_xor(e1, 2); e1 += __shfl_xor(e1, 1);
;             const int col = ((lane >> 5) & 1) * 4 + ((lane >> 4) & 1) * 2 + ((lane >> 3) & 1);
;             if ((lane & 7) == 0) { const float p = e1 + dt_bias[col]; DT[(size_t)row * 8 + col] = fmaxf(p, 0.f) + log1pf(__expf(-fabsf(p))); }
	v_add_f32_e32 v160, v160, v161
	v_add_f32_e32 v176, v176, v177
	v_mov_b32_e32 v161, v160
	v_mov_b32_e32 v177, v176
	s_nop 1
	v_permlane32_swap_b32_e32 v160, v161
	v_permlane32_swap_b32_e32 v176, v177
	v_add_f32_e32 v160, v160, v161
	v_add_f32_e32 v176, v176, v177
	v_add_f32_e32 v160, v160, v12
	v_add_f32_e32 v176, v176, v12
	v_and_b32_e32 v216, 0x7fffffff, v160
	v_and_b32_e32 v224, 0x7fffffff, v176
	v_mul_f32_e32 v216, 0xbfb8aa3b, v216
	v_mul_f32_e32 v224, 0xbfb8aa3b, v224
	v_exp_f32_e32 v216, v216
	v_exp_f32_e32 v224, v224
	s_nop 0
	v_add_f32_e32 v217, 1.0, v216
	v_add_f32_e32 v225, 1.0, v224
	v_log_f32_e32 v218, v217
	v_log_f32_e32 v226, v225
	v_add_f32_e32 v219, -1.0, v217
	v_add_f32_e32 v227, -1.0, v225
	v_rcp_f32_e32 v219, v219
	v_rcp_f32_e32 v227, v227
	v_mul_f32_e32 v218, 0x3f317218, v218
	v_mul_f32_e32 v226, 0x3f317218, v226
	v_mul_f32_e32 v219, v216, v219
	v_mul_f32_e32 v227, v224, v227
	v_mul_f32_e32 v218, v218, v219
	v_mul_f32_e32 v226, v226, v227
	v_cmp_eq_f32_e32 vcc, 1.0, v217
	s_nop 1
	v_cndmask_b32_e32 v218, v218, v216, vcc
	v_cmp_eq_f32_e32 vcc, 1.0, v225
	s_nop 1
	v_cndmask_b32_e32 v226, v226, v224, vcc
	v_max_f32_e32 v160, 0, v160
	v_max_f32_e32 v176, 0, v176
	v_add_f32_e32 v160, v160, v218
	v_add_f32_e32 v176, v176, v226
	v_cndmask_b32_e64 v160, v160, v176, s[44:45]
	s_mov_b64 exec, 0xffff
	global_store_dword v4, v160, s[28:29]
	s_mov_b64 exec, -1
	s_add_u32 s28, s28, 64
	s_addc_u32 s29, s29, 0
	s_waitcnt vmcnt(52)
	v_lshlrev_b32_e32 v128, 16, v80
	v_and_b32_e32 v129, 0xffff0000, v80
	v_lshlrev_b32_e32 v130, 16, v81
	v_and_b32_e32 v131, 0xffff0000, v81
	v_lshlrev_b32_e32 v132, 16, v82
	v_and_b32_e32 v133, 0xffff0000, v82
	v_lshlrev_b32_e32 v134, 16, v83
	v_and_b32_e32 v135, 0xffff0000, v83
	v_lshlrev_b32_e32 v136, 16, v84
	v_and_b32_e32 v137, 0xffff0000, v84
	v_lshlrev_b32_e32 v138, 16, v85
	v_and_b32_e32 v139, 0xffff0000, v85
	v_lshlrev_b32_e32 v140, 16, v86
	v_and_b32_e32 v141, 0xffff0000, v86
	v_lshlrev_b32_e32 v142, 16, v87
	v_and_b32_e32 v143, 0xffff0000, v87
	v_lshlrev_b32_e32 v144, 16, v88
	v_and_b32_e32 v145, 0xffff0000, v88
	v_lshlrev_b32_e32 v146, 16, v89
	v_and_b32_e32 v147, 0xffff0000, v89
	v_lshlrev_b32_e32 v148, 16, v90
	v_and_b32_e32 v149, 0xffff0000, v90
	v_lshlrev_b32_e32 v150, 16, v91
	v_and_b32_e32 v151, 0xffff0000, v91
	v_lshlrev_b32_e32 v152, 16, v92
	v_and_b32_e32 v153, 0xffff0000, v92
	v_lshlrev_b32_e32 v154, 16, v93
	v_and_b32_e32 v155, 0xffff0000, v93
	v_lshlrev_b32_e32 v156, 16, v94
	v_and_b32_e32 v157, 0xffff0000, v94
	v_lshlrev_b32_e32 v158, 16, v95
	v_and_b32_e32 v159, 0xffff0000, v95
	v_pk_mul_f32 v[208:209], v[128:129], v[128:129]
	v_pk_mul_f32 v[210:211], v[130:131], v[130:131]
	v_pk_mul_f32 v[212:213], v[144:145], v[144:145]
	v_pk_mul_f32 v[214:215], v[146:147], v[146:147]
	v_pk_fma_f32 v[208:209], v[132:133], v[132:133], v[208:209]
	v_pk_fma_f32 v[210:211], v[134:135], v[134:135], v[210:211]
	v_pk_fma_f32 v[212:213], v[148:149], v[148:149], v[212:213]
	v_pk_fma_f32 v[214:215], v[150:151], v[150:151], v[214:215]
	v_pk_fma_f32 v[208:209], v[136:137], v[136:137], v[208:209]
	v_pk_fma_f32 v[210:211], v[138:139], v[138:139], v[210:211]
	v_pk_fma_f32 v[212:213], v[152:153], v[152:153], v[212:213]
	v_pk_fma_f32 v[214:215], v[154:155], v[154:155], v[214:215]
	v_pk_fma_f32 v[208:209], v[140:141], v[140:141], v[208:209]
	v_pk_fma_f32 v[210:211], v[142:143], v[142:143], v[210:211]
	v_pk_fma_f32 v[212:213], v[156:157], v[156:157], v[212:213]
	v_pk_fma_f32 v[214:215], v[158:159], v[158:159], v[214:215]
	v_pk_add_f32 v[208:209], v[208:209], v[210:211]
	v_pk_add_f32 v[212:213], v[212:213], v[214:215]
	v_add_f32_e32 v208, v208, v209
	v_add_f32_e32 v212, v212, v213
	s_nop 0
	v_add_f32_dpp v208, v208, v208 quad_perm:[1,0,3,2] row_mask:0xf bank_mask:0xf
	v_add_f32_dpp v212, v212, v212 quad_perm:[1,0,3,2] row_mask:0xf bank_mask:0xf
	s_nop 0
	v_add_f32_dpp v208, v208, v208 quad_perm:[2,3,0,1] row_mask:0xf bank_mask:0xf
	v_add_f32_dpp v212, v212, v212 quad_perm:[2,3,0,1] row_mask:0xf bank_mask:0xf
	s_nop 0
	v_add_f32_dpp v208, v208, v208 row_half_mirror row_mask:0xf bank_mask:0xf
	v_add_f32_dpp v212, v212, v212 row_half_mirror row_mask:0xf bank_mask:0xf
	s_nop 0
	v_add_f32_dpp v208, v208, v208 row_mirror row_mask:0xf bank_mask:0xf
	v_add_f32_dpp v212, v212, v212 row_mirror row_mask:0xf bank_mask:0xf
	s_nop 0
	v_readlane_b32 s30, v208, 0
	v_readlane_b32 s31, v208, 16
	v_readlane_b32 s32, v208, 32
	v_readlane_b32 s33, v208, 48
	v_readlane_b32 s34, v212, 0
	v_readlane_b32 s35, v212, 16
	v_readlane_b32 s36, v212, 32
	v_readlane_b32 s37, v212, 48
	s_nop 1
	v_mov_b32_e32 v209, s30
	v_mov_b32_e32 v213, s34
	v_add_f32_e32 v209, s31, v209
	v_add_f32_e32 v213, s35, v213
	v_add_f32_e32 v209, s32, v209
	v_add_f32_e32 v213, s36, v213
	v_add_f32_e32 v209, s33, v209
	v_add_f32_e32 v213, s37, v213
	v_fmamk_f32 v209, v209, 0x3a800000, v8
	v_fmamk_f32 v213, v213, 0x3a800000, v8
	v_rsq_f32_e32 v210, v209
	v_rsq_f32_e32 v214, v213
	s_nop 0
	v_pk_mul_f32 v[128:129], v[128:129], v[210:211] op_sel_hi:[1,0]
	v_pk_mul_f32 v[130:131], v[130:131], v[210:211] op_sel_hi:[1,0]
	v_pk_mul_f32 v[132:133], v[132:133], v[210:211] op_sel_hi:[1,0]
	v_pk_mul_f32 v[134:135], v[134:135], v[210:211] op_sel_hi:[1,0]
	v_pk_mul_f32 v[136:137], v[136:137], v[210:211] op_sel_hi:[1,0]
	v_pk_mul_f32 v[138:139], v[138:139], v[210:211] op_sel_hi:[1,0]
	v_pk_mul_f32 v[140:141], v[140:141], v[210:211] op_sel_hi:[1,0]
	v_pk_mul_f32 v[142:143], v[142:143], v[210:211] op_sel_hi:[1,0]
	v_pk_mul_f32 v[144:145], v[144:145], v[214:215] op_sel_hi:[1,0]
	v_pk_mul_f32 v[146:147], v[146:147], v[214:215] op_sel_hi:[1,0]
	v_pk_mul_f32 v[148:149], v[148:149], v[214:215] op_sel_hi:[1,0]
; __device__ __forceinline__ unsigned pk2(float lo, float hi) { return pg8::cvt_pk_bf16(lo, hi); }
; template <bool WITH_DT, bool OUT8> __device__ __forceinline__ void norm_mod_rows(const void* xp, bool pb16, const void* xs, bool sb16, const float* w, const float* MOD, int ish, int isc, bf16* H, ...
;     ...
;         for (int j = 0; j < 4; ++j) { const f32x4 a = v[j] * rstd * wv[j]; v[j] = a * (sc[lane + 64 * j] + 1.0f) + sh[lane + 64 * j];
;             if (OUT8) { *(unsigned*)((unsigned char*)H + (size_t)row * DM + 4 * (lane + 64 * j)) = pk4_fp8(v[j][0] * SC_H8, v[j][1] * SC_H8, v[j][2] * SC_H8, v[j][3] * SC_H8); }
;             else { v2u o; o.x = pk2(v[j][0], v[j][1]); o.y = pk2(v[j][2], v[j][3]); *(v2u*)(H + (size_t)row * DM + 4 * (lane + 64 * j)) = o; } }
;         if (WITH_DT) {
;             float d[8];
; #pragma unroll
;             for (int c = 0; c < 8; ++c) { float p = 0.f;
; #pragma unroll
;                 for (int j = 0; j < 4; ++j) { const f32x4 ww = wdt[WITH_DT ? c : 0][j]; p += (v[j][0] * ww[0] + v[j][1] * ww[1]) + (v[j][2] * ww[2] + v[j][3] * ww[3]); }
;                 d[c] = p; }
	v_pk_mul_f32 v[150:151], v[150:151], v[214:215] op_sel_hi:[1,0]
	v_pk_mul_f32 v[152:153], v[152:153], v[214:215] op_sel_hi:[1,0]
	v_pk_mul_f32 v[154:155], v[154:155], v[214:215] op_sel_hi:[1,0]
	v_pk_mul_f32 v[156:157], v[156:157], v[214:215] op_sel_hi:[1,0]
	v_pk_mul_f32 v[158:159], v[158:159], v[214:215] op_sel_hi:[1,0]
	v_pk_fma_f32 v[128:129], v[128:129], v[16:17], v[32:33]
	v_pk_fma_f32 v[130:131], v[130:131], v[18:19], v[34:35]
	v_pk_fma_f32 v[132:133], v[132:133], v[20:21], v[36:37]
	v_pk_fma_f32 v[134:135], v[134:135], v[22:23], v[38:39]
	v_pk_fma_f32 v[136:137], v[136:137], v[24:25], v[40:41]
	v_pk_fma_f32 v[138:139], v[138:139], v[26:27], v[42:43]
	v_pk_fma_f32 v[140:141], v[140:141], v[28:29], v[44:45]
	v_pk_fma_f32 v[142:143], v[142:143], v[30:31], v[46:47]
	v_pk_fma_f32 v[144:145], v[144:145], v[16:17], v[32:33]
	v_pk_fma_f32 v[146:147], v[146:147], v[18:19], v[34:35]
	v_pk_fma_f32 v[148:149], v[148:149], v[20:21], v[36:37]
	v_pk_fma_f32 v[150:151], v[150:151], v[22:23], v[38:39]
	v_pk_fma_f32 v[152:153], v[152:153], v[24:25], v[40:41]
	v_pk_fma_f32 v[154:155], v[154:155], v[26:27], v[42:43]
	v_pk_fma_f32 v[156:157], v[156:157], v[28:29], v[44:45]
	v_pk_fma_f32 v[158:159], v[158:159], v[30:31], v[46:47]
	v_cvt_pk_bf16_f32 v216, v128, v129
	v_cvt_pk_bf16_f32 v217, v130, v131
	v_cvt_pk_bf16_f32 v218, v132, v133
	v_cvt_pk_bf16_f32 v219, v134, v135
	v_cvt_pk_bf16_f32 v220, v136, v137
	v_cvt_pk_bf16_f32 v221, v138, v139
	v_cvt_pk_bf16_f32 v222, v140, v141
	v_cvt_pk_bf16_f32 v223, v142, v143
	v_cvt_pk_bf16_f32 v224, v144, v145
	v_cvt_pk_bf16_f32 v225, v146, v147
	v_cvt_pk_bf16_f32 v226, v148, v149
	v_cvt_pk_bf16_f32 v227, v150, v151
	v_cvt_pk_bf16_f32 v228, v152, v153
	v_cvt_pk_bf16_f32 v229, v154, v155
	v_cvt_pk_bf16_f32 v230, v156, v157
	v_cvt_pk_bf16_f32 v231, v158, v159
	global_store_dwordx2 v2, v[216:217], s[20:21]
	global_store_dwordx2 v2, v[218:219], s[20:21] offset:512
	global_store_dwordx2 v2, v[220:221], s[20:21] offset:1024
	global_store_dwordx2 v2, v[222:223], s[20:21] offset:1536
	global_store_dwordx2 v2, v[224:225], s[20:21] offset:2048
	global_store_dwordx2 v2, v[226:227], s[20:21] offset:2560
	global_store_dwordx2 v2, v[228:229], s[20:21] offset:3072
	global_store_dwordx2 v2, v[230:231], s[20:21] offset:3584
	s_add_u32 s20, s20, 0x1000
	s_addc_u32 s21, s21, 0
	ds_read_b128 v[192:195], v3 offset:0
	ds_read_b128 v[196:199], v3 offset:1024
	ds_read_b128 v[200:203], v3 offset:2048
	ds_read_b128 v[204:207], v3 offset:3072
	s_waitcnt lgkmcnt(3)
	v_pk_mul_f32 v[160:161], v[128:129], v[192:193]
	v_pk_mul_f32 v[176:177], v[144:145], v[192:193]
	v_pk_fma_f32 v[160:161], v[130:131], v[194:195], v[160:161]
	v_pk_fma_f32 v[176:177], v[146:147], v[194:195], v[176:177]
	ds_read_b128 v[192:195], v3 offset:4096
	s_waitcnt lgkmcnt(3)
	v_pk_fma_f32 v[160:161], v[132:133], v[196:197], v[160:161]
	v_pk_fma_f32 v[176:177], v[148:149], v[196:197], v[176:177]
	v_pk_fma_f32 v[160:161], v[134:135], v[198:199], v[160:161]
	v_pk_fma_f32 v[176:177], v[150:151], v[198:199], v[176:177]
	ds_read_b128 v[196:199], v3 offset:5120
	s_waitcnt lgkmcnt(3)
	v_pk_fma_f32 v[160:161], v[136:137], v[200:201], v[160:161]
	v_pk_fma_f32 v[176:177], v[152:153], v[200:201], v[176:177]
	v_pk_fma_f32 v[160:161], v[138:139], v[202:203], v[160:161]
	v_pk_fma_f32 v[176:177], v[154:155], v[202:203], v[176:177]
	ds_read_b128 v[200:203], v3 offset:6144
	s_waitcnt lgkmcnt(3)
	v_pk_fma_f32 v[160:161], v[140:141], v[204:205], v[160:161]
	v_pk_fma_f32 v[176:177], v[156:157], v[204:205], v[176:177]
	v_pk_fma_f32 v[160:161], v[142:143], v[206:207], v[160:161]
	v_pk_fma_f32 v[176:177], v[158:159], v[206:207], v[176:177]
	ds_read_b128 v[204:207], v3 offset:7168
	s_waitcnt lgkmcnt(3)
	v_pk_mul_f32 v[162:163], v[128:129], v[192:193]
	v_pk_mul_f32 v[178:179], v[144:145], v[192:193]
	v_pk_fma_f32 v[162:163], v[130:131], v[194:195], v[162:163]
	v_pk_fma_f32 v[178:179], v[146:147], v[194:195], v[178:179]
	ds_read_b128 v[192:195], v3 offset:8192
	s_waitcnt lgkmcnt(3)
	v_pk_fma_f32 v[162:163], v[132:133], v[196:197], v[162:163]
	v_pk_fma_f32 v[178:179], v[148:149], v[196:197], v[178:179]
	v_pk_fma_f32 v[162:163], v[134:135], v[198:199], v[162:163]
	v_pk_fma_f32 v[178:179], v[150:151], v[198:199], v[178:179]
	ds_read_b128 v[196:199], v3 offset:9216
	s_waitcnt lgkmcnt(3)
	v_pk_fma_f32 v[162:163], v[136:137], v[200:201], v[162:163]
	v_pk_fma_f32 v[178:179], v[152:153], v[200:201], v[178:179]
	v_pk_fma_f32 v[162:163], v[138:139], v[202:203], v[162:163]
	v_pk_fma_f32 v[178:179], v[154:155], v[202:203], v[178:179]
	ds_read_b128 v[200:203], v3 offset:10240
	s_waitcnt lgkmcnt(3)
	v_pk_fma_f32 v[162:163], v[140:141], v[204:205], v[162:163]
	v_pk_fma_f32 v[178:179], v[156:157], v[204:205], v[178:179]
	v_pk_fma_f32 v[162:163], v[142:143], v[206:207], v[162:163]
	v_pk_fma_f32 v[178:179], v[158:159], v[206:207], v[178:179]
	ds_read_b128 v[204:207], v3 offset:11264
	s_waitcnt lgkmcnt(3)
	v_pk_mul_f32 v[164:165], v[128:129], v[192:193]
	v_pk_mul_f32 v[180:181], v[144:145], v[192:193]
	v_pk_fma_f32 v[164:165], v[130:131], v[194:195], v[164:165]
	v_pk_fma_f32 v[180:181], v[146:147], v[194:195], v[180:181]
	ds_read_b128 v[192:195], v3 offset:12288
	s_waitcnt lgkmcnt(3)
	v_pk_fma_f32 v[164:165], v[132:133], v[196:197], v[164:165]
	v_pk_fma_f32 v[180:181], v[148:149], v[196:197], v[180:181]
	v_pk_fma_f32 v[164:165], v[134:135], v[198:199], v[164:165]
	v_pk_fma_f32 v[180:181], v[150:151], v[198:199], v[180:181]
	ds_read_b128 v[196:199], v3 offset:13312
	s_waitcnt lgkmcnt(3)
; template <bool WITH_DT, bool OUT8> __device__ __forceinline__ void norm_mod_rows(const void* xp, bool pb16, const void* xs, bool sb16, const float* w, const float* MOD, int ish, int isc, bf16* H, ...
;     ...
;             for (int c = 0; c < 8; ++c) { float p = 0.f;
; #pragma unroll
;                 for (int j = 0; j < 4; ++j) { const f32x4 ww = wdt[WITH_DT ? c : 0][j]; p += (v[j][0] * ww[0] + v[j][1] * ww[1]) + (v[j][2] * ww[2] + v[j][3] * ww[3]); }
;                 d[c] = p; }
	v_pk_fma_f32 v[164:165], v[136:137], v[200:201], v[164:165]
	v_pk_fma_f32 v[180:181], v[152:153], v[200:201], v[180:181]
	v_pk_fma_f32 v[164:165], v[138:139], v[202:203], v[164:165]
	v_pk_fma_f32 v[180:181], v[154:155], v[202:203], v[180:181]
	ds_read_b128 v[200:203], v3 offset:14336
	s_waitcnt lgkmcnt(3)
	v_pk_fma_f32 v[164:165], v[140:141], v[204:205], v[164:165]
	v_pk_fma_f32 v[180:181], v[156:157], v[204:205], v[180:181]
	v_pk_fma_f32 v[164:165], v[142:143], v[206:207], v[164:165]
	v_pk_fma_f32 v[180:181], v[158:159], v[206:207], v[180:181]
	ds_read_b128 v[204:207], v3 offset:15360
	s_waitcnt lgkmcnt(3)
	v_pk_mul_f32 v[166:167], v[128:129], v[192:193]
	v_pk_mul_f32 v[182:183], v[144:145], v[192:193]
	v_pk_fma_f32 v[166:167], v[130:131], v[194:195], v[166:167]
	v_pk_fma_f32 v[182:183], v[146:147], v[194:195], v[182:183]
	ds_read_b128 v[192:195], v3 offset:16384
	s_waitcnt lgkmcnt(3)
	v_pk_fma_f32 v[166:167], v[132:133], v[196:197], v[166:167]
	v_pk_fma_f32 v[182:183], v[148:149], v[196:197], v[182:183]
	v_pk_fma_f32 v[166:167], v[134:135], v[198:199], v[166:167]
	v_pk_fma_f32 v[182:183], v[150:151], v[198:199], v[182:183]
	ds_read_b128 v[196:199], v3 offset:17408
	s_waitcnt lgkmcnt(3)
	v_pk_fma_f32 v[166:167], v[136:137], v[200:201], v[166:167]
	v_pk_fma_f32 v[182:183], v[152:153], v[200:201], v[182:183]
	v_pk_fma_f32 v[166:167], v[138:139], v[202:203], v[166:167]
	v_pk_fma_f32 v[182:183], v[154:155], v[202:203], v[182:183]
	ds_read_b128 v[200:203], v3 offset:18432
	s_waitcnt lgkmcnt(3)
	v_pk_fma_f32 v[166:167], v[140:141], v[204:205], v[166:167]
	v_pk_fma_f32 v[182:183], v[156:157], v[204:205], v[182:183]
	v_pk_fma_f32 v[166:167], v[142:143], v[206:207], v[166:167]
	v_pk_fma_f32 v[182:183], v[158:159], v[206:207], v[182:183]
	ds_read_b128 v[204:207], v3 offset:19456
	s_waitcnt lgkmcnt(3)
	v_pk_mul_f32 v[168:169], v[128:129], v[192:193]
	v_pk_mul_f32 v[184:185], v[144:145], v[192:193]
	v_pk_fma_f32 v[168:169], v[130:131], v[194:195], v[168:169]
	v_pk_fma_f32 v[184:185], v[146:147], v[194:195], v[184:185]
	ds_read_b128 v[192:195], v3 offset:20480
	s_waitcnt lgkmcnt(3)
	v_pk_fma_f32 v[168:169], v[132:133], v[196:197], v[168:169]
	v_pk_fma_f32 v[184:185], v[148:149], v[196:197], v[184:185]
	v_pk_fma_f32 v[168:169], v[134:135], v[198:199], v[168:169]
	v_pk_fma_f32 v[184:185], v[150:151], v[198:199], v[184:185]
	ds_read_b128 v[196:199], v3 offset:21504
	s_waitcnt lgkmcnt(3)
	v_pk_fma_f32 v[168:169], v[136:137], v[200:201], v[168:169]
	v_pk_fma_f32 v[184:185], v[152:153], v[200:201], v[184:185]
	v_pk_fma_f32 v[168:169], v[138:139], v[202:203], v[168:169]
	v_pk_fma_f32 v[184:185], v[154:155], v[202:203], v[184:185]
	ds_read_b128 v[200:203], v3 offset:22528
	s_waitcnt lgkmcnt(3)
	v_pk_fma_f32 v[168:169], v[140:141], v[204:205], v[168:169]
	v_pk_fma_f32 v[184:185], v[156:157], v[204:205], v[184:185]
	v_pk_fma_f32 v[168:169], v[142:143], v[206:207], v[168:169]
	v_pk_fma_f32 v[184:185], v[158:159], v[206:207], v[184:185]
	ds_read_b128 v[204:207], v3 offset:23552
	s_waitcnt lgkmcnt(3)
	v_pk_mul_f32 v[170:171], v[128:129], v[192:193]
	v_pk_mul_f32 v[186:187], v[144:145], v[192:193]
	v_pk_fma_f32 v[170:171], v[130:131], v[194:195], v[170:171]
	v_pk_fma_f32 v[186:187], v[146:147], v[194:195], v[186:187]
	ds_read_b128 v[192:195], v3 offset:24576
	s_waitcnt lgkmcnt(3)
	v_pk_fma_f32 v[170:171], v[132:133], v[196:197], v[170:171]
	v_pk_fma_f32 v[186:187], v[148:149], v[196:197], v[186:187]
	v_pk_fma_f32 v[170:171], v[134:135], v[198:199], v[170:171]
	v_pk_fma_f32 v[186:187], v[150:151], v[198:199], v[186:187]
	ds_read_b128 v[196:199], v3 offset:25600
	s_waitcnt lgkmcnt(3)
	v_pk_fma_f32 v[170:171], v[136:137], v[200:201], v[170:171]
	v_pk_fma_f32 v[186:187], v[152:153], v[200:201], v[186:187]
	v_pk_fma_f32 v[170:171], v[138:139], v[202:203], v[170:171]
	v_pk_fma_f32 v[186:187], v[154:155], v[202:203], v[186:187]
	ds_read_b128 v[200:203], v3 offset:26624
	s_waitcnt lgkmcnt(3)
	v_pk_fma_f32 v[170:171], v[140:141], v[204:205], v[170:171]
	v_pk_fma_f32 v[186:187], v[156:157], v[204:205], v[186:187]
	v_pk_fma_f32 v[170:171], v[142:143], v[206:207], v[170:171]
	v_pk_fma_f32 v[186:187], v[158:159], v[206:207], v[186:187]
	ds_read_b128 v[204:207], v3 offset:27648
	s_waitcnt lgkmcnt(3)
	v_pk_mul_f32 v[172:173], v[128:129], v[192:193]
	v_pk_mul_f32 v[188:189], v[144:145], v[192:193]
	v_pk_fma_f32 v[172:173], v[130:131], v[194:195], v[172:173]
	v_pk_fma_f32 v[188:189], v[146:147], v[194:195], v[188:189]
	ds_read_b128 v[192:195], v3 offset:28672
	s_waitcnt lgkmcnt(3)
	v_pk_fma_f32 v[172:173], v[132:133], v[196:197], v[172:173]
	v_pk_fma_f32 v[188:189], v[148:149], v[196:197], v[188:189]
	v_pk_fma_f32 v[172:173], v[134:135], v[198:199], v[172:173]
	v_pk_fma_f32 v[188:189], v[150:151], v[198:199], v[188:189]
	ds_read_b128 v[196:199], v3 offset:29696
	s_waitcnt lgkmcnt(3)
	v_pk_fma_f32 v[172:173], v[136:137], v[200:201], v[172:173]
	v_pk_fma_f32 v[188:189], v[152:153], v[200:201], v[188:189]
	v_pk_fma_f32 v[172:173], v[138:139], v[202:203], v[172:173]
	v_pk_fma_f32 v[188:189], v[154:155], v[202:203], v[188:189]
	ds_read_b128 v[200:203], v3 offset:30720
	s_waitcnt lgkmcnt(3)
	v_pk_fma_f32 v[172:173], v[140:141], v[204:205], v[172:173]
	v_pk_fma_f32 v[188:189], v[156:157], v[204:205], v[188:189]
	v_pk_fma_f32 v[172:173], v[142:143], v[206:207], v[172:173]
	v_pk_fma_f32 v[188:189], v[158:159], v[206:207], v[188:189]
	ds_read_b128 v[204:207], v3 offset:31744
	s_waitcnt lgkmcnt(3)
	v_pk_mul_f32 v[174:175], v[128:129], v[192:193]
	v_pk_mul_f32 v[190:191], v[144:145], v[192:193]
	v_pk_fma_f32 v[174:175], v[130:131], v[194:195], v[174:175]
	v_pk_fma_f32 v[190:191], v[146:147], v[194:195], v[190:191]
	s_waitcnt lgkmcnt(2)
; template <bool WITH_DT, bool OUT8> __device__ __forceinline__ void norm_mod_rows(const void* xp, bool pb16, const void* xs, bool sb16, const float* w, const float* MOD, int ish, int isc, bf16* H, ...
;     ...
;             float e4[4], e2[2], e1;
;             { const bool up = (lane & 32) != 0;
; #pragma unroll
;               for (int c = 0; c < 4; ++c) { const float keep = up ? d[4 + c] : d[c], give = up ? d[c] : d[4 + c]; e4[c] = keep + __shfl_xor(give, 32); } }
;             { const bool up = (lane & 16) != 0;
; #pragma unroll
;               for (int c = 0; c < 2; ++c) { const float keep = up ? e4[2 + c] : e4[c], give = up ? e4[c] : e4[2 + c]; e2[c] = keep + __shfl_xor(give, 16); } }
;             { const bool up = (lane & 8) != 0; const float keep = up ? e2[1] : e2[0], give = up ? e2[0] : e2[1]; e1 = keep + __shfl_xor(give, 8); }
;             e1 += __shfl_xor(e1, 4); e1 += __shfl_xor(e1, 2); e1 += __shfl_xor(e1, 1);
;             const int col = ((lane >> 5) & 1) * 4 + ((lane >> 4) & 1) * 2 + ((lane >> 3) & 1);
;             if ((lane & 7) == 0) { const float p = e1 + dt_bias[col]; DT[(size_t)row * 8 + col] = fmaxf(p, 0.f) + log1pf(__expf(-fabsf(p))); }
	v_pk_fma_f32 v[174:175], v[132:133], v[196:197], v[174:175]
	v_pk_fma_f32 v[190:191], v[148:149], v[196:197], v[190:191]
	v_pk_fma_f32 v[174:175], v[134:135], v[198:199], v[174:175]
	v_pk_fma_f32 v[190:191], v[150:151], v[198:199], v[190:191]
	s_waitcnt lgkmcnt(1)
	v_pk_fma_f32 v[174:175], v[136:137], v[200:201], v[174:175]
	v_pk_fma_f32 v[190:191], v[152:153], v[200:201], v[190:191]
	v_pk_fma_f32 v[174:175], v[138:139], v[202:203], v[174:175]
	v_pk_fma_f32 v[190:191], v[154:155], v[202:203], v[190:191]
	s_waitcnt lgkmcnt(0)
	v_pk_fma_f32 v[174:175], v[140:141], v[204:205], v[174:175]
	v_pk_fma_f32 v[190:191], v[156:157], v[204:205], v[190:191]
	v_pk_fma_f32 v[174:175], v[142:143], v[206:207], v[174:175]
	v_pk_fma_f32 v[190:191], v[158:159], v[206:207], v[190:191]
	v_add_f32_e32 v160, v160, v161
	v_add_f32_e32 v176, v176, v177
	v_add_f32_e32 v162, v162, v163
	v_add_f32_e32 v178, v178, v179
	v_add_f32_e32 v164, v164, v165
	v_add_f32_e32 v180, v180, v181
	v_add_f32_e32 v166, v166, v167
	v_add_f32_e32 v182, v182, v183
	v_add_f32_e32 v168, v168, v169
	v_add_f32_e32 v184, v184, v185
	v_add_f32_e32 v170, v170, v171
	v_add_f32_e32 v186, v186, v187
	v_add_f32_e32 v172, v172, v173
	v_add_f32_e32 v188, v188, v189
	v_add_f32_e32 v174, v174, v175
	v_add_f32_e32 v190, v190, v191
	v_cndmask_b32_e64 v216, v160, v168, s[38:39]
	v_cndmask_b32_e64 v217, v168, v160, s[38:39]
	v_cndmask_b32_e64 v224, v176, v184, s[38:39]
	v_cndmask_b32_e64 v225, v184, v176, s[38:39]
	v_cndmask_b32_e64 v218, v162, v170, s[38:39]
	v_cndmask_b32_e64 v219, v170, v162, s[38:39]
	v_cndmask_b32_e64 v226, v178, v186, s[38:39]
	v_cndmask_b32_e64 v227, v186, v178, s[38:39]
	v_cndmask_b32_e64 v220, v164, v172, s[38:39]
	v_cndmask_b32_e64 v221, v172, v164, s[38:39]
	v_cndmask_b32_e64 v228, v180, v188, s[38:39]
	v_cndmask_b32_e64 v229, v188, v180, s[38:39]
	v_cndmask_b32_e64 v222, v166, v174, s[38:39]
	v_cndmask_b32_e64 v223, v174, v166, s[38:39]
	v_cndmask_b32_e64 v230, v182, v190, s[38:39]
	v_cndmask_b32_e64 v231, v190, v182, s[38:39]
	s_nop 0
	v_add_f32_dpp v160, v217, v216 quad_perm:[1,0,3,2] row_mask:0xf bank_mask:0xf
	v_add_f32_dpp v176, v225, v224 quad_perm:[1,0,3,2] row_mask:0xf bank_mask:0xf
	v_add_f32_dpp v162, v219, v218 quad_perm:[1,0,3,2] row_mask:0xf bank_mask:0xf
	v_add_f32_dpp v178, v227, v226 quad_perm:[1,0,3,2] row_mask:0xf bank_mask:0xf
	v_add_f32_dpp v164, v221, v220 quad_perm:[1,0,3,2] row_mask:0xf bank_mask:0xf
	v_add_f32_dpp v180, v229, v228 quad_perm:[1,0,3,2] row_mask:0xf bank_mask:0xf
	v_add_f32_dpp v166, v223, v222 quad_perm:[1,0,3,2] row_mask:0xf bank_mask:0xf
	v_add_f32_dpp v182, v231, v230 quad_perm:[1,0,3,2] row_mask:0xf bank_mask:0xf
	v_cndmask_b32_e64 v216, v160, v164, s[40:41]
	v_cndmask_b32_e64 v217, v164, v160, s[40:41]
	v_cndmask_b32_e64 v224, v176, v180, s[40:41]
	v_cndmask_b32_e64 v225, v180, v176, s[40:41]
	v_cndmask_b32_e64 v218, v162, v166, s[40:41]
	v_cndmask_b32_e64 v219, v166, v162, s[40:41]
	v_cndmask_b32_e64 v226, v178, v182, s[40:41]
	v_cndmask_b32_e64 v227, v182, v178, s[40:41]
	s_nop 0
	v_add_f32_dpp v160, v217, v216 quad_perm:[2,3,0,1] row_mask:0xf bank_mask:0xf
	v_add_f32_dpp v176, v225, v224 quad_perm:[2,3,0,1] row_mask:0xf bank_mask:0xf
	v_add_f32_dpp v162, v219, v218 quad_perm:[2,3,0,1] row_mask:0xf bank_mask:0xf
	v_add_f32_dpp v178, v227, v226 quad_perm:[2,3,0,1] row_mask:0xf bank_mask:0xf
	v_cndmask_b32_e64 v216, v160, v162, s[42:43]
	v_cndmask_b32_e64 v217, v162, v160, s[42:43]
	v_cndmask_b32_e64 v224, v176, v178, s[42:43]
	v_cndmask_b32_e64 v225, v178, v176, s[42:43]
	s_nop 0
	v_add_f32_dpp v160, v217, v216 row_shl:4 row_mask:0xf bank_mask:0x5
	v_add_f32_dpp v160, v217, v216 row_shr:4 row_mask:0xf bank_mask:0xa
	v_add_f32_dpp v176, v225, v224 row_shl:4 row_mask:0xf bank_mask:0x5
	v_add_f32_dpp v176, v225, v224 row_shr:4 row_mask:0xf bank_mask:0xa
	s_nop 1
	v_add_f32_dpp v160, v160, v160 row_ror:8 row_mask:0xf bank_mask:0xf
	v_add_f32_dpp v176, v176, v176 row_ror:8 row_mask:0xf bank_mask:0xf
	s_nop 0
	ds_bpermute_b32 v161, v5, v160
	ds_bpermute_b32 v177, v5, v176
	s_waitcnt lgkmcnt(0)
	v_add_f32_e32 v160, v160, v161
	v_add_f32_e32 v176, v176, v177
	v_mov_b32_e32 v161, v160
	v_mov_b32_e32 v177, v176
	s_nop 1
	v_permlane32_swap_b32_e32 v160, v161
	v_permlane32_swap_b32_e32 v176, v177
	v_add_f32_e32 v160, v160, v161
	v_add_f32_e32 v176, v176, v177
	v_add_f32_e32 v160, v160, v12
	v_add_f32_e32 v176, v176, v12
	v_and_b32_e32 v216, 0x7fffffff, v160
	v_and_b32_e32 v224, 0x7fffffff, v176
	v_mul_f32_e32 v216, 0xbfb8aa3b, v216
	v_mul_f32_e32 v224, 0xbfb8aa3b, v224
	v_exp_f32_e32 v216, v216
	v_exp_f32_e32 v224, v224
	s_nop 0
	v_add_f32_e32 v217, 1.0, v216
	v_add_f32_e32 v225, 1.0, v224
	v_log_f32_e32 v218, v217
	v_log_f32_e32 v226, v225
	v_add_f32_e32 v219, -1.0, v217
	v_add_f32_e32 v227, -1.0, v225
	v_rcp_f32_e32 v219, v219
	v_rcp_f32_e32 v227, v227
	v_mul_f32_e32 v218, 0x3f317218, v218
	v_mul_f32_e32 v226, 0x3f317218, v226
	v_mul_f32_e32 v219, v216, v219
	v_mul_f32_e32 v227, v224, v227
	v_mul_f32_e32 v218, v218, v219
	v_mul_f32_e32 v226, v226, v227
	v_cmp_eq_f32_e32 vcc, 1.0, v217
	s_nop 1
	v_cndmask_b32_e32 v218, v218, v216, vcc
	v_cmp_eq_f32_e32 vcc, 1.0, v225
	s_nop 1
	v_cndmask_b32_e32 v226, v226, v224, vcc
	v_max_f32_e32 v160, 0, v160
	v_max_f32_e32 v176, 0, v176
	v_add_f32_e32 v160, v160, v218
	v_add_f32_e32 v176, v176, v226
	v_cndmask_b32_e64 v160, v160, v176, s[44:45]
	s_mov_b64 exec, 0xffff
	global_store_dword v4, v160, s[28:29]
	s_mov_b64 exec, -1
	s_add_u32 s28, s28, 64
	s_addc_u32 s29, s29, 0
	s_waitcnt vmcnt(44)
; __device__ __forceinline__ unsigned pk2(float lo, float hi) { return pg8::cvt_pk_bf16(lo, hi); }
; template <bool WITH_DT, bool OUT8> __device__ __forceinline__ void norm_mod_rows(const void* xp, bool pb16, const void* xs, bool sb16, const float* w, const float* MOD, int ish, int isc, bf16* H, ...
;     ...
;         for (int j = 0; j < 4; ++j) s += (v[j][0] * v[j][0] + v[j][1] * v[j][1]) + (v[j][2] * v[j][2] + v[j][3] * v[j][3]);
;         const float rstd = rsqrtf(wave_sum(s) * (1.0f / DM) + EPSN);
;         const f32x4* sh = (const f32x4*)(MOD + (size_t)mb * 9216 + ish * 1024); const f32x4* sc = (const f32x4*)(MOD + (size_t)mb * 9216 + isc * 1024);
; #pragma unroll
;         for (int j = 0; j < 4; ++j) { const f32x4 a = v[j] * rstd * wv[j]; v[j] = a * (sc[lane + 64 * j] + 1.0f) + sh[lane + 64 * j];
;             if (OUT8) { *(unsigned*)((unsigned char*)H + (size_t)row * DM + 4 * (lane + 64 * j)) = pk4_fp8(v[j][0] * SC_H8, v[j][1] * SC_H8, v[j][2] * SC_H8, v[j][3] * SC_H8); }
;             else { v2u o; o.x = pk2(v[j][0], v[j][1]); o.y = pk2(v[j][2], v[j][3]); *(v2u*)(H + (size_t)row * DM + 4 * (lane + 64 * j)) = o; } }
	v_lshlrev_b32_e32 v128, 16, v96
	v_and_b32_e32 v129, 0xffff0000, v96
	v_lshlrev_b32_e32 v130, 16, v97
	v_and_b32_e32 v131, 0xffff0000, v97
	v_lshlrev_b32_e32 v132, 16, v98
	v_and_b32_e32 v133, 0xffff0000, v98
	v_lshlrev_b32_e32 v134, 16, v99
	v_and_b32_e32 v135, 0xffff0000, v99
	v_lshlrev_b32_e32 v136, 16, v100
	v_and_b32_e32 v137, 0xffff0000, v100
	v_lshlrev_b32_e32 v138, 16, v101
	v_and_b32_e32 v139, 0xffff0000, v101
	v_lshlrev_b32_e32 v140, 16, v102
	v_and_b32_e32 v141, 0xffff0000, v102
	v_lshlrev_b32_e32 v142, 16, v103
	v_and_b32_e32 v143, 0xffff0000, v103
	v_lshlrev_b32_e32 v144, 16, v104
	v_and_b32_e32 v145, 0xffff0000, v104
	v_lshlrev_b32_e32 v146, 16, v105
	v_and_b32_e32 v147, 0xffff0000, v105
	v_lshlrev_b32_e32 v148, 16, v106
	v_and_b32_e32 v149, 0xffff0000, v106
	v_lshlrev_b32_e32 v150, 16, v107
	v_and_b32_e32 v151, 0xffff0000, v107
	v_lshlrev_b32_e32 v152, 16, v108
	v_and_b32_e32 v153, 0xffff0000, v108
	v_lshlrev_b32_e32 v154, 16, v109
	v_and_b32_e32 v155, 0xffff0000, v109
	v_lshlrev_b32_e32 v156, 16, v110
	v_and_b32_e32 v157, 0xffff0000, v110
	v_lshlrev_b32_e32 v158, 16, v111
	v_and_b32_e32 v159, 0xffff0000, v111
	v_pk_mul_f32 v[208:209], v[128:129], v[128:129]
	v_pk_mul_f32 v[210:211], v[130:131], v[130:131]
	v_pk_mul_f32 v[212:213], v[144:145], v[144:145]
	v_pk_mul_f32 v[214:215], v[146:147], v[146:147]
	v_pk_fma_f32 v[208:209], v[132:133], v[132:133], v[208:209]
	v_pk_fma_f32 v[210:211], v[134:135], v[134:135], v[210:211]
	v_pk_fma_f32 v[212:213], v[148:149], v[148:149], v[212:213]
	v_pk_fma_f32 v[214:215], v[150:151], v[150:151], v[214:215]
	v_pk_fma_f32 v[208:209], v[136:137], v[136:137], v[208:209]
	v_pk_fma_f32 v[210:211], v[138:139], v[138:139], v[210:211]
	v_pk_fma_f32 v[212:213], v[152:153], v[152:153], v[212:213]
	v_pk_fma_f32 v[214:215], v[154:155], v[154:155], v[214:215]
	v_pk_fma_f32 v[208:209], v[140:141], v[140:141], v[208:209]
	v_pk_fma_f32 v[210:211], v[142:143], v[142:143], v[210:211]
	v_pk_fma_f32 v[212:213], v[156:157], v[156:157], v[212:213]
	v_pk_fma_f32 v[214:215], v[158:159], v[158:159], v[214:215]
	v_pk_add_f32 v[208:209], v[208:209], v[210:211]
	v_pk_add_f32 v[212:213], v[212:213], v[214:215]
	v_add_f32_e32 v208, v208, v209
	v_add_f32_e32 v212, v212, v213
	s_nop 0
	v_add_f32_dpp v208, v208, v208 quad_perm:[1,0,3,2] row_mask:0xf bank_mask:0xf
	v_add_f32_dpp v212, v212, v212 quad_perm:[1,0,3,2] row_mask:0xf bank_mask:0xf
	s_nop 0
	v_add_f32_dpp v208, v208, v208 quad_perm:[2,3,0,1] row_mask:0xf bank_mask:0xf
	v_add_f32_dpp v212, v212, v212 quad_perm:[2,3,0,1] row_mask:0xf bank_mask:0xf
	s_nop 0
	v_add_f32_dpp v208, v208, v208 row_half_mirror row_mask:0xf bank_mask:0xf
	v_add_f32_dpp v212, v212, v212 row_half_mirror row_mask:0xf bank_mask:0xf
	s_nop 0
	v_add_f32_dpp v208, v208, v208 row_mirror row_mask:0xf bank_mask:0xf
	v_add_f32_dpp v212, v212, v212 row_mirror row_mask:0xf bank_mask:0xf
	s_nop 0
	v_readlane_b32 s30, v208, 0
	v_readlane_b32 s31, v208, 16
	v_readlane_b32 s32, v208, 32
	v_readlane_b32 s33, v208, 48
	v_readlane_b32 s34, v212, 0
	v_readlane_b32 s35, v212, 16
	v_readlane_b32 s36, v212, 32
	v_readlane_b32 s37, v212, 48
	s_nop 1
	v_mov_b32_e32 v209, s30
	v_mov_b32_e32 v213, s34
	v_add_f32_e32 v209, s31, v209
	v_add_f32_e32 v213, s35, v213
	v_add_f32_e32 v209, s32, v209
	v_add_f32_e32 v213, s36, v213
	v_add_f32_e32 v209, s33, v209
	v_add_f32_e32 v213, s37, v213
	v_fmamk_f32 v209, v209, 0x3a800000, v8
	v_fmamk_f32 v213, v213, 0x3a800000, v8
	v_rsq_f32_e32 v210, v209
	v_rsq_f32_e32 v214, v213
	s_nop 0
	v_pk_mul_f32 v[128:129], v[128:129], v[210:211] op_sel_hi:[1,0]
	v_pk_mul_f32 v[130:131], v[130:131], v[210:211] op_sel_hi:[1,0]
	v_pk_mul_f32 v[132:133], v[132:133], v[210:211] op_sel_hi:[1,0]
	v_pk_mul_f32 v[134:135], v[134:135], v[210:211] op_sel_hi:[1,0]
	v_pk_mul_f32 v[136:137], v[136:137], v[210:211] op_sel_hi:[1,0]
	v_pk_mul_f32 v[138:139], v[138:139], v[210:211] op_sel_hi:[1,0]
	v_pk_mul_f32 v[140:141], v[140:141], v[210:211] op_sel_hi:[1,0]
	v_pk_mul_f32 v[142:143], v[142:143], v[210:211] op_sel_hi:[1,0]
	v_pk_mul_f32 v[144:145], v[144:145], v[214:215] op_sel_hi:[1,0]
	v_pk_mul_f32 v[146:147], v[146:147], v[214:215] op_sel_hi:[1,0]
	v_pk_mul_f32 v[148:149], v[148:149], v[214:215] op_sel_hi:[1,0]
	v_pk_mul_f32 v[150:151], v[150:151], v[214:215] op_sel_hi:[1,0]
	v_pk_mul_f32 v[152:153], v[152:153], v[214:215] op_sel_hi:[1,0]
	v_pk_mul_f32 v[154:155], v[154:155], v[214:215] op_sel_hi:[1,0]
	v_pk_mul_f32 v[156:157], v[156:157], v[214:215] op_sel_hi:[1,0]
	v_pk_mul_f32 v[158:159], v[158:159], v[214:215] op_sel_hi:[1,0]
	v_pk_fma_f32 v[128:129], v[128:129], v[16:17], v[32:33]
	v_pk_fma_f32 v[130:131], v[130:131], v[18:19], v[34:35]
	v_pk_fma_f32 v[132:133], v[132:133], v[20:21], v[36:37]
	v_pk_fma_f32 v[134:135], v[134:135], v[22:23], v[38:39]
	v_pk_fma_f32 v[136:137], v[136:137], v[24:25], v[40:41]
	v_pk_fma_f32 v[138:139], v[138:139], v[26:27], v[42:43]
	v_pk_fma_f32 v[140:141], v[140:141], v[28:29], v[44:45]
	v_pk_fma_f32 v[142:143], v[142:143], v[30:31], v[46:47]
	v_pk_fma_f32 v[144:145], v[144:145], v[16:17], v[32:33]
	v_pk_fma_f32 v[146:147], v[146:147], v[18:19], v[34:35]
	v_pk_fma_f32 v[148:149], v[148:149], v[20:21], v[36:37]
	v_pk_fma_f32 v[150:151], v[150:151], v[22:23], v[38:39]
	v_pk_fma_f32 v[152:153], v[152:153], v[24:25], v[40:41]
	v_pk_fma_f32 v[154:155], v[154:155], v[26:27], v[42:43]
	v_pk_fma_f32 v[156:157], v[156:157], v[28:29], v[44:45]
	v_pk_fma_f32 v[158:159], v[158:159], v[30:31], v[46:47]
	v_cvt_pk_bf16_f32 v216, v128, v129
	v_cvt_pk_bf16_f32 v217, v130, v131
	v_cvt_pk_bf16_f32 v218, v132, v133
	v_cvt_pk_bf16_f32 v219, v134, v135
	v_cvt_pk_bf16_f32 v220, v136, v137
	v_cvt_pk_bf16_f32 v221, v138, v139
	v_cvt_pk_bf16_f32 v222, v140, v141
	v_cvt_pk_bf16_f32 v223, v142, v143
	v_cvt_pk_bf16_f32 v224, v144, v145
	v_cvt_pk_bf16_f32 v225, v146, v147
	v_cvt_pk_bf16_f32 v226, v148, v149
	v_cvt_pk_bf16_f32 v227, v150, v151
	v_cvt_pk_bf16_f32 v228, v152, v153
	v_cvt_pk_bf16_f32 v229, v154, v155
	v_cvt_pk_bf16_f32 v230, v156, v157
	v_cvt_pk_bf16_f32 v231, v158, v159
	global_store_dwordx2 v2, v[216:217], s[20:21]
	global_store_dwordx2 v2, v[218:219], s[20:21] offset:512
	global_store_dwordx2 v2, v[220:221], s[20:21] offset:1024
	global_store_dwordx2 v2, v[222:223], s[20:21] offset:1536
	global_store_dwordx2 v2, v[224:225], s[20:21] offset:2048
	global_store_dwordx2 v2, v[226:227], s[20:21] offset:2560
	global_store_dwordx2 v2, v[228:229], s[20:21] offset:3072
	global_store_dwordx2 v2, v[230:231], s[20:21] offset:3584
	s_add_u32 s20, s20, 0x1000
	s_addc_u32 s21, s21, 0
	ds_read_b128 v[192:195], v3 offset:0
	ds_read_b128 v[196:199], v3 offset:1024
	ds_read_b128 v[200:203], v3 offset:2048
	ds_read_b128 v[204:207], v3 offset:3072
	s_waitcnt lgkmcnt(3)
; template <bool WITH_DT, bool OUT8> __device__ __forceinline__ void norm_mod_rows(const void* xp, bool pb16, const void* xs, bool sb16, const float* w, const float* MOD, int ish, int isc, bf16* H, ...
;     ...
;         if (WITH_DT) {
;             float d[8];
; #pragma unroll
;             for (int c = 0; c < 8; ++c) { float p = 0.f;
; #pragma unroll
;                 for (int j = 0; j < 4; ++j) { const f32x4 ww = wdt[WITH_DT ? c : 0][j]; p += (v[j][0] * ww[0] + v[j][1] * ww[1]) + (v[j][2] * ww[2] + v[j][3] * ww[3]); }
;                 d[c] = p; }
	v_pk_mul_f32 v[160:161], v[128:129], v[192:193]
	v_pk_mul_f32 v[176:177], v[144:145], v[192:193]
	v_pk_fma_f32 v[160:161], v[130:131], v[194:195], v[160:161]
	v_pk_fma_f32 v[176:177], v[146:147], v[194:195], v[176:177]
	ds_read_b128 v[192:195], v3 offset:4096
	s_waitcnt lgkmcnt(3)
	v_pk_fma_f32 v[160:161], v[132:133], v[196:197], v[160:161]
	v_pk_fma_f32 v[176:177], v[148:149], v[196:197], v[176:177]
	v_pk_fma_f32 v[160:161], v[134:135], v[198:199], v[160:161]
	v_pk_fma_f32 v[176:177], v[150:151], v[198:199], v[176:177]
	ds_read_b128 v[196:199], v3 offset:5120
	s_waitcnt lgkmcnt(3)
	v_pk_fma_f32 v[160:161], v[136:137], v[200:201], v[160:161]
	v_pk_fma_f32 v[176:177], v[152:153], v[200:201], v[176:177]
	v_pk_fma_f32 v[160:161], v[138:139], v[202:203], v[160:161]
	v_pk_fma_f32 v[176:177], v[154:155], v[202:203], v[176:177]
	ds_read_b128 v[200:203], v3 offset:6144
	s_waitcnt lgkmcnt(3)
	v_pk_fma_f32 v[160:161], v[140:141], v[204:205], v[160:161]
	v_pk_fma_f32 v[176:177], v[156:157], v[204:205], v[176:177]
	v_pk_fma_f32 v[160:161], v[142:143], v[206:207], v[160:161]
	v_pk_fma_f32 v[176:177], v[158:159], v[206:207], v[176:177]
	ds_read_b128 v[204:207], v3 offset:7168
	s_waitcnt lgkmcnt(3)
	v_pk_mul_f32 v[162:163], v[128:129], v[192:193]
	v_pk_mul_f32 v[178:179], v[144:145], v[192:193]
	v_pk_fma_f32 v[162:163], v[130:131], v[194:195], v[162:163]
	v_pk_fma_f32 v[178:179], v[146:147], v[194:195], v[178:179]
	ds_read_b128 v[192:195], v3 offset:8192
	s_waitcnt lgkmcnt(3)
	v_pk_fma_f32 v[162:163], v[132:133], v[196:197], v[162:163]
	v_pk_fma_f32 v[178:179], v[148:149], v[196:197], v[178:179]
	v_pk_fma_f32 v[162:163], v[134:135], v[198:199], v[162:163]
	v_pk_fma_f32 v[178:179], v[150:151], v[198:199], v[178:179]
	ds_read_b128 v[196:199], v3 offset:9216
	s_waitcnt lgkmcnt(3)
	v_pk_fma_f32 v[162:163], v[136:137], v[200:201], v[162:163]
	v_pk_fma_f32 v[178:179], v[152:153], v[200:201], v[178:179]
	v_pk_fma_f32 v[162:163], v[138:139], v[202:203], v[162:163]
	v_pk_fma_f32 v[178:179], v[154:155], v[202:203], v[178:179]
	ds_read_b128 v[200:203], v3 offset:10240
	s_waitcnt lgkmcnt(3)
	v_pk_fma_f32 v[162:163], v[140:141], v[204:205], v[162:163]
	v_pk_fma_f32 v[178:179], v[156:157], v[204:205], v[178:179]
	v_pk_fma_f32 v[162:163], v[142:143], v[206:207], v[162:163]
	v_pk_fma_f32 v[178:179], v[158:159], v[206:207], v[178:179]
	ds_read_b128 v[204:207], v3 offset:11264
	s_waitcnt lgkmcnt(3)
	v_pk_mul_f32 v[164:165], v[128:129], v[192:193]
	v_pk_mul_f32 v[180:181], v[144:145], v[192:193]
	v_pk_fma_f32 v[164:165], v[130:131], v[194:195], v[164:165]
	v_pk_fma_f32 v[180:181], v[146:147], v[194:195], v[180:181]
	ds_read_b128 v[192:195], v3 offset:12288
	s_waitcnt lgkmcnt(3)
	v_pk_fma_f32 v[164:165], v[132:133], v[196:197], v[164:165]
	v_pk_fma_f32 v[180:181], v[148:149], v[196:197], v[180:181]
	v_pk_fma_f32 v[164:165], v[134:135], v[198:199], v[164:165]
	v_pk_fma_f32 v[180:181], v[150:151], v[198:199], v[180:181]
	ds_read_b128 v[196:199], v3 offset:13312
	s_waitcnt lgkmcnt(3)
	v_pk_fma_f32 v[164:165], v[136:137], v[200:201], v[164:165]
	v_pk_fma_f32 v[180:181], v[152:153], v[200:201], v[180:181]
	v_pk_fma_f32 v[164:165], v[138:139], v[202:203], v[164:165]
	v_pk_fma_f32 v[180:181], v[154:155], v[202:203], v[180:181]
	ds_read_b128 v[200:203], v3 offset:14336
	s_waitcnt lgkmcnt(3)
	v_pk_fma_f32 v[164:165], v[140:141], v[204:205], v[164:165]
	v_pk_fma_f32 v[180:181], v[156:157], v[204:205], v[180:181]
	v_pk_fma_f32 v[164:165], v[142:143], v[206:207], v[164:165]
	v_pk_fma_f32 v[180:181], v[158:159], v[206:207], v[180:181]
	ds_read_b128 v[204:207], v3 offset:15360
	s_waitcnt lgkmcnt(3)
	v_pk_mul_f32 v[166:167], v[128:129], v[192:193]
	v_pk_mul_f32 v[182:183], v[144:145], v[192:193]
	v_pk_fma_f32 v[166:167], v[130:131], v[194:195], v[166:167]
	v_pk_fma_f32 v[182:183], v[146:147], v[194:195], v[182:183]
	ds_read_b128 v[192:195], v3 offset:16384
	s_waitcnt lgkmcnt(3)
	v_pk_fma_f32 v[166:167], v[132:133], v[196:197], v[166:167]
	v_pk_fma_f32 v[182:183], v[148:149], v[196:197], v[182:183]
	v_pk_fma_f32 v[166:167], v[134:135], v[198:199], v[166:167]
	v_pk_fma_f32 v[182:183], v[150:151], v[198:199], v[182:183]
	ds_read_b128 v[196:199], v3 offset:17408
	s_waitcnt lgkmcnt(3)
	v_pk_fma_f32 v[166:167], v[136:137], v[200:201], v[166:167]
	v_pk_fma_f32 v[182:183], v[152:153], v[200:201], v[182:183]
	v_pk_fma_f32 v[166:167], v[138:139], v[202:203], v[166:167]
	v_pk_fma_f32 v[182:183], v[154:155], v[202:203], v[182:183]
	ds_read_b128 v[200:203], v3 offset:18432
	s_waitcnt lgkmcnt(3)
	v_pk_fma_f32 v[166:167], v[140:141], v[204:205], v[166:167]
	v_pk_fma_f32 v[182:183], v[156:157], v[204:205], v[182:183]
	v_pk_fma_f32 v[166:167], v[142:143], v[206:207], v[166:167]
	v_pk_fma_f32 v[182:183], v[158:159], v[206:207], v[182:183]
	ds_read_b128 v[204:207], v3 offset:19456
	s_waitcnt lgkmcnt(3)
	v_pk_mul_f32 v[168:169], v[128:129], v[192:193]
	v_pk_mul_f32 v[184:185], v[144:145], v[192:193]
	v_pk_fma_f32 v[168:169], v[130:131], v[194:195], v[168:169]
	v_pk_fma_f32 v[184:185], v[146:147], v[194:195], v[184:185]
	ds_read_b128 v[192:195], v3 offset:20480
	s_waitcnt lgkmcnt(3)
	v_pk_fma_f32 v[168:169], v[132:133], v[196:197], v[168:169]
	v_pk_fma_f32 v[184:185], v[148:149], v[196:197], v[184:185]
	v_pk_fma_f32 v[168:169], v[134:135], v[198:199], v[168:169]
	v_pk_fma_f32 v[184:185], v[150:151], v[198:199], v[184:185]
	ds_read_b128 v[196:199], v3 offset:21504
	s_waitcnt lgkmcnt(3)
	v_pk_fma_f32 v[168:169], v[136:137], v[200:201], v[168:169]
	v_pk_fma_f32 v[184:185], v[152:153], v[200:201], v[184:185]
	v_pk_fma_f32 v[168:169], v[138:139], v[202:203], v[168:169]
	v_pk_fma_f32 v[184:185], v[154:155], v[202:203], v[184:185]
	ds_read_b128 v[200:203], v3 offset:22528
	s_waitcnt lgkmcnt(3)
; template <bool WITH_DT, bool OUT8> __device__ __forceinline__ void norm_mod_rows(const void* xp, bool pb16, const void* xs, bool sb16, const float* w, const float* MOD, int ish, int isc, bf16* H, ...
;     ...
;             for (int c = 0; c < 8; ++c) { float p = 0.f;
; #pragma unroll
;                 for (int j = 0; j < 4; ++j) { const f32x4 ww = wdt[WITH_DT ? c : 0][j]; p += (v[j][0] * ww[0] + v[j][1] * ww[1]) + (v[j][2] * ww[2] + v[j][3] * ww[3]); }
;                 d[c] = p; }
;             float e4[4], e2[2], e1;
;             { const bool up = (lane & 32) != 0;
; #pragma unroll
;               for (int c = 0; c < 4; ++c) { const float keep = up ? d[4 + c] : d[c], give = up ? d[c] : d[4 + c]; e4[c] = keep + __shfl_xor(give, 32); } }
;             { const bool up = (lane & 16) != 0;
; #pragma unroll
;               for (int c = 0; c < 2; ++c) { const float keep = up ? e4[2 + c] : e4[c], give = up ? e4[c] : e4[2 + c]; e2[c] = keep + __shfl_xor(give, 16); } }
;             { const bool up = (lane & 8) != 0; const float keep = up ? e2[1] : e2[0], give = up ? e2[0] : e2[1]; e1 = keep + __shfl_xor(give, 8); }
;             e1 += __shfl_xor(e1, 4); e1 += __shfl_xor(e1, 2); e1 += __shfl_xor(e1, 1);
	v_pk_fma_f32 v[168:169], v[140:141], v[204:205], v[168:169]
	v_pk_fma_f32 v[184:185], v[156:157], v[204:205], v[184:185]
	v_pk_fma_f32 v[168:169], v[142:143], v[206:207], v[168:169]
	v_pk_fma_f32 v[184:185], v[158:159], v[206:207], v[184:185]
	ds_read_b128 v[204:207], v3 offset:23552
	s_waitcnt lgkmcnt(3)
	v_pk_mul_f32 v[170:171], v[128:129], v[192:193]
	v_pk_mul_f32 v[186:187], v[144:145], v[192:193]
	v_pk_fma_f32 v[170:171], v[130:131], v[194:195], v[170:171]
	v_pk_fma_f32 v[186:187], v[146:147], v[194:195], v[186:187]
	ds_read_b128 v[192:195], v3 offset:24576
	s_waitcnt lgkmcnt(3)
	v_pk_fma_f32 v[170:171], v[132:133], v[196:197], v[170:171]
	v_pk_fma_f32 v[186:187], v[148:149], v[196:197], v[186:187]
	v_pk_fma_f32 v[170:171], v[134:135], v[198:199], v[170:171]
	v_pk_fma_f32 v[186:187], v[150:151], v[198:199], v[186:187]
	ds_read_b128 v[196:199], v3 offset:25600
	s_waitcnt lgkmcnt(3)
	v_pk_fma_f32 v[170:171], v[136:137], v[200:201], v[170:171]
	v_pk_fma_f32 v[186:187], v[152:153], v[200:201], v[186:187]
	v_pk_fma_f32 v[170:171], v[138:139], v[202:203], v[170:171]
	v_pk_fma_f32 v[186:187], v[154:155], v[202:203], v[186:187]
	ds_read_b128 v[200:203], v3 offset:26624
	s_waitcnt lgkmcnt(3)
	v_pk_fma_f32 v[170:171], v[140:141], v[204:205], v[170:171]
	v_pk_fma_f32 v[186:187], v[156:157], v[204:205], v[186:187]
	v_pk_fma_f32 v[170:171], v[142:143], v[206:207], v[170:171]
	v_pk_fma_f32 v[186:187], v[158:159], v[206:207], v[186:187]
	ds_read_b128 v[204:207], v3 offset:27648
	s_waitcnt lgkmcnt(3)
	v_pk_mul_f32 v[172:173], v[128:129], v[192:193]
	v_pk_mul_f32 v[188:189], v[144:145], v[192:193]
	v_pk_fma_f32 v[172:173], v[130:131], v[194:195], v[172:173]
	v_pk_fma_f32 v[188:189], v[146:147], v[194:195], v[188:189]
	ds_read_b128 v[192:195], v3 offset:28672
	s_waitcnt lgkmcnt(3)
	v_pk_fma_f32 v[172:173], v[132:133], v[196:197], v[172:173]
	v_pk_fma_f32 v[188:189], v[148:149], v[196:197], v[188:189]
	v_pk_fma_f32 v[172:173], v[134:135], v[198:199], v[172:173]
	v_pk_fma_f32 v[188:189], v[150:151], v[198:199], v[188:189]
	ds_read_b128 v[196:199], v3 offset:29696
	s_waitcnt lgkmcnt(3)
	v_pk_fma_f32 v[172:173], v[136:137], v[200:201], v[172:173]
	v_pk_fma_f32 v[188:189], v[152:153], v[200:201], v[188:189]
	v_pk_fma_f32 v[172:173], v[138:139], v[202:203], v[172:173]
	v_pk_fma_f32 v[188:189], v[154:155], v[202:203], v[188:189]
	ds_read_b128 v[200:203], v3 offset:30720
	s_waitcnt lgkmcnt(3)
	v_pk_fma_f32 v[172:173], v[140:141], v[204:205], v[172:173]
	v_pk_fma_f32 v[188:189], v[156:157], v[204:205], v[188:189]
	v_pk_fma_f32 v[172:173], v[142:143], v[206:207], v[172:173]
	v_pk_fma_f32 v[188:189], v[158:159], v[206:207], v[188:189]
	ds_read_b128 v[204:207], v3 offset:31744
	s_waitcnt lgkmcnt(3)
	v_pk_mul_f32 v[174:175], v[128:129], v[192:193]
	v_pk_mul_f32 v[190:191], v[144:145], v[192:193]
	v_pk_fma_f32 v[174:175], v[130:131], v[194:195], v[174:175]
	v_pk_fma_f32 v[190:191], v[146:147], v[194:195], v[190:191]
	s_waitcnt lgkmcnt(2)
	v_pk_fma_f32 v[174:175], v[132:133], v[196:197], v[174:175]
	v_pk_fma_f32 v[190:191], v[148:149], v[196:197], v[190:191]
	v_pk_fma_f32 v[174:175], v[134:135], v[198:199], v[174:175]
	v_pk_fma_f32 v[190:191], v[150:151], v[198:199], v[190:191]
	s_waitcnt lgkmcnt(1)
	v_pk_fma_f32 v[174:175], v[136:137], v[200:201], v[174:175]
	v_pk_fma_f32 v[190:191], v[152:153], v[200:201], v[190:191]
	v_pk_fma_f32 v[174:175], v[138:139], v[202:203], v[174:175]
	v_pk_fma_f32 v[190:191], v[154:155], v[202:203], v[190:191]
	s_waitcnt lgkmcnt(0)
	v_pk_fma_f32 v[174:175], v[140:141], v[204:205], v[174:175]
	v_pk_fma_f32 v[190:191], v[156:157], v[204:205], v[190:191]
	v_pk_fma_f32 v[174:175], v[142:143], v[206:207], v[174:175]
	v_pk_fma_f32 v[190:191], v[158:159], v[206:207], v[190:191]
	v_add_f32_e32 v160, v160, v161
	v_add_f32_e32 v176, v176, v177
	v_add_f32_e32 v162, v162, v163
	v_add_f32_e32 v178, v178, v179
	v_add_f32_e32 v164, v164, v165
	v_add_f32_e32 v180, v180, v181
	v_add_f32_e32 v166, v166, v167
	v_add_f32_e32 v182, v182, v183
	v_add_f32_e32 v168, v168, v169
	v_add_f32_e32 v184, v184, v185
	v_add_f32_e32 v170, v170, v171
	v_add_f32_e32 v186, v186, v187
	v_add_f32_e32 v172, v172, v173
	v_add_f32_e32 v188, v188, v189
	v_add_f32_e32 v174, v174, v175
	v_add_f32_e32 v190, v190, v191
	v_cndmask_b32_e64 v216, v160, v168, s[38:39]
	v_cndmask_b32_e64 v217, v168, v160, s[38:39]
	v_cndmask_b32_e64 v224, v176, v184, s[38:39]
	v_cndmask_b32_e64 v225, v184, v176, s[38:39]
	v_cndmask_b32_e64 v218, v162, v170, s[38:39]
	v_cndmask_b32_e64 v219, v170, v162, s[38:39]
	v_cndmask_b32_e64 v226, v178, v186, s[38:39]
	v_cndmask_b32_e64 v227, v186, v178, s[38:39]
	v_cndmask_b32_e64 v220, v164, v172, s[38:39]
	v_cndmask_b32_e64 v221, v172, v164, s[38:39]
	v_cndmask_b32_e64 v228, v180, v188, s[38:39]
	v_cndmask_b32_e64 v229, v188, v180, s[38:39]
	v_cndmask_b32_e64 v222, v166, v174, s[38:39]
	v_cndmask_b32_e64 v223, v174, v166, s[38:39]
	v_cndmask_b32_e64 v230, v182, v190, s[38:39]
	v_cndmask_b32_e64 v231, v190, v182, s[38:39]
	s_nop 0
	v_add_f32_dpp v160, v217, v216 quad_perm:[1,0,3,2] row_mask:0xf bank_mask:0xf
	v_add_f32_dpp v176, v225, v224 quad_perm:[1,0,3,2] row_mask:0xf bank_mask:0xf
	v_add_f32_dpp v162, v219, v218 quad_perm:[1,0,3,2] row_mask:0xf bank_mask:0xf
	v_add_f32_dpp v178, v227, v226 quad_perm:[1,0,3,2] row_mask:0xf bank_mask:0xf
	v_add_f32_dpp v164, v221, v220 quad_perm:[1,0,3,2] row_mask:0xf bank_mask:0xf
	v_add_f32_dpp v180, v229, v228 quad_perm:[1,0,3,2] row_mask:0xf bank_mask:0xf
	v_add_f32_dpp v166, v223, v222 quad_perm:[1,0,3,2] row_mask:0xf bank_mask:0xf
	v_add_f32_dpp v182, v231, v230 quad_perm:[1,0,3,2] row_mask:0xf bank_mask:0xf
	v_cndmask_b32_e64 v216, v160, v164, s[40:41]
	v_cndmask_b32_e64 v217, v164, v160, s[40:41]
	v_cndmask_b32_e64 v224, v176, v180, s[40:41]
	v_cndmask_b32_e64 v225, v180, v176, s[40:41]
	v_cndmask_b32_e64 v218, v162, v166, s[40:41]
	v_cndmask_b32_e64 v219, v166, v162, s[40:41]
	v_cndmask_b32_e64 v226, v178, v182, s[40:41]
	v_cndmask_b32_e64 v227, v182, v178, s[40:41]
	s_nop 0
	v_add_f32_dpp v160, v217, v216 quad_perm:[2,3,0,1] row_mask:0xf bank_mask:0xf
	v_add_f32_dpp v176, v225, v224 quad_perm:[2,3,0,1] row_mask:0xf bank_mask:0xf
	v_add_f32_dpp v162, v219, v218 quad_perm:[2,3,0,1] row_mask:0xf bank_mask:0xf
	v_add_f32_dpp v178, v227, v226 quad_perm:[2,3,0,1] row_mask:0xf bank_mask:0xf
	v_cndmask_b32_e64 v216, v160, v162, s[42:43]
	v_cndmask_b32_e64 v217, v162, v160, s[42:43]
	v_cndmask_b32_e64 v224, v176, v178, s[42:43]
	v_cndmask_b32_e64 v225, v178, v176, s[42:43]
	s_nop 0
	v_add_f32_dpp v160, v217, v216 row_shl:4 row_mask:0xf bank_mask:0x5
	v_add_f32_dpp v160, v217, v216 row_shr:4 row_mask:0xf bank_mask:0xa
	v_add_f32_dpp v176, v225, v224 row_shl:4 row_mask:0xf bank_mask:0x5
	v_add_f32_dpp v176, v225, v224 row_shr:4 row_mask:0xf bank_mask:0xa
	s_nop 1
	v_add_f32_dpp v160, v160, v160 row_ror:8 row_mask:0xf bank_mask:0xf
	v_add_f32_dpp v176, v176, v176 row_ror:8 row_mask:0xf bank_mask:0xf
	s_nop 0
	ds_bpermute_b32 v161, v5, v160
	ds_bpermute_b32 v177, v5, v176
	s_waitcnt lgkmcnt(0)
; template <bool WITH_DT, bool OUT8> __device__ __forceinline__ void norm_mod_rows(const void* xp, bool pb16, const void* xs, bool sb16, const float* w, const float* MOD, int ish, int isc, bf16* H, ...
;     ...
;         for (int j = 0; j < 4; ++j) s += (v[j][0] * v[j][0] + v[j][1] * v[j][1]) + (v[j][2] * v[j][2] + v[j][3] * v[j][3]);
;         const float rstd = rsqrtf(wave_sum(s) * (1.0f / DM) + EPSN);
;         const f32x4* sh = (const f32x4*)(MOD + (size_t)mb * 9216 + ish * 1024); const f32x4* sc = (const f32x4*)(MOD + (size_t)mb * 9216 + isc * 1024);
; #pragma unroll
;         for (int j = 0; j < 4; ++j) { const f32x4 a = v[j] * rstd * wv[j]; v[j] = a * (sc[lane + 64 * j] + 1.0f) + sh[lane + 64 * j];
;     ...
;             float e4[4], e2[2], e1;
;             { const bool up = (lane & 32) != 0;
; #pragma unroll
;               for (int c = 0; c < 4; ++c) { const float keep = up ? d[4 + c] : d[c], give = up ? d[c] : d[4 + c]; e4[c] = keep + __shfl_xor(give, 32); } }
;             { const bool up = (lane & 16) != 0;
; #pragma unroll
;               for (int c = 0; c < 2; ++c) { const float keep = up ? e4[2 + c] : e4[c], give = up ? e4[c] : e4[2 + c]; e2[c] = keep + __shfl_xor(give, 16); } }
;             { const bool up = (lane & 8) != 0; const float keep = up ? e2[1] : e2[0], give = up ? e2[0] : e2[1]; e1 = keep + __shfl_xor(give, 8); }
;             e1 += __shfl_xor(e1, 4); e1 += __shfl_xor(e1, 2); e1 += __shfl_xor(e1, 1);
;             const int col = ((lane >> 5) & 1) * 4 + ((lane >> 4) & 1) * 2 + ((lane >> 3) & 1);
;             if ((lane & 7) == 0) { const float p = e1 + dt_bias[col]; DT[(size_t)row * 8 + col] = fmaxf(p, 0.f) + log1pf(__expf(-fabsf(p))); }
	v_add_f32_e32 v160, v160, v161
	v_add_f32_e32 v176, v176, v177
	v_mov_b32_e32 v161, v160
	v_mov_b32_e32 v177, v176
	s_nop 1
	v_permlane32_swap_b32_e32 v160, v161
	v_permlane32_swap_b32_e32 v176, v177
	v_add_f32_e32 v160, v160, v161
	v_add_f32_e32 v176, v176, v177
	v_add_f32_e32 v160, v160, v12
	v_add_f32_e32 v176, v176, v12
	v_and_b32_e32 v216, 0x7fffffff, v160
	v_and_b32_e32 v224, 0x7fffffff, v176
	v_mul_f32_e32 v216, 0xbfb8aa3b, v216
	v_mul_f32_e32 v224, 0xbfb8aa3b, v224
	v_exp_f32_e32 v216, v216
	v_exp_f32_e32 v224, v224
	s_nop 0
	v_add_f32_e32 v217, 1.0, v216
	v_add_f32_e32 v225, 1.0, v224
	v_log_f32_e32 v218, v217
	v_log_f32_e32 v226, v225
	v_add_f32_e32 v219, -1.0, v217
	v_add_f32_e32 v227, -1.0, v225
	v_rcp_f32_e32 v219, v219
	v_rcp_f32_e32 v227, v227
	v_mul_f32_e32 v218, 0x3f317218, v218
	v_mul_f32_e32 v226, 0x3f317218, v226
	v_mul_f32_e32 v219, v216, v219
	v_mul_f32_e32 v227, v224, v227
	v_mul_f32_e32 v218, v218, v219
	v_mul_f32_e32 v226, v226, v227
	v_cmp_eq_f32_e32 vcc, 1.0, v217
	s_nop 1
	v_cndmask_b32_e32 v218, v218, v216, vcc
	v_cmp_eq_f32_e32 vcc, 1.0, v225
	s_nop 1
	v_cndmask_b32_e32 v226, v226, v224, vcc
	v_max_f32_e32 v160, 0, v160
	v_max_f32_e32 v176, 0, v176
	v_add_f32_e32 v160, v160, v218
	v_add_f32_e32 v176, v176, v226
	v_cndmask_b32_e64 v160, v160, v176, s[44:45]
	s_mov_b64 exec, 0xffff
	global_store_dword v4, v160, s[28:29]
	s_mov_b64 exec, -1
	s_add_u32 s28, s28, 64
	s_addc_u32 s29, s29, 0
	s_waitcnt vmcnt(36)
	v_lshlrev_b32_e32 v128, 16, v112
	v_and_b32_e32 v129, 0xffff0000, v112
	v_lshlrev_b32_e32 v130, 16, v113
	v_and_b32_e32 v131, 0xffff0000, v113
	v_lshlrev_b32_e32 v132, 16, v114
	v_and_b32_e32 v133, 0xffff0000, v114
	v_lshlrev_b32_e32 v134, 16, v115
	v_and_b32_e32 v135, 0xffff0000, v115
	v_lshlrev_b32_e32 v136, 16, v116
	v_and_b32_e32 v137, 0xffff0000, v116
	v_lshlrev_b32_e32 v138, 16, v117
	v_and_b32_e32 v139, 0xffff0000, v117
	v_lshlrev_b32_e32 v140, 16, v118
	v_and_b32_e32 v141, 0xffff0000, v118
	v_lshlrev_b32_e32 v142, 16, v119
	v_and_b32_e32 v143, 0xffff0000, v119
	v_lshlrev_b32_e32 v144, 16, v120
	v_and_b32_e32 v145, 0xffff0000, v120
	v_lshlrev_b32_e32 v146, 16, v121
	v_and_b32_e32 v147, 0xffff0000, v121
	v_lshlrev_b32_e32 v148, 16, v122
	v_and_b32_e32 v149, 0xffff0000, v122
	v_lshlrev_b32_e32 v150, 16, v123
	v_and_b32_e32 v151, 0xffff0000, v123
	v_lshlrev_b32_e32 v152, 16, v124
	v_and_b32_e32 v153, 0xffff0000, v124
	v_lshlrev_b32_e32 v154, 16, v125
	v_and_b32_e32 v155, 0xffff0000, v125
	v_lshlrev_b32_e32 v156, 16, v126
	v_and_b32_e32 v157, 0xffff0000, v126
	v_lshlrev_b32_e32 v158, 16, v127
	v_and_b32_e32 v159, 0xffff0000, v127
	v_pk_mul_f32 v[208:209], v[128:129], v[128:129]
	v_pk_mul_f32 v[210:211], v[130:131], v[130:131]
	v_pk_mul_f32 v[212:213], v[144:145], v[144:145]
	v_pk_mul_f32 v[214:215], v[146:147], v[146:147]
	v_pk_fma_f32 v[208:209], v[132:133], v[132:133], v[208:209]
	v_pk_fma_f32 v[210:211], v[134:135], v[134:135], v[210:211]
	v_pk_fma_f32 v[212:213], v[148:149], v[148:149], v[212:213]
	v_pk_fma_f32 v[214:215], v[150:151], v[150:151], v[214:215]
	v_pk_fma_f32 v[208:209], v[136:137], v[136:137], v[208:209]
	v_pk_fma_f32 v[210:211], v[138:139], v[138:139], v[210:211]
	v_pk_fma_f32 v[212:213], v[152:153], v[152:153], v[212:213]
	v_pk_fma_f32 v[214:215], v[154:155], v[154:155], v[214:215]
	v_pk_fma_f32 v[208:209], v[140:141], v[140:141], v[208:209]
	v_pk_fma_f32 v[210:211], v[142:143], v[142:143], v[210:211]
	v_pk_fma_f32 v[212:213], v[156:157], v[156:157], v[212:213]
	v_pk_fma_f32 v[214:215], v[158:159], v[158:159], v[214:215]
	v_pk_add_f32 v[208:209], v[208:209], v[210:211]
	v_pk_add_f32 v[212:213], v[212:213], v[214:215]
	v_add_f32_e32 v208, v208, v209
	v_add_f32_e32 v212, v212, v213
	s_nop 0
	v_add_f32_dpp v208, v208, v208 quad_perm:[1,0,3,2] row_mask:0xf bank_mask:0xf
	v_add_f32_dpp v212, v212, v212 quad_perm:[1,0,3,2] row_mask:0xf bank_mask:0xf
	s_nop 0
	v_add_f32_dpp v208, v208, v208 quad_perm:[2,3,0,1] row_mask:0xf bank_mask:0xf
	v_add_f32_dpp v212, v212, v212 quad_perm:[2,3,0,1] row_mask:0xf bank_mask:0xf
	s_nop 0
	v_add_f32_dpp v208, v208, v208 row_half_mirror row_mask:0xf bank_mask:0xf
	v_add_f32_dpp v212, v212, v212 row_half_mirror row_mask:0xf bank_mask:0xf
	s_nop 0
	v_add_f32_dpp v208, v208, v208 row_mirror row_mask:0xf bank_mask:0xf
	v_add_f32_dpp v212, v212, v212 row_mirror row_mask:0xf bank_mask:0xf
	s_nop 0
	v_readlane_b32 s30, v208, 0
	v_readlane_b32 s31, v208, 16
	v_readlane_b32 s32, v208, 32
	v_readlane_b32 s33, v208, 48
	v_readlane_b32 s34, v212, 0
	v_readlane_b32 s35, v212, 16
	v_readlane_b32 s36, v212, 32
	v_readlane_b32 s37, v212, 48
	s_nop 1
	v_mov_b32_e32 v209, s30
	v_mov_b32_e32 v213, s34
	v_add_f32_e32 v209, s31, v209
	v_add_f32_e32 v213, s35, v213
	v_add_f32_e32 v209, s32, v209
	v_add_f32_e32 v213, s36, v213
	v_add_f32_e32 v209, s33, v209
	v_add_f32_e32 v213, s37, v213
	v_fmamk_f32 v209, v209, 0x3a800000, v8
	v_fmamk_f32 v213, v213, 0x3a800000, v8
	v_rsq_f32_e32 v210, v209
	v_rsq_f32_e32 v214, v213
	s_nop 0
	v_pk_mul_f32 v[128:129], v[128:129], v[210:211] op_sel_hi:[1,0]
	v_pk_mul_f32 v[130:131], v[130:131], v[210:211] op_sel_hi:[1,0]
	v_pk_mul_f32 v[132:133], v[132:133], v[210:211] op_sel_hi:[1,0]
	v_pk_mul_f32 v[134:135], v[134:135], v[210:211] op_sel_hi:[1,0]
	v_pk_mul_f32 v[136:137], v[136:137], v[210:211] op_sel_hi:[1,0]
	v_pk_mul_f32 v[138:139], v[138:139], v[210:211] op_sel_hi:[1,0]
	v_pk_mul_f32 v[140:141], v[140:141], v[210:211] op_sel_hi:[1,0]
	v_pk_mul_f32 v[142:143], v[142:143], v[210:211] op_sel_hi:[1,0]
	v_pk_mul_f32 v[144:145], v[144:145], v[214:215] op_sel_hi:[1,0]
	v_pk_mul_f32 v[146:147], v[146:147], v[214:215] op_sel_hi:[1,0]
; __device__ __forceinline__ unsigned pk2(float lo, float hi) { return pg8::cvt_pk_bf16(lo, hi); }
; template <bool WITH_DT, bool OUT8> __device__ __forceinline__ void norm_mod_rows(const void* xp, bool pb16, const void* xs, bool sb16, const float* w, const float* MOD, int ish, int isc, bf16* H, ...
;     ...
;         for (int j = 0; j < 4; ++j) { const f32x4 a = v[j] * rstd * wv[j]; v[j] = a * (sc[lane + 64 * j] + 1.0f) + sh[lane + 64 * j];
;             if (OUT8) { *(unsigned*)((unsigned char*)H + (size_t)row * DM + 4 * (lane + 64 * j)) = pk4_fp8(v[j][0] * SC_H8, v[j][1] * SC_H8, v[j][2] * SC_H8, v[j][3] * SC_H8); }
;             else { v2u o; o.x = pk2(v[j][0], v[j][1]); o.y = pk2(v[j][2], v[j][3]); *(v2u*)(H + (size_t)row * DM + 4 * (lane + 64 * j)) = o; } }
;         if (WITH_DT) {
;             float d[8];
; #pragma unroll
;             for (int c = 0; c < 8; ++c) { float p = 0.f;
; #pragma unroll
;                 for (int j = 0; j < 4; ++j) { const f32x4 ww = wdt[WITH_DT ? c : 0][j]; p += (v[j][0] * ww[0] + v[j][1] * ww[1]) + (v[j][2] * ww[2] + v[j][3] * ww[3]); }
;                 d[c] = p; }
	v_pk_mul_f32 v[148:149], v[148:149], v[214:215] op_sel_hi:[1,0]
	v_pk_mul_f32 v[150:151], v[150:151], v[214:215] op_sel_hi:[1,0]
	v_pk_mul_f32 v[152:153], v[152:153], v[214:215] op_sel_hi:[1,0]
	v_pk_mul_f32 v[154:155], v[154:155], v[214:215] op_sel_hi:[1,0]
	v_pk_mul_f32 v[156:157], v[156:157], v[214:215] op_sel_hi:[1,0]
	v_pk_mul_f32 v[158:159], v[158:159], v[214:215] op_sel_hi:[1,0]
	v_pk_fma_f32 v[128:129], v[128:129], v[16:17], v[32:33]
	v_pk_fma_f32 v[130:131], v[130:131], v[18:19], v[34:35]
	v_pk_fma_f32 v[132:133], v[132:133], v[20:21], v[36:37]
	v_pk_fma_f32 v[134:135], v[134:135], v[22:23], v[38:39]
	v_pk_fma_f32 v[136:137], v[136:137], v[24:25], v[40:41]
	v_pk_fma_f32 v[138:139], v[138:139], v[26:27], v[42:43]
	v_pk_fma_f32 v[140:141], v[140:141], v[28:29], v[44:45]
	v_pk_fma_f32 v[142:143], v[142:143], v[30:31], v[46:47]
	v_pk_fma_f32 v[144:145], v[144:145], v[16:17], v[32:33]
	v_pk_fma_f32 v[146:147], v[146:147], v[18:19], v[34:35]
	v_pk_fma_f32 v[148:149], v[148:149], v[20:21], v[36:37]
	v_pk_fma_f32 v[150:151], v[150:151], v[22:23], v[38:39]
	v_pk_fma_f32 v[152:153], v[152:153], v[24:25], v[40:41]
	v_pk_fma_f32 v[154:155], v[154:155], v[26:27], v[42:43]
	v_pk_fma_f32 v[156:157], v[156:157], v[28:29], v[44:45]
	v_pk_fma_f32 v[158:159], v[158:159], v[30:31], v[46:47]
	v_cvt_pk_bf16_f32 v216, v128, v129
	v_cvt_pk_bf16_f32 v217, v130, v131
	v_cvt_pk_bf16_f32 v218, v132, v133
	v_cvt_pk_bf16_f32 v219, v134, v135
	v_cvt_pk_bf16_f32 v220, v136, v137
	v_cvt_pk_bf16_f32 v221, v138, v139
	v_cvt_pk_bf16_f32 v222, v140, v141
	v_cvt_pk_bf16_f32 v223, v142, v143
	v_cvt_pk_bf16_f32 v224, v144, v145
	v_cvt_pk_bf16_f32 v225, v146, v147
	v_cvt_pk_bf16_f32 v226, v148, v149
	v_cvt_pk_bf16_f32 v227, v150, v151
	v_cvt_pk_bf16_f32 v228, v152, v153
	v_cvt_pk_bf16_f32 v229, v154, v155
	v_cvt_pk_bf16_f32 v230, v156, v157
	v_cvt_pk_bf16_f32 v231, v158, v159
	global_store_dwordx2 v2, v[216:217], s[20:21]
	global_store_dwordx2 v2, v[218:219], s[20:21] offset:512
	global_store_dwordx2 v2, v[220:221], s[20:21] offset:1024
	global_store_dwordx2 v2, v[222:223], s[20:21] offset:1536
	global_store_dwordx2 v2, v[224:225], s[20:21] offset:2048
	global_store_dwordx2 v2, v[226:227], s[20:21] offset:2560
	global_store_dwordx2 v2, v[228:229], s[20:21] offset:3072
	global_store_dwordx2 v2, v[230:231], s[20:21] offset:3584
	s_add_u32 s20, s20, 0x1000
	s_addc_u32 s21, s21, 0
	ds_read_b128 v[192:195], v3 offset:0
	ds_read_b128 v[196:199], v3 offset:1024
	ds_read_b128 v[200:203], v3 offset:2048
	ds_read_b128 v[204:207], v3 offset:3072
	s_waitcnt lgkmcnt(3)
	v_pk_mul_f32 v[160:161], v[128:129], v[192:193]
	v_pk_mul_f32 v[176:177], v[144:145], v[192:193]
	v_pk_fma_f32 v[160:161], v[130:131], v[194:195], v[160:161]
	v_pk_fma_f32 v[176:177], v[146:147], v[194:195], v[176:177]
	ds_read_b128 v[192:195], v3 offset:4096
	s_waitcnt lgkmcnt(3)
	v_pk_fma_f32 v[160:161], v[132:133], v[196:197], v[160:161]
	v_pk_fma_f32 v[176:177], v[148:149], v[196:197], v[176:177]
	v_pk_fma_f32 v[160:161], v[134:135], v[198:199], v[160:161]
	v_pk_fma_f32 v[176:177], v[150:151], v[198:199], v[176:177]
	ds_read_b128 v[196:199], v3 offset:5120
	s_waitcnt lgkmcnt(3)
	v_pk_fma_f32 v[160:161], v[136:137], v[200:201], v[160:161]
	v_pk_fma_f32 v[176:177], v[152:153], v[200:201], v[176:177]
	v_pk_fma_f32 v[160:161], v[138:139], v[202:203], v[160:161]
	v_pk_fma_f32 v[176:177], v[154:155], v[202:203], v[176:177]
	ds_read_b128 v[200:203], v3 offset:6144
	s_waitcnt lgkmcnt(3)
	v_pk_fma_f32 v[160:161], v[140:141], v[204:205], v[160:161]
	v_pk_fma_f32 v[176:177], v[156:157], v[204:205], v[176:177]
	v_pk_fma_f32 v[160:161], v[142:143], v[206:207], v[160:161]
	v_pk_fma_f32 v[176:177], v[158:159], v[206:207], v[176:177]
	ds_read_b128 v[204:207], v3 offset:7168
	s_waitcnt lgkmcnt(3)
	v_pk_mul_f32 v[162:163], v[128:129], v[192:193]
	v_pk_mul_f32 v[178:179], v[144:145], v[192:193]
	v_pk_fma_f32 v[162:163], v[130:131], v[194:195], v[162:163]
	v_pk_fma_f32 v[178:179], v[146:147], v[194:195], v[178:179]
	ds_read_b128 v[192:195], v3 offset:8192
	s_waitcnt lgkmcnt(3)
	v_pk_fma_f32 v[162:163], v[132:133], v[196:197], v[162:163]
	v_pk_fma_f32 v[178:179], v[148:149], v[196:197], v[178:179]
	v_pk_fma_f32 v[162:163], v[134:135], v[198:199], v[162:163]
	v_pk_fma_f32 v[178:179], v[150:151], v[198:199], v[178:179]
	ds_read_b128 v[196:199], v3 offset:9216
	s_waitcnt lgkmcnt(3)
	v_pk_fma_f32 v[162:163], v[136:137], v[200:201], v[162:163]
	v_pk_fma_f32 v[178:179], v[152:153], v[200:201], v[178:179]
	v_pk_fma_f32 v[162:163], v[138:139], v[202:203], v[162:163]
	v_pk_fma_f32 v[178:179], v[154:155], v[202:203], v[178:179]
	ds_read_b128 v[200:203], v3 offset:10240
	s_waitcnt lgkmcnt(3)
	v_pk_fma_f32 v[162:163], v[140:141], v[204:205], v[162:163]
	v_pk_fma_f32 v[178:179], v[156:157], v[204:205], v[178:179]
	v_pk_fma_f32 v[162:163], v[142:143], v[206:207], v[162:163]
	v_pk_fma_f32 v[178:179], v[158:159], v[206:207], v[178:179]
	ds_read_b128 v[204:207], v3 offset:11264
	s_waitcnt lgkmcnt(3)
	v_pk_mul_f32 v[164:165], v[128:129], v[192:193]
	v_pk_mul_f32 v[180:181], v[144:145], v[192:193]
	v_pk_fma_f32 v[164:165], v[130:131], v[194:195], v[164:165]
	v_pk_fma_f32 v[180:181], v[146:147], v[194:195], v[180:181]
	ds_read_b128 v[192:195], v3 offset:12288
	s_waitcnt lgkmcnt(3)
	v_pk_fma_f32 v[164:165], v[132:133], v[196:197], v[164:165]
	v_pk_fma_f32 v[180:181], v[148:149], v[196:197], v[180:181]
	v_pk_fma_f32 v[164:165], v[134:135], v[198:199], v[164:165]
	v_pk_fma_f32 v[180:181], v[150:151], v[198:199], v[180:181]
	ds_read_b128 v[196:199], v3 offset:13312
	s_waitcnt lgkmcnt(3)
; template <bool WITH_DT, bool OUT8> __device__ __forceinline__ void norm_mod_rows(const void* xp, bool pb16, const void* xs, bool sb16, const float* w, const float* MOD, int ish, int isc, bf16* H, ...
;     ...
;             for (int c = 0; c < 8; ++c) { float p = 0.f;
; #pragma unroll
;                 for (int j = 0; j < 4; ++j) { const f32x4 ww = wdt[WITH_DT ? c : 0][j]; p += (v[j][0] * ww[0] + v[j][1] * ww[1]) + (v[j][2] * ww[2] + v[j][3] * ww[3]); }
;                 d[c] = p; }
	v_pk_fma_f32 v[164:165], v[136:137], v[200:201], v[164:165]
	v_pk_fma_f32 v[180:181], v[152:153], v[200:201], v[180:181]
	v_pk_fma_f32 v[164:165], v[138:139], v[202:203], v[164:165]
	v_pk_fma_f32 v[180:181], v[154:155], v[202:203], v[180:181]
	ds_read_b128 v[200:203], v3 offset:14336
	s_waitcnt lgkmcnt(3)
	v_pk_fma_f32 v[164:165], v[140:141], v[204:205], v[164:165]
	v_pk_fma_f32 v[180:181], v[156:157], v[204:205], v[180:181]
	v_pk_fma_f32 v[164:165], v[142:143], v[206:207], v[164:165]
	v_pk_fma_f32 v[180:181], v[158:159], v[206:207], v[180:181]
	ds_read_b128 v[204:207], v3 offset:15360
	s_waitcnt lgkmcnt(3)
	v_pk_mul_f32 v[166:167], v[128:129], v[192:193]
	v_pk_mul_f32 v[182:183], v[144:145], v[192:193]
	v_pk_fma_f32 v[166:167], v[130:131], v[194:195], v[166:167]
	v_pk_fma_f32 v[182:183], v[146:147], v[194:195], v[182:183]
	ds_read_b128 v[192:195], v3 offset:16384
	s_waitcnt lgkmcnt(3)
	v_pk_fma_f32 v[166:167], v[132:133], v[196:197], v[166:167]
	v_pk_fma_f32 v[182:183], v[148:149], v[196:197], v[182:183]
	v_pk_fma_f32 v[166:167], v[134:135], v[198:199], v[166:167]
	v_pk_fma_f32 v[182:183], v[150:151], v[198:199], v[182:183]
	ds_read_b128 v[196:199], v3 offset:17408
	s_waitcnt lgkmcnt(3)
	v_pk_fma_f32 v[166:167], v[136:137], v[200:201], v[166:167]
	v_pk_fma_f32 v[182:183], v[152:153], v[200:201], v[182:183]
	v_pk_fma_f32 v[166:167], v[138:139], v[202:203], v[166:167]
	v_pk_fma_f32 v[182:183], v[154:155], v[202:203], v[182:183]
	ds_read_b128 v[200:203], v3 offset:18432
	s_waitcnt lgkmcnt(3)
	v_pk_fma_f32 v[166:167], v[140:141], v[204:205], v[166:167]
	v_pk_fma_f32 v[182:183], v[156:157], v[204:205], v[182:183]
	v_pk_fma_f32 v[166:167], v[142:143], v[206:207], v[166:167]
	v_pk_fma_f32 v[182:183], v[158:159], v[206:207], v[182:183]
	ds_read_b128 v[204:207], v3 offset:19456
	s_waitcnt lgkmcnt(3)
	v_pk_mul_f32 v[168:169], v[128:129], v[192:193]
	v_pk_mul_f32 v[184:185], v[144:145], v[192:193]
	v_pk_fma_f32 v[168:169], v[130:131], v[194:195], v[168:169]
	v_pk_fma_f32 v[184:185], v[146:147], v[194:195], v[184:185]
	ds_read_b128 v[192:195], v3 offset:20480
	s_waitcnt lgkmcnt(3)
	v_pk_fma_f32 v[168:169], v[132:133], v[196:197], v[168:169]
	v_pk_fma_f32 v[184:185], v[148:149], v[196:197], v[184:185]
	v_pk_fma_f32 v[168:169], v[134:135], v[198:199], v[168:169]
	v_pk_fma_f32 v[184:185], v[150:151], v[198:199], v[184:185]
	ds_read_b128 v[196:199], v3 offset:21504
	s_waitcnt lgkmcnt(3)
	v_pk_fma_f32 v[168:169], v[136:137], v[200:201], v[168:169]
	v_pk_fma_f32 v[184:185], v[152:153], v[200:201], v[184:185]
	v_pk_fma_f32 v[168:169], v[138:139], v[202:203], v[168:169]
	v_pk_fma_f32 v[184:185], v[154:155], v[202:203], v[184:185]
	ds_read_b128 v[200:203], v3 offset:22528
	s_waitcnt lgkmcnt(3)
	v_pk_fma_f32 v[168:169], v[140:141], v[204:205], v[168:169]
	v_pk_fma_f32 v[184:185], v[156:157], v[204:205], v[184:185]
	v_pk_fma_f32 v[168:169], v[142:143], v[206:207], v[168:169]
	v_pk_fma_f32 v[184:185], v[158:159], v[206:207], v[184:185]
	ds_read_b128 v[204:207], v3 offset:23552
	s_waitcnt lgkmcnt(3)
	v_pk_mul_f32 v[170:171], v[128:129], v[192:193]
	v_pk_mul_f32 v[186:187], v[144:145], v[192:193]
	v_pk_fma_f32 v[170:171], v[130:131], v[194:195], v[170:171]
	v_pk_fma_f32 v[186:187], v[146:147], v[194:195], v[186:187]
	ds_read_b128 v[192:195], v3 offset:24576
	s_waitcnt lgkmcnt(3)
	v_pk_fma_f32 v[170:171], v[132:133], v[196:197], v[170:171]
	v_pk_fma_f32 v[186:187], v[148:149], v[196:197], v[186:187]
	v_pk_fma_f32 v[170:171], v[134:135], v[198:199], v[170:171]
	v_pk_fma_f32 v[186:187], v[150:151], v[198:199], v[186:187]
	ds_read_b128 v[196:199], v3 offset:25600
	s_waitcnt lgkmcnt(3)
	v_pk_fma_f32 v[170:171], v[136:137], v[200:201], v[170:171]
	v_pk_fma_f32 v[186:187], v[152:153], v[200:201], v[186:187]
	v_pk_fma_f32 v[170:171], v[138:139], v[202:203], v[170:171]
	v_pk_fma_f32 v[186:187], v[154:155], v[202:203], v[186:187]
	ds_read_b128 v[200:203], v3 offset:26624
	s_waitcnt lgkmcnt(3)
	v_pk_fma_f32 v[170:171], v[140:141], v[204:205], v[170:171]
	v_pk_fma_f32 v[186:187], v[156:157], v[204:205], v[186:187]
	v_pk_fma_f32 v[170:171], v[142:143], v[206:207], v[170:171]
	v_pk_fma_f32 v[186:187], v[158:159], v[206:207], v[186:187]
	ds_read_b128 v[204:207], v3 offset:27648
	s_waitcnt lgkmcnt(3)
	v_pk_mul_f32 v[172:173], v[128:129], v[192:193]
	v_pk_mul_f32 v[188:189], v[144:145], v[192:193]
	v_pk_fma_f32 v[172:173], v[130:131], v[194:195], v[172:173]
	v_pk_fma_f32 v[188:189], v[146:147], v[194:195], v[188:189]
	ds_read_b128 v[192:195], v3 offset:28672
	s_waitcnt lgkmcnt(3)
	v_pk_fma_f32 v[172:173], v[132:133], v[196:197], v[172:173]
	v_pk_fma_f32 v[188:189], v[148:149], v[196:197], v[188:189]
	v_pk_fma_f32 v[172:173], v[134:135], v[198:199], v[172:173]
	v_pk_fma_f32 v[188:189], v[150:151], v[198:199], v[188:189]
	ds_read_b128 v[196:199], v3 offset:29696
	s_waitcnt lgkmcnt(3)
	v_pk_fma_f32 v[172:173], v[136:137], v[200:201], v[172:173]
	v_pk_fma_f32 v[188:189], v[152:153], v[200:201], v[188:189]
	v_pk_fma_f32 v[172:173], v[138:139], v[202:203], v[172:173]
	v_pk_fma_f32 v[188:189], v[154:155], v[202:203], v[188:189]
	ds_read_b128 v[200:203], v3 offset:30720
	s_waitcnt lgkmcnt(3)
	v_pk_fma_f32 v[172:173], v[140:141], v[204:205], v[172:173]
	v_pk_fma_f32 v[188:189], v[156:157], v[204:205], v[188:189]
	v_pk_fma_f32 v[172:173], v[142:143], v[206:207], v[172:173]
	v_pk_fma_f32 v[188:189], v[158:159], v[206:207], v[188:189]
	ds_read_b128 v[204:207], v3 offset:31744
	s_waitcnt lgkmcnt(3)
	v_pk_mul_f32 v[174:175], v[128:129], v[192:193]
	v_pk_mul_f32 v[190:191], v[144:145], v[192:193]
	v_pk_fma_f32 v[174:175], v[130:131], v[194:195], v[174:175]
	v_pk_fma_f32 v[190:191], v[146:147], v[194:195], v[190:191]
	s_waitcnt lgkmcnt(2)
; template <bool WITH_DT, bool OUT8> __device__ __forceinline__ void norm_mod_rows(const void* xp, bool pb16, const void* xs, bool sb16, const float* w, const float* MOD, int ish, int isc, bf16* H, ...
;     ...
;             float e4[4], e2[2], e1;
;             { const bool up = (lane & 32) != 0;
; #pragma unroll
;               for (int c = 0; c < 4; ++c) { const float keep = up ? d[4 + c] : d[c], give = up ? d[c] : d[4 + c]; e4[c] = keep + __shfl_xor(give, 32); } }
;             { const bool up = (lane & 16) != 0;
; #pragma unroll
;               for (int c = 0; c < 2; ++c) { const float keep = up ? e4[2 + c] : e4[c], give = up ? e4[c] : e4[2 + c]; e2[c] = keep + __shfl_xor(give, 16); } }
;             { const bool up = (lane & 8) != 0; const float keep = up ? e2[1] : e2[0], give = up ? e2[0] : e2[1]; e1 = keep + __shfl_xor(give, 8); }
;             e1 += __shfl_xor(e1, 4); e1 += __shfl_xor(e1, 2); e1 += __shfl_xor(e1, 1);
;             const int col = ((lane >> 5) & 1) * 4 + ((lane >> 4) & 1) * 2 + ((lane >> 3) & 1);
;             if ((lane & 7) == 0) { const float p = e1 + dt_bias[col]; DT[(size_t)row * 8 + col] = fmaxf(p, 0.f) + log1pf(__expf(-fabsf(p))); }
	v_pk_fma_f32 v[174:175], v[132:133], v[196:197], v[174:175]
	v_pk_fma_f32 v[190:191], v[148:149], v[196:197], v[190:191]
	v_pk_fma_f32 v[174:175], v[134:135], v[198:199], v[174:175]
	v_pk_fma_f32 v[190:191], v[150:151], v[198:199], v[190:191]
	s_waitcnt lgkmcnt(1)
	v_pk_fma_f32 v[174:175], v[136:137], v[200:201], v[174:175]
	v_pk_fma_f32 v[190:191], v[152:153], v[200:201], v[190:191]
	v_pk_fma_f32 v[174:175], v[138:139], v[202:203], v[174:175]
	v_pk_fma_f32 v[190:191], v[154:155], v[202:203], v[190:191]
	s_waitcnt lgkmcnt(0)
	v_pk_fma_f32 v[174:175], v[140:141], v[204:205], v[174:175]
	v_pk_fma_f32 v[190:191], v[156:157], v[204:205], v[190:191]
	v_pk_fma_f32 v[174:175], v[142:143], v[206:207], v[174:175]
	v_pk_fma_f32 v[190:191], v[158:159], v[206:207], v[190:191]
	v_add_f32_e32 v160, v160, v161
	v_add_f32_e32 v176, v176, v177
	v_add_f32_e32 v162, v162, v163
	v_add_f32_e32 v178, v178, v179
	v_add_f32_e32 v164, v164, v165
	v_add_f32_e32 v180, v180, v181
	v_add_f32_e32 v166, v166, v167
	v_add_f32_e32 v182, v182, v183
	v_add_f32_e32 v168, v168, v169
	v_add_f32_e32 v184, v184, v185
	v_add_f32_e32 v170, v170, v171
	v_add_f32_e32 v186, v186, v187
	v_add_f32_e32 v172, v172, v173
	v_add_f32_e32 v188, v188, v189
	v_add_f32_e32 v174, v174, v175
	v_add_f32_e32 v190, v190, v191
	v_cndmask_b32_e64 v216, v160, v168, s[38:39]
	v_cndmask_b32_e64 v217, v168, v160, s[38:39]
	v_cndmask_b32_e64 v224, v176, v184, s[38:39]
	v_cndmask_b32_e64 v225, v184, v176, s[38:39]
	v_cndmask_b32_e64 v218, v162, v170, s[38:39]
	v_cndmask_b32_e64 v219, v170, v162, s[38:39]
	v_cndmask_b32_e64 v226, v178, v186, s[38:39]
	v_cndmask_b32_e64 v227, v186, v178, s[38:39]
	v_cndmask_b32_e64 v220, v164, v172, s[38:39]
	v_cndmask_b32_e64 v221, v172, v164, s[38:39]
	v_cndmask_b32_e64 v228, v180, v188, s[38:39]
	v_cndmask_b32_e64 v229, v188, v180, s[38:39]
	v_cndmask_b32_e64 v222, v166, v174, s[38:39]
	v_cndmask_b32_e64 v223, v174, v166, s[38:39]
	v_cndmask_b32_e64 v230, v182, v190, s[38:39]
	v_cndmask_b32_e64 v231, v190, v182, s[38:39]
	s_nop 0
	v_add_f32_dpp v160, v217, v216 quad_perm:[1,0,3,2] row_mask:0xf bank_mask:0xf
	v_add_f32_dpp v176, v225, v224 quad_perm:[1,0,3,2] row_mask:0xf bank_mask:0xf
	v_add_f32_dpp v162, v219, v218 quad_perm:[1,0,3,2] row_mask:0xf bank_mask:0xf
	v_add_f32_dpp v178, v227, v226 quad_perm:[1,0,3,2] row_mask:0xf bank_mask:0xf
	v_add_f32_dpp v164, v221, v220 quad_perm:[1,0,3,2] row_mask:0xf bank_mask:0xf
	v_add_f32_dpp v180, v229, v228 quad_perm:[1,0,3,2] row_mask:0xf bank_mask:0xf
	v_add_f32_dpp v166, v223, v222 quad_perm:[1,0,3,2] row_mask:0xf bank_mask:0xf
	v_add_f32_dpp v182, v231, v230 quad_perm:[1,0,3,2] row_mask:0xf bank_mask:0xf
	v_cndmask_b32_e64 v216, v160, v164, s[40:41]
	v_cndmask_b32_e64 v217, v164, v160, s[40:41]
	v_cndmask_b32_e64 v224, v176, v180, s[40:41]
	v_cndmask_b32_e64 v225, v180, v176, s[40:41]
	v_cndmask_b32_e64 v218, v162, v166, s[40:41]
	v_cndmask_b32_e64 v219, v166, v162, s[40:41]
	v_cndmask_b32_e64 v226, v178, v182, s[40:41]
	v_cndmask_b32_e64 v227, v182, v178, s[40:41]
	s_nop 0
	v_add_f32_dpp v160, v217, v216 quad_perm:[2,3,0,1] row_mask:0xf bank_mask:0xf
	v_add_f32_dpp v176, v225, v224 quad_perm:[2,3,0,1] row_mask:0xf bank_mask:0xf
	v_add_f32_dpp v162, v219, v218 quad_perm:[2,3,0,1] row_mask:0xf bank_mask:0xf
	v_add_f32_dpp v178, v227, v226 quad_perm:[2,3,0,1] row_mask:0xf bank_mask:0xf
	v_cndmask_b32_e64 v216, v160, v162, s[42:43]
	v_cndmask_b32_e64 v217, v162, v160, s[42:43]
	v_cndmask_b32_e64 v224, v176, v178, s[42:43]
	v_cndmask_b32_e64 v225, v178, v176, s[42:43]
	s_nop 0
	v_add_f32_dpp v160, v217, v216 row_shl:4 row_mask:0xf bank_mask:0x5
	v_add_f32_dpp v160, v217, v216 row_shr:4 row_mask:0xf bank_mask:0xa
	v_add_f32_dpp v176, v225, v224 row_shl:4 row_mask:0xf bank_mask:0x5
	v_add_f32_dpp v176, v225, v224 row_shr:4 row_mask:0xf bank_mask:0xa
	s_nop 1
	v_add_f32_dpp v160, v160, v160 row_ror:8 row_mask:0xf bank_mask:0xf
	v_add_f32_dpp v176, v176, v176 row_ror:8 row_mask:0xf bank_mask:0xf
	s_nop 0
	ds_bpermute_b32 v161, v5, v160
	ds_bpermute_b32 v177, v5, v176
	s_waitcnt lgkmcnt(0)
	v_add_f32_e32 v160, v160, v161
	v_add_f32_e32 v176, v176, v177
	v_mov_b32_e32 v161, v160
	v_mov_b32_e32 v177, v176
	s_nop 1
	v_permlane32_swap_b32_e32 v160, v161
	v_permlane32_swap_b32_e32 v176, v177
	v_add_f32_e32 v160, v160, v161
	v_add_f32_e32 v176, v176, v177
	v_add_f32_e32 v160, v160, v12
	v_add_f32_e32 v176, v176, v12
	v_and_b32_e32 v216, 0x7fffffff, v160
	v_and_b32_e32 v224, 0x7fffffff, v176
	v_mul_f32_e32 v216, 0xbfb8aa3b, v216
	v_mul_f32_e32 v224, 0xbfb8aa3b, v224
	v_exp_f32_e32 v216, v216
	v_exp_f32_e32 v224, v224
	s_nop 0
	v_add_f32_e32 v217, 1.0, v216
	v_add_f32_e32 v225, 1.0, v224
	v_log_f32_e32 v218, v217
	v_log_f32_e32 v226, v225
	v_add_f32_e32 v219, -1.0, v217
	v_add_f32_e32 v227, -1.0, v225
	v_rcp_f32_e32 v219, v219
	v_rcp_f32_e32 v227, v227
	v_mul_f32_e32 v218, 0x3f317218, v218
	v_mul_f32_e32 v226, 0x3f317218, v226
	v_mul_f32_e32 v219, v216, v219
	v_mul_f32_e32 v227, v224, v227
	v_mul_f32_e32 v218, v218, v219
	v_mul_f32_e32 v226, v226, v227
	v_cmp_eq_f32_e32 vcc, 1.0, v217
	s_nop 1
	v_cndmask_b32_e32 v218, v218, v216, vcc
	v_cmp_eq_f32_e32 vcc, 1.0, v225
	s_nop 1
	v_cndmask_b32_e32 v226, v226, v224, vcc
	v_max_f32_e32 v160, 0, v160
	v_max_f32_e32 v176, 0, v176
	v_add_f32_e32 v160, v160, v218
	v_add_f32_e32 v176, v176, v226
	v_cndmask_b32_e64 v160, v160, v176, s[44:45]
	s_mov_b64 exec, 0xffff
	global_store_dword v4, v160, s[28:29]
	s_mov_b64 exec, -1
	s_add_u32 s28, s28, 64
	s_addc_u32 s29, s29, 0
	v_mov_b32_e32 v144, v252
	s_add_i32 s5, s5, 0x8000
; #define LAS __attribute__((address_space(3)))
; template <bool WITH_DT, bool OUT8> __device__ __forceinline__ void norm_mod_rows(const void* xp, bool pb16, const void* xs, bool sb16, const float* w, const float* MOD, int ish, int isc, bf16* H, ...
;     ...
;     f32x4 wv[4];
; #pragma unroll
;     for (int j = 0; j < 4; ++j) wv[j] = ((const f32x4*)w)[lane + 64 * j];
;     f32x4 wdt[WITH_DT ? 8 : 1][4];
;     if (WITH_DT) {
; #pragma unroll
;         for (int c = 0; c < 8; ++c)
; #pragma unroll
;             for (int j = 0; j < 4; ++j) wdt[c][j] = *(const LAS f32x4*)(sW + c * 1024 + 4 * (lane + 64 * j)); }
;     f32x4 vn[4];
;     if (gw < MT) { if (gw < MP) load_row4(xp, pb16, (size_t)gw, lane, vn); else load_row4(xs, sb16, (size_t)(gw - MP), lane, vn); }
;     for (int row = gw; row < MT; row += NGW) {
;         const int mb = row < MP ? (row >> 12) : 8 + ((row - MP) >> 6);
;         f32x4 v[4]; float s = 0.f;
; #pragma unroll
;         for (int j = 0; j < 4; ++j) v[j] = vn[j];
;         { const int rn = row + NGW; if (rn < MT) { if (rn < MP) load_row4(xp, pb16, (size_t)rn, lane, vn); else load_row4(xs, sb16, (size_t)(rn - MP), lane, vn); } }
.Lp4_orig:
	s_add_i32 s24, s5, s4
	s_cmp_gt_i32 s24, 0x81ff
	s_cbranch_scc1 .LBB0_400
	v_and_b32_e32 v145, 63, v144
	v_mov_b32_e32 v181, 0
	v_lshlrev_b32_e32 v180, 4, v145
	v_lshl_add_u64 v[16:17], s[2:3], 0, v[180:181]
	flat_load_dwordx4 v[0:3], v[16:17]
	flat_load_dwordx4 v[4:7], v[16:17] offset:1024
	flat_load_dwordx4 v[8:11], v[16:17] offset:2048
	flat_load_dwordx4 v[12:15], v[16:17] offset:3072
	v_add_u32_e32 v140, 0, v180
	ds_read_b128 v[16:19], v140
	ds_read_b128 v[20:23], v140 offset:1024
	ds_read_b128 v[24:27], v140 offset:2048
	ds_read_b128 v[28:31], v140 offset:3072
	ds_read_b128 v[32:35], v140 offset:4096
	ds_read_b128 v[36:39], v140 offset:5120
	ds_read_b128 v[40:43], v140 offset:6144
	ds_read_b128 v[44:47], v140 offset:7168
	ds_read_b128 v[48:51], v140 offset:8192
	ds_read_b128 v[52:55], v140 offset:9216
	ds_read_b128 v[56:59], v140 offset:10240
	ds_read_b128 v[60:63], v140 offset:11264
	ds_read_b128 v[64:67], v140 offset:12288
	ds_read_b128 v[68:71], v140 offset:13312
	ds_read_b128 v[72:75], v140 offset:14336
	ds_read_b128 v[76:79], v140 offset:15360
	ds_read_b128 v[80:83], v140 offset:16384
	ds_read_b128 v[84:87], v140 offset:17408
	ds_read_b128 v[88:91], v140 offset:18432
	ds_read_b128 v[92:95], v140 offset:19456
	ds_read_b128 v[96:99], v140 offset:20480
	ds_read_b128 v[100:103], v140 offset:21504
	ds_read_b128 v[104:107], v140 offset:22528
	ds_read_b128 v[108:111], v140 offset:23552
	ds_read_b128 v[112:115], v140 offset:24576
	ds_read_b128 v[116:119], v140 offset:25600
	ds_read_b128 v[120:123], v140 offset:26624
	ds_read_b128 v[124:127], v140 offset:27648
	ds_read_b128 v[128:131], v140 offset:28672
	ds_read_b128 v[132:135], v140 offset:29696
	ds_read_b128 v[136:139], v140 offset:30720
	ds_read_b128 v[140:143], v140 offset:31744
	s_cmpk_gt_i32 s24, 0x7fff
	s_mov_b32 s3, 0
	s_cbranch_scc0 .LBB0_387
	s_add_i32 s2, s24, 0xffff8000
	s_lshl_b64 s[2:3], s[2:3], 12
	s_add_u32 s2, s0, s2
	s_addc_u32 s3, s1, s3
	v_lshl_add_u64 v[146:147], s[2:3], 0, v[180:181]
	flat_load_dwordx4 v[172:175], v[146:147]
	flat_load_dwordx4 v[168:171], v[146:147] offset:1024
	flat_load_dwordx4 v[164:167], v[146:147] offset:2048
	flat_load_dwordx4 v[160:163], v[146:147] offset:3072
	s_ashr_i32 s25, s24, 31
	s_lshl_b64 s[16:17], s[24:25], 11
	v_lshlrev_b32_e32 v182, 3, v145
	s_cbranch_execz .LBB0_388
	s_branch .LBB0_389
